# A/B: all per-phase s_setprio flips deleted from the nine GEMM K-loops (on top of v083)
# speedup vs baseline: 1.0067x; 1.0067x over previous
; #define PG8_STAGE(bufoff, gbase, voff) do { _Pragma("unroll") for (int _i = 0; _i < 2; ++_i) \
;         __builtin_amdgcn_global_load_lds((const unsigned*)((const char*)(gbase) + (voff)[_i]), (LAS unsigned*)(lds + (bufoff) + ldsw + _i * 8192), 16, 0, 0); } while (0)
; #define PG8_WAIT_V(n) asm volatile("s_waitcnt vmcnt(" #n ")" ::: "memory")
; #define PG8_WAIT_L(n) asm volatile("s_waitcnt lgkmcnt(" #n ")" ::: "memory")
; #define PG8_BAR __builtin_amdgcn_s_barrier()
; #define PG8_SCHED __builtin_amdgcn_sched_barrier(0)
; template <bool F8 = false, class Epi, class Sched>
; __device__ __forceinline__ void gemm_phase(LAS unsigned char* lds, const int lda, const int ldb, const int K, const Sched& S, const Epi& E) {
;     ...
;         for (int t = 0; t < nt; t += 2) {
;             const bool last = (t == nt - 2);
;             const char* a1 = cA + (size_t)(t + 1) * kstep;
;             const char* a2 = last ? nA : cA + (size_t)(t + 2) * kstep; const char* b2 = last ? nB : cB + (size_t)(t + 2) * kstep;
;             const char* a3 = a2 + kstep; const char* b3 = b2 + kstep;
;             PG8_LDB(B0, 0, 0); PG8_LDB(B1, 0, 1); PG8_SCHED; PG8_LDA(At, 0, 0); PG8_STAGE(PG8_SA(1, 1), a1 + hstepA, voffA);
;             PG8_WAIT_V(8); PG8_WAIT_L(0); PG8_BAR; PG8_MMA(0, 0, At, B0); PG8_MMA(0, 1, At, B1); PG8_BAR; PG8_SCHED;
;             PG8_LDA(At, 0, 1); PG8_STAGE(PG8_SB(0, 0), b2, voffB); PG8_STAGE(PG8_SB(0, 1), b2 + hstepB, voffB); PG8_STAGE(PG8_SA(0, 0), a2, voffA);
;             PG8_WAIT_V(8); PG8_WAIT_L(0); PG8_BAR; PG8_MMA(1, 0, At, B0); PG8_MMA(1, 1, At, B1); PG8_BAR; PG8_SCHED;
.LBB0_242:
	s_add_u32 s29, s72, 0xfff80080
	s_addc_u32 s30, s73, -1
	s_add_i32 s31, 0, 0x10000
	s_cmp_eq_u32 s28, 28
	s_cselect_b32 s75, s5, s30
	s_cselect_b32 s74, s13, s29
	s_cselect_b32 s53, s11, vcc_hi
	s_cselect_b32 s52, s15, vcc_lo
	s_add_i32 s29, 0, 0x14000
	v_add_u32_e32 v158, s31, v147
	v_add_u32_e32 v174, s29, v147
	ds_read_b128 v[142:145], v158
	ds_read_b128 v[150:153], v158 offset:1024
	ds_read_b128 v[154:157], v158 offset:2048
	ds_read_b128 v[158:161], v158 offset:3072
	ds_read_b128 v[162:165], v174
	ds_read_b128 v[166:169], v174 offset:1024
	ds_read_b128 v[170:173], v174 offset:2048
	ds_read_b128 v[174:177], v174 offset:3072
	v_lshl_add_u64 v[194:195], s[72:73], 0, v[136:137]
	s_add_i32 m0, s26, 0xc000
	ds_read_b128 v[178:181], v149
	ds_read_b128 v[182:185], v149 offset:1024
	ds_read_b128 v[186:189], v149 offset:2048
	ds_read_b128 v[190:193], v149 offset:3072
	ds_read_b128 v[202:205], v149 offset:4096
	ds_read_b128 v[206:209], v149 offset:5120
	ds_read_b128 v[210:213], v149 offset:6144
	ds_read_b128 v[214:217], v149 offset:7168
	global_load_lds_dwordx4 v[194:195], off
	v_lshl_add_u64 v[194:195], s[72:73], 0, v[138:139]
	s_add_i32 m0, s26, 0xe000
	s_nop 0
	global_load_lds_dwordx4 v[194:195], off
	s_waitcnt vmcnt(8)
	s_waitcnt lgkmcnt(0)
	s_barrier
	v_mfma_f32_16x16x32_bf16 v[126:129], v[142:145], v[178:181], v[126:129]
	v_mfma_f32_16x16x32_bf16 v[122:125], v[154:157], v[178:181], v[122:125]
	v_mfma_f32_16x16x32_bf16 v[114:117], v[142:145], v[186:189], v[114:117]
	v_mfma_f32_16x16x32_bf16 v[106:109], v[154:157], v[186:189], v[106:109]
	v_mfma_f32_16x16x32_bf16 v[98:101], v[142:145], v[202:205], v[98:101]
	v_mfma_f32_16x16x32_bf16 v[90:93], v[154:157], v[202:205], v[90:93]
	v_mfma_f32_16x16x32_bf16 v[82:85], v[142:145], v[210:213], v[82:85]
	v_mfma_f32_16x16x32_bf16 v[74:77], v[154:157], v[210:213], v[74:77]
	v_mfma_f32_16x16x32_bf16 v[126:129], v[150:153], v[182:185], v[126:129]
	v_mfma_f32_16x16x32_bf16 v[122:125], v[158:161], v[182:185], v[122:125]
	v_mfma_f32_16x16x32_bf16 v[114:117], v[150:153], v[190:193], v[114:117]
	v_mfma_f32_16x16x32_bf16 v[106:109], v[158:161], v[190:193], v[106:109]
	v_mfma_f32_16x16x32_bf16 v[98:101], v[150:153], v[206:209], v[98:101]
	v_mfma_f32_16x16x32_bf16 v[90:93], v[158:161], v[206:209], v[90:93]
	v_mfma_f32_16x16x32_bf16 v[82:85], v[150:153], v[214:217], v[82:85]
	v_mfma_f32_16x16x32_bf16 v[74:77], v[158:161], v[214:217], v[74:77]
	v_mfma_f32_16x16x32_bf16 v[118:121], v[162:165], v[178:181], v[118:121]
	v_mfma_f32_16x16x32_bf16 v[110:113], v[170:173], v[178:181], v[110:113]
	v_mfma_f32_16x16x32_bf16 v[102:105], v[162:165], v[186:189], v[102:105]
	v_mfma_f32_16x16x32_bf16 v[94:97], v[170:173], v[186:189], v[94:97]
	v_mfma_f32_16x16x32_bf16 v[86:89], v[162:165], v[202:205], v[86:89]
	v_mfma_f32_16x16x32_bf16 v[78:81], v[170:173], v[202:205], v[78:81]
	v_mfma_f32_16x16x32_bf16 v[70:73], v[162:165], v[210:213], v[70:73]
	v_mfma_f32_16x16x32_bf16 v[66:69], v[170:173], v[210:213], v[66:69]
	v_mfma_f32_16x16x32_bf16 v[118:121], v[166:169], v[182:185], v[118:121]
	v_mfma_f32_16x16x32_bf16 v[110:113], v[174:177], v[182:185], v[110:113]
	v_mfma_f32_16x16x32_bf16 v[102:105], v[166:169], v[190:193], v[102:105]
	v_mfma_f32_16x16x32_bf16 v[94:97], v[174:177], v[190:193], v[94:97]
	v_mfma_f32_16x16x32_bf16 v[86:89], v[166:169], v[206:209], v[86:89]
	v_mfma_f32_16x16x32_bf16 v[78:81], v[174:177], v[206:209], v[78:81]
	v_mfma_f32_16x16x32_bf16 v[70:73], v[166:169], v[214:217], v[70:73]
	v_mfma_f32_16x16x32_bf16 v[66:69], v[174:177], v[214:217], v[66:69]
	s_barrier
	s_add_i32 s30, s31, s25
	v_lshl_add_u64 v[194:195], s[52:53], 0, v[0:1]
	s_mov_b32 m0, s30
	ds_read_b128 v[178:181], v149 offset:16384
	ds_read_b128 v[182:185], v149 offset:17408
	ds_read_b128 v[186:189], v149 offset:18432
	ds_read_b128 v[190:193], v149 offset:19456
	ds_read_b128 v[202:205], v149 offset:20480
	ds_read_b128 v[206:209], v149 offset:21504
	ds_read_b128 v[210:213], v149 offset:22528
	ds_read_b128 v[214:217], v149 offset:23552
	global_load_lds_dwordx4 v[194:195], off
	s_add_i32 m0, s30, 0x2000
	s_add_u32 s30, s52, 0x80000
	v_lshl_add_u64 v[218:219], s[52:53], 0, v[134:135]
	s_addc_u32 s31, s53, 0
	s_add_i32 s29, s29, s25
	global_load_lds_dwordx4 v[218:219], off
	v_lshl_add_u64 v[220:221], s[30:31], 0, v[0:1]
	s_mov_b32 m0, s29
	v_lshl_add_u64 v[222:223], s[74:75], 0, v[132:133]
	global_load_lds_dwordx4 v[220:221], off
	v_lshl_add_u64 v[220:221], s[30:31], 0, v[134:135]
	s_add_i32 m0, s29, 0x2000
	s_nop 0
	global_load_lds_dwordx4 v[220:221], off
	v_lshl_add_u64 v[220:221], s[74:75], 0, v[130:131]
	s_mov_b32 m0, s26
	s_nop 0
	global_load_lds_dwordx4 v[220:221], off
	s_mov_b32 m0, s27
	s_nop 0
	global_load_lds_dwordx4 v[222:223], off
	s_waitcnt vmcnt(8)
	s_waitcnt lgkmcnt(0)
	s_barrier
; #define PG8_STAGE(bufoff, gbase, voff) do { _Pragma("unroll") for (int _i = 0; _i < 2; ++_i) \
;         __builtin_amdgcn_global_load_lds((const unsigned*)((const char*)(gbase) + (voff)[_i]), (LAS unsigned*)(lds + (bufoff) + ldsw + _i * 8192), 16, 0, 0); } while (0)
; #define PG8_WAIT_V(n) asm volatile("s_waitcnt vmcnt(" #n ")" ::: "memory")
; #define PG8_WAIT_L(n) asm volatile("s_waitcnt lgkmcnt(" #n ")" ::: "memory")
; #define PG8_BAR __builtin_amdgcn_s_barrier()
; #define PG8_SCHED __builtin_amdgcn_sched_barrier(0)
; template <bool F8 = false, class Epi, class Sched>
; __device__ __forceinline__ void gemm_phase(LAS unsigned char* lds, const int lda, const int ldb, const int K, const Sched& S, const Epi& E) {
;     ...
;             PG8_WAIT_V(8); PG8_WAIT_L(0); PG8_BAR; PG8_MMA(1, 0, At, B0); PG8_MMA(1, 1, At, B1); PG8_BAR; PG8_SCHED;
;             PG8_LDB(B0, 1, 0); PG8_LDB(B1, 1, 1); PG8_SCHED; PG8_LDA(At, 1, 0); PG8_STAGE(PG8_SA(0, 1), a2 + hstepA, voffA);
;             PG8_WAIT_V(8); PG8_WAIT_L(0); PG8_BAR; PG8_MMA(0, 0, At, B0); PG8_MMA(0, 1, At, B1); PG8_BAR; PG8_SCHED;
	v_mfma_f32_16x16x32_bf16 v[62:65], v[142:145], v[178:181], v[62:65]
	v_mfma_f32_16x16x32_bf16 v[58:61], v[154:157], v[178:181], v[58:61]
	v_mfma_f32_16x16x32_bf16 v[50:53], v[142:145], v[186:189], v[50:53]
	v_mfma_f32_16x16x32_bf16 v[42:45], v[154:157], v[186:189], v[42:45]
	v_mfma_f32_16x16x32_bf16 v[34:37], v[142:145], v[202:205], v[34:37]
	v_mfma_f32_16x16x32_bf16 v[26:29], v[154:157], v[202:205], v[26:29]
	v_mfma_f32_16x16x32_bf16 v[18:21], v[142:145], v[210:213], v[18:21]
	v_mfma_f32_16x16x32_bf16 v[10:13], v[154:157], v[210:213], v[10:13]
	v_mfma_f32_16x16x32_bf16 v[62:65], v[150:153], v[182:185], v[62:65]
	v_mfma_f32_16x16x32_bf16 v[58:61], v[158:161], v[182:185], v[58:61]
	v_mfma_f32_16x16x32_bf16 v[50:53], v[150:153], v[190:193], v[50:53]
	v_mfma_f32_16x16x32_bf16 v[42:45], v[158:161], v[190:193], v[42:45]
	v_mfma_f32_16x16x32_bf16 v[34:37], v[150:153], v[206:209], v[34:37]
	v_mfma_f32_16x16x32_bf16 v[26:29], v[158:161], v[206:209], v[26:29]
	v_mfma_f32_16x16x32_bf16 v[18:21], v[150:153], v[214:217], v[18:21]
	v_mfma_f32_16x16x32_bf16 v[10:13], v[158:161], v[214:217], v[10:13]
	v_mfma_f32_16x16x32_bf16 v[54:57], v[162:165], v[178:181], v[54:57]
	v_mfma_f32_16x16x32_bf16 v[46:49], v[170:173], v[178:181], v[46:49]
	v_mfma_f32_16x16x32_bf16 v[38:41], v[162:165], v[186:189], v[38:41]
	v_mfma_f32_16x16x32_bf16 v[30:33], v[170:173], v[186:189], v[30:33]
	v_mfma_f32_16x16x32_bf16 v[22:25], v[162:165], v[202:205], v[22:25]
	v_mfma_f32_16x16x32_bf16 v[14:17], v[170:173], v[202:205], v[14:17]
	v_mfma_f32_16x16x32_bf16 v[6:9], v[162:165], v[210:213], v[6:9]
	v_mfma_f32_16x16x32_bf16 v[2:5], v[170:173], v[210:213], v[2:5]
	v_mfma_f32_16x16x32_bf16 v[54:57], v[166:169], v[182:185], v[54:57]
	v_mfma_f32_16x16x32_bf16 v[46:49], v[174:177], v[182:185], v[46:49]
	v_mfma_f32_16x16x32_bf16 v[38:41], v[166:169], v[190:193], v[38:41]
	v_mfma_f32_16x16x32_bf16 v[30:33], v[174:177], v[190:193], v[30:33]
	v_mfma_f32_16x16x32_bf16 v[22:25], v[166:169], v[206:209], v[22:25]
	v_mfma_f32_16x16x32_bf16 v[14:17], v[174:177], v[206:209], v[14:17]
	v_mfma_f32_16x16x32_bf16 v[6:9], v[166:169], v[214:217], v[6:9]
	v_mfma_f32_16x16x32_bf16 v[2:5], v[174:177], v[214:217], v[2:5]
	s_barrier
	s_add_i32 s29, 0, 0x18000
	s_add_i32 s33, 0, 0x1c000
	v_add_u32_e32 v158, s29, v147
	v_add_u32_e32 v174, s33, v147
	ds_read_b128 v[142:145], v158
	ds_read_b128 v[150:153], v158 offset:1024
	ds_read_b128 v[154:157], v158 offset:2048
	ds_read_b128 v[158:161], v158 offset:3072
	ds_read_b128 v[162:165], v174
	ds_read_b128 v[166:169], v174 offset:1024
	ds_read_b128 v[170:173], v174 offset:2048
	ds_read_b128 v[174:177], v174 offset:3072
	s_add_u32 s30, s74, 0x80000
	s_addc_u32 s31, s75, 0
	s_mov_b32 m0, s56
	v_lshl_add_u64 v[224:225], s[30:31], 0, v[130:131]
	ds_read_b128 v[178:181], v149 offset:32768
	ds_read_b128 v[182:185], v149 offset:33792
	ds_read_b128 v[186:189], v149 offset:34816
	ds_read_b128 v[190:193], v149 offset:35840
	ds_read_b128 v[202:205], v149 offset:36864
	ds_read_b128 v[206:209], v149 offset:37888
	ds_read_b128 v[210:213], v149 offset:38912
	ds_read_b128 v[214:217], v149 offset:39936
	global_load_lds_dwordx4 v[224:225], off
	v_lshl_add_u64 v[224:225], s[30:31], 0, v[132:133]
	s_mov_b32 m0, s57
	s_nop 0
	global_load_lds_dwordx4 v[224:225], off
	s_waitcnt vmcnt(8)
	s_waitcnt lgkmcnt(0)
	s_barrier
	v_mfma_f32_16x16x32_bf16 v[126:129], v[142:145], v[178:181], v[126:129]
	v_mfma_f32_16x16x32_bf16 v[122:125], v[154:157], v[178:181], v[122:125]
	v_mfma_f32_16x16x32_bf16 v[114:117], v[142:145], v[186:189], v[114:117]
	v_mfma_f32_16x16x32_bf16 v[106:109], v[154:157], v[186:189], v[106:109]
	v_mfma_f32_16x16x32_bf16 v[98:101], v[142:145], v[202:205], v[98:101]
	v_mfma_f32_16x16x32_bf16 v[90:93], v[154:157], v[202:205], v[90:93]
	v_mfma_f32_16x16x32_bf16 v[82:85], v[142:145], v[210:213], v[82:85]
	v_mfma_f32_16x16x32_bf16 v[74:77], v[154:157], v[210:213], v[74:77]
	v_mfma_f32_16x16x32_bf16 v[126:129], v[150:153], v[182:185], v[126:129]
	v_mfma_f32_16x16x32_bf16 v[122:125], v[158:161], v[182:185], v[122:125]
	v_mfma_f32_16x16x32_bf16 v[114:117], v[150:153], v[190:193], v[114:117]
	v_mfma_f32_16x16x32_bf16 v[106:109], v[158:161], v[190:193], v[106:109]
	v_mfma_f32_16x16x32_bf16 v[98:101], v[150:153], v[206:209], v[98:101]
	v_mfma_f32_16x16x32_bf16 v[90:93], v[158:161], v[206:209], v[90:93]
	v_mfma_f32_16x16x32_bf16 v[82:85], v[150:153], v[214:217], v[82:85]
	v_mfma_f32_16x16x32_bf16 v[74:77], v[158:161], v[214:217], v[74:77]
	v_mfma_f32_16x16x32_bf16 v[118:121], v[162:165], v[178:181], v[118:121]
	v_mfma_f32_16x16x32_bf16 v[110:113], v[170:173], v[178:181], v[110:113]
	v_mfma_f32_16x16x32_bf16 v[102:105], v[162:165], v[186:189], v[102:105]
	v_mfma_f32_16x16x32_bf16 v[94:97], v[170:173], v[186:189], v[94:97]
	v_mfma_f32_16x16x32_bf16 v[86:89], v[162:165], v[202:205], v[86:89]
	v_mfma_f32_16x16x32_bf16 v[78:81], v[170:173], v[202:205], v[78:81]
	v_mfma_f32_16x16x32_bf16 v[70:73], v[162:165], v[210:213], v[70:73]
	v_mfma_f32_16x16x32_bf16 v[66:69], v[170:173], v[210:213], v[66:69]
	v_mfma_f32_16x16x32_bf16 v[118:121], v[166:169], v[182:185], v[118:121]
	v_mfma_f32_16x16x32_bf16 v[110:113], v[174:177], v[182:185], v[110:113]
	v_mfma_f32_16x16x32_bf16 v[102:105], v[166:169], v[190:193], v[102:105]
	v_mfma_f32_16x16x32_bf16 v[94:97], v[174:177], v[190:193], v[94:97]
	v_mfma_f32_16x16x32_bf16 v[86:89], v[166:169], v[206:209], v[86:89]
	v_mfma_f32_16x16x32_bf16 v[78:81], v[174:177], v[206:209], v[78:81]
	v_mfma_f32_16x16x32_bf16 v[70:73], v[166:169], v[214:217], v[70:73]
	v_mfma_f32_16x16x32_bf16 v[66:69], v[174:177], v[214:217], v[66:69]
	s_barrier
; #define PG8_STAGE(bufoff, gbase, voff) do { _Pragma("unroll") for (int _i = 0; _i < 2; ++_i) \
;         __builtin_amdgcn_global_load_lds((const unsigned*)((const char*)(gbase) + (voff)[_i]), (LAS unsigned*)(lds + (bufoff) + ldsw + _i * 8192), 16, 0, 0); } while (0)
; #define PG8_WAIT_V(n) asm volatile("s_waitcnt vmcnt(" #n ")" ::: "memory")
; #define PG8_WAIT_L(n) asm volatile("s_waitcnt lgkmcnt(" #n ")" ::: "memory")
; #define PG8_BAR __builtin_amdgcn_s_barrier()
; #define PG8_SCHED __builtin_amdgcn_sched_barrier(0)
; template <bool F8 = false, class Epi, class Sched>
; __device__ __forceinline__ void gemm_phase(LAS unsigned char* lds, const int lda, const int ldb, const int K, const Sched& S, const Epi& E) {
;     ...
;             PG8_LDA(At, 1, 1); PG8_STAGE(PG8_SB(1, 0), b3, voffB); PG8_STAGE(PG8_SB(1, 1), b3 + hstepB, voffB); PG8_STAGE(PG8_SA(1, 0), a3, voffA);
;             PG8_WAIT_V(8); PG8_WAIT_L(0); PG8_BAR; PG8_MMA(1, 0, At, B0); PG8_MMA(1, 1, At, B1); PG8_BAR; PG8_SCHED;
;         }
	s_add_i32 s29, s29, s25
	v_lshl_add_u64 v[194:195], v[194:195], 0, s[40:41]
	s_mov_b32 m0, s29
	ds_read_b128 v[178:181], v149 offset:49152
	ds_read_b128 v[182:185], v149 offset:50176
	ds_read_b128 v[186:189], v149 offset:51200
	ds_read_b128 v[190:193], v149 offset:52224
	ds_read_b128 v[202:205], v149 offset:53248
	ds_read_b128 v[206:209], v149 offset:54272
	ds_read_b128 v[210:213], v149 offset:55296
	ds_read_b128 v[214:217], v149 offset:56320
	global_load_lds_dwordx4 v[194:195], off
	s_add_i32 m0, s29, 0x2000
	s_add_u32 s30, s52, 0x80080
	v_lshl_add_u64 v[194:195], v[218:219], 0, s[40:41]
	s_addc_u32 s31, s53, 0
	s_add_i32 s29, s33, s25
	global_load_lds_dwordx4 v[194:195], off
	v_lshl_add_u64 v[194:195], s[30:31], 0, v[0:1]
	s_mov_b32 m0, s29
	s_nop 0
	global_load_lds_dwordx4 v[194:195], off
	v_lshl_add_u64 v[194:195], s[30:31], 0, v[134:135]
	s_add_i32 m0, s29, 0x2000
	s_nop 0
	global_load_lds_dwordx4 v[194:195], off
	v_lshl_add_u64 v[194:195], v[220:221], 0, s[40:41]
	s_mov_b32 m0, s94
	s_nop 0
	global_load_lds_dwordx4 v[194:195], off
	v_lshl_add_u64 v[194:195], v[222:223], 0, s[40:41]
	s_mov_b32 m0, s95
	s_nop 0
	global_load_lds_dwordx4 v[194:195], off
	s_waitcnt vmcnt(8)
	s_waitcnt lgkmcnt(0)
	s_barrier
	v_mfma_f32_16x16x32_bf16 v[62:65], v[142:145], v[178:181], v[62:65]
	v_mfma_f32_16x16x32_bf16 v[58:61], v[154:157], v[178:181], v[58:61]
	v_mfma_f32_16x16x32_bf16 v[50:53], v[142:145], v[186:189], v[50:53]
	v_mfma_f32_16x16x32_bf16 v[42:45], v[154:157], v[186:189], v[42:45]
	v_mfma_f32_16x16x32_bf16 v[34:37], v[142:145], v[202:205], v[34:37]
	v_mfma_f32_16x16x32_bf16 v[26:29], v[154:157], v[202:205], v[26:29]
	v_mfma_f32_16x16x32_bf16 v[18:21], v[142:145], v[210:213], v[18:21]
	v_mfma_f32_16x16x32_bf16 v[10:13], v[154:157], v[210:213], v[10:13]
	v_mfma_f32_16x16x32_bf16 v[62:65], v[150:153], v[182:185], v[62:65]
	v_mfma_f32_16x16x32_bf16 v[58:61], v[158:161], v[182:185], v[58:61]
	v_mfma_f32_16x16x32_bf16 v[50:53], v[150:153], v[190:193], v[50:53]
	v_mfma_f32_16x16x32_bf16 v[42:45], v[158:161], v[190:193], v[42:45]
	v_mfma_f32_16x16x32_bf16 v[34:37], v[150:153], v[206:209], v[34:37]
	v_mfma_f32_16x16x32_bf16 v[26:29], v[158:161], v[206:209], v[26:29]
	v_mfma_f32_16x16x32_bf16 v[18:21], v[150:153], v[214:217], v[18:21]
	v_mfma_f32_16x16x32_bf16 v[10:13], v[158:161], v[214:217], v[10:13]
	v_mfma_f32_16x16x32_bf16 v[54:57], v[162:165], v[178:181], v[54:57]
	v_mfma_f32_16x16x32_bf16 v[46:49], v[170:173], v[178:181], v[46:49]
	v_mfma_f32_16x16x32_bf16 v[38:41], v[162:165], v[186:189], v[38:41]
	v_mfma_f32_16x16x32_bf16 v[30:33], v[170:173], v[186:189], v[30:33]
	v_mfma_f32_16x16x32_bf16 v[22:25], v[162:165], v[202:205], v[22:25]
	v_mfma_f32_16x16x32_bf16 v[14:17], v[170:173], v[202:205], v[14:17]
	v_mfma_f32_16x16x32_bf16 v[6:9], v[162:165], v[210:213], v[6:9]
	v_mfma_f32_16x16x32_bf16 v[2:5], v[170:173], v[210:213], v[2:5]
	v_mfma_f32_16x16x32_bf16 v[54:57], v[166:169], v[182:185], v[54:57]
	v_mfma_f32_16x16x32_bf16 v[46:49], v[174:177], v[182:185], v[46:49]
	v_mfma_f32_16x16x32_bf16 v[38:41], v[166:169], v[190:193], v[38:41]
	v_mfma_f32_16x16x32_bf16 v[30:33], v[174:177], v[190:193], v[30:33]
	v_mfma_f32_16x16x32_bf16 v[22:25], v[166:169], v[206:209], v[22:25]
	v_mfma_f32_16x16x32_bf16 v[14:17], v[174:177], v[206:209], v[14:17]
	v_mfma_f32_16x16x32_bf16 v[6:9], v[166:169], v[214:217], v[6:9]
	v_mfma_f32_16x16x32_bf16 v[2:5], v[174:177], v[214:217], v[2:5]
	s_barrier
	s_add_i32 s28, s28, 2
	s_add_u32 s72, s72, 0x100
	s_addc_u32 s73, s73, 0
	s_add_u32 vcc_lo, vcc_lo, 0x100
	s_addc_u32 vcc_hi, vcc_hi, 0
	s_cmp_gt_u32 s28, 29
	s_cbranch_scc0 .LBB0_242
	s_and_b64 vcc, exec, s[8:9]
	s_cbranch_vccz .LBB0_245
	s_barrier

; #define PG8_STAGE(bufoff, gbase, voff) do { _Pragma("unroll") for (int _i = 0; _i < 2; ++_i) \
;         __builtin_amdgcn_global_load_lds((const unsigned*)((const char*)(gbase) + (voff)[_i]), (LAS unsigned*)(lds + (bufoff) + ldsw + _i * 8192), 16, 0, 0); } while (0)
; #define PG8_WAIT_V(n) asm volatile("s_waitcnt vmcnt(" #n ")" ::: "memory")
; #define PG8_WAIT_L(n) asm volatile("s_waitcnt lgkmcnt(" #n ")" ::: "memory")
; #define PG8_BAR __builtin_amdgcn_s_barrier()
; #define PG8_SCHED __builtin_amdgcn_sched_barrier(0)
; template <bool F8 = false, class Epi, class Sched>
; __device__ __forceinline__ void gemm_phase(LAS unsigned char* lds, const int lda, const int ldb, const int K, const Sched& S, const Epi& E) {
;     ...
;         for (int t = 0; t < nt; t += 2) {
;             const bool last = (t == nt - 2);
;             const char* a1 = cA + (size_t)(t + 1) * kstep;
;             const char* a2 = last ? nA : cA + (size_t)(t + 2) * kstep; const char* b2 = last ? nB : cB + (size_t)(t + 2) * kstep;
;             const char* a3 = a2 + kstep; const char* b3 = b2 + kstep;
;             PG8_LDB(B0, 0, 0); PG8_LDB(B1, 0, 1); PG8_SCHED; PG8_LDA(At, 0, 0); PG8_STAGE(PG8_SA(1, 1), a1 + hstepA, voffA);
;             PG8_WAIT_V(8); PG8_WAIT_L(0); PG8_BAR; PG8_MMA(0, 0, At, B0); PG8_MMA(0, 1, At, B1); PG8_BAR; PG8_SCHED;
;             PG8_LDA(At, 0, 1); PG8_STAGE(PG8_SB(0, 0), b2, voffB); PG8_STAGE(PG8_SB(0, 1), b2 + hstepB, voffB); PG8_STAGE(PG8_SA(0, 0), a2, voffA);
;             PG8_WAIT_V(8); PG8_WAIT_L(0); PG8_BAR; PG8_MMA(1, 0, At, B0); PG8_MMA(1, 1, At, B1); PG8_BAR; PG8_SCHED;
.LBB0_292:
	s_add_u32 s29, s72, 0xfffc0080
	s_addc_u32 s30, s73, -1
	s_add_i32 s28, 0, 0x10000
	s_cmp_eq_u32 s97, 12
	s_cselect_b32 s53, s11, s30
	s_cselect_b32 s52, s13, s29
	s_cselect_b32 vcc_hi, s9, s19
	s_cselect_b32 vcc_lo, s96, s18
	s_add_i32 s29, 0, 0x14000
	v_add_u32_e32 v2, s28, v177
	v_add_u32_e32 v14, s29, v177
	ds_read_b128 v[18:21], v2
	ds_read_b128 v[22:25], v2 offset:1024
	ds_read_b128 v[26:29], v2 offset:2048
	ds_read_b128 v[30:33], v2 offset:3072
	ds_read_b128 v[2:5], v14
	ds_read_b128 v[6:9], v14 offset:1024
	ds_read_b128 v[10:13], v14 offset:2048
	ds_read_b128 v[14:17], v14 offset:3072
	v_lshl_add_u64 v[210:211], s[72:73], 0, v[164:165]
	s_add_i32 m0, s15, 0xc000
	ds_read_b128 v[168:171], v179
	ds_read_b128 v[172:175], v179 offset:1024
	ds_read_b128 v[180:183], v179 offset:2048
	ds_read_b128 v[184:187], v179 offset:3072
	ds_read_b128 v[188:191], v179 offset:4096
	ds_read_b128 v[192:195], v179 offset:5120
	ds_read_b128 v[202:205], v179 offset:6144
	ds_read_b128 v[206:209], v179 offset:7168
	global_load_lds_dwordx4 v[210:211], off
	v_lshl_add_u64 v[210:211], s[72:73], 0, v[166:167]
	s_add_i32 m0, s15, 0xe000
	s_nop 0
	global_load_lds_dwordx4 v[210:211], off
	s_waitcnt vmcnt(8)
	s_waitcnt lgkmcnt(0)
	s_barrier
	v_mfma_scale_f32_16x16x128_f8f6f4 v[158:161], v[18:25], v[168:175], v[158:161], v236, v236 op_sel_hi:[0,0,0]
	v_mfma_scale_f32_16x16x128_f8f6f4 v[154:157], v[26:33], v[168:175], v[154:157], v236, v236 op_sel_hi:[0,0,0]
	v_mfma_scale_f32_16x16x128_f8f6f4 v[150:153], v[18:25], v[180:187], v[150:153], v236, v236 op_sel_hi:[0,0,0]
	v_mfma_scale_f32_16x16x128_f8f6f4 v[142:145], v[26:33], v[180:187], v[142:145], v236, v236 op_sel_hi:[0,0,0]
	v_mfma_scale_f32_16x16x128_f8f6f4 v[134:137], v[18:25], v[188:195], v[134:137], v236, v236 op_sel_hi:[0,0,0]
	v_mfma_scale_f32_16x16x128_f8f6f4 v[126:129], v[26:33], v[188:195], v[126:129], v236, v236 op_sel_hi:[0,0,0]
	v_mfma_scale_f32_16x16x128_f8f6f4 v[118:121], v[18:25], v[202:209], v[118:121], v236, v236 op_sel_hi:[0,0,0]
	v_mfma_scale_f32_16x16x128_f8f6f4 v[110:113], v[26:33], v[202:209], v[110:113], v236, v236 op_sel_hi:[0,0,0]
	v_mfma_scale_f32_16x16x128_f8f6f4 v[146:149], v[2:9], v[168:175], v[146:149], v236, v236 op_sel_hi:[0,0,0]
	v_mfma_scale_f32_16x16x128_f8f6f4 v[138:141], v[10:17], v[168:175], v[138:141], v236, v236 op_sel_hi:[0,0,0]
	v_mfma_scale_f32_16x16x128_f8f6f4 v[130:133], v[2:9], v[180:187], v[130:133], v236, v236 op_sel_hi:[0,0,0]
	v_mfma_scale_f32_16x16x128_f8f6f4 v[122:125], v[10:17], v[180:187], v[122:125], v236, v236 op_sel_hi:[0,0,0]
	v_mfma_scale_f32_16x16x128_f8f6f4 v[114:117], v[2:9], v[188:195], v[114:117], v236, v236 op_sel_hi:[0,0,0]
	v_mfma_scale_f32_16x16x128_f8f6f4 v[106:109], v[10:17], v[188:195], v[106:109], v236, v236 op_sel_hi:[0,0,0]
	v_mfma_scale_f32_16x16x128_f8f6f4 v[102:105], v[2:9], v[202:209], v[102:105], v236, v236 op_sel_hi:[0,0,0]
	v_mfma_scale_f32_16x16x128_f8f6f4 v[98:101], v[10:17], v[202:209], v[98:101], v236, v236 op_sel_hi:[0,0,0]
	s_barrier
	s_add_i32 s28, s28, s24
	v_lshl_add_u64 v[168:169], vcc, 0, v[0:1]
	s_mov_b32 m0, s28
	ds_read_b128 v[180:183], v179 offset:16384
	ds_read_b128 v[184:187], v179 offset:17408
	ds_read_b128 v[188:191], v179 offset:18432
	ds_read_b128 v[192:195], v179 offset:19456
	ds_read_b128 v[202:205], v179 offset:20480
	ds_read_b128 v[206:209], v179 offset:21504
	ds_read_b128 v[210:213], v179 offset:22528
	ds_read_b128 v[214:217], v179 offset:23552
	global_load_lds_dwordx4 v[168:169], off
	s_add_i32 m0, s28, 0x2000
	s_add_u32 s30, vcc_lo, 0x40000
	v_lshl_add_u64 v[170:171], vcc, 0, v[162:163]
	s_addc_u32 s31, vcc_hi, 0
	s_add_i32 s28, s29, s24
	global_load_lds_dwordx4 v[170:171], off
	v_lshl_add_u64 v[172:173], s[30:31], 0, v[0:1]
	s_mov_b32 m0, s28
	v_lshl_add_u64 v[174:175], s[52:53], 0, v[162:163]
	global_load_lds_dwordx4 v[172:173], off
	v_lshl_add_u64 v[172:173], s[30:31], 0, v[162:163]
	s_add_i32 m0, s28, 0x2000
	s_nop 0
	global_load_lds_dwordx4 v[172:173], off
	v_lshl_add_u64 v[172:173], s[52:53], 0, v[0:1]
	s_mov_b32 m0, s15
	s_nop 0
	global_load_lds_dwordx4 v[172:173], off
	s_mov_b32 m0, s26
	s_nop 0
	global_load_lds_dwordx4 v[174:175], off
	s_waitcnt vmcnt(8)
	s_waitcnt lgkmcnt(0)
	s_barrier
	v_mfma_scale_f32_16x16x128_f8f6f4 v[94:97], v[18:25], v[180:187], v[94:97], v236, v236 op_sel_hi:[0,0,0]
	v_mfma_scale_f32_16x16x128_f8f6f4 v[90:93], v[26:33], v[180:187], v[90:93], v236, v236 op_sel_hi:[0,0,0]
	v_mfma_scale_f32_16x16x128_f8f6f4 v[86:89], v[18:25], v[188:195], v[86:89], v236, v236 op_sel_hi:[0,0,0]
	v_mfma_scale_f32_16x16x128_f8f6f4 v[78:81], v[26:33], v[188:195], v[78:81], v236, v236 op_sel_hi:[0,0,0]
	v_mfma_scale_f32_16x16x128_f8f6f4 v[70:73], v[18:25], v[202:209], v[70:73], v236, v236 op_sel_hi:[0,0,0]
	v_mfma_scale_f32_16x16x128_f8f6f4 v[62:65], v[26:33], v[202:209], v[62:65], v236, v236 op_sel_hi:[0,0,0]
	v_mfma_scale_f32_16x16x128_f8f6f4 v[54:57], v[18:25], v[210:217], v[54:57], v236, v236 op_sel_hi:[0,0,0]
	v_mfma_scale_f32_16x16x128_f8f6f4 v[46:49], v[26:33], v[210:217], v[46:49], v236, v236 op_sel_hi:[0,0,0]
	v_mfma_scale_f32_16x16x128_f8f6f4 v[82:85], v[2:9], v[180:187], v[82:85], v236, v236 op_sel_hi:[0,0,0]
	v_mfma_scale_f32_16x16x128_f8f6f4 v[74:77], v[10:17], v[180:187], v[74:77], v236, v236 op_sel_hi:[0,0,0]
	v_mfma_scale_f32_16x16x128_f8f6f4 v[66:69], v[2:9], v[188:195], v[66:69], v236, v236 op_sel_hi:[0,0,0]
	v_mfma_scale_f32_16x16x128_f8f6f4 v[58:61], v[10:17], v[188:195], v[58:61], v236, v236 op_sel_hi:[0,0,0]
	v_mfma_scale_f32_16x16x128_f8f6f4 v[50:53], v[2:9], v[202:209], v[50:53], v236, v236 op_sel_hi:[0,0,0]
	v_mfma_scale_f32_16x16x128_f8f6f4 v[42:45], v[10:17], v[202:209], v[42:45], v236, v236 op_sel_hi:[0,0,0]
	v_mfma_scale_f32_16x16x128_f8f6f4 v[38:41], v[2:9], v[210:217], v[38:41], v236, v236 op_sel_hi:[0,0,0]
	v_mfma_scale_f32_16x16x128_f8f6f4 v[34:37], v[10:17], v[210:217], v[34:37], v236, v236 op_sel_hi:[0,0,0]
	s_barrier
; #define PG8_STAGE(bufoff, gbase, voff) do { _Pragma("unroll") for (int _i = 0; _i < 2; ++_i) \
;         __builtin_amdgcn_global_load_lds((const unsigned*)((const char*)(gbase) + (voff)[_i]), (LAS unsigned*)(lds + (bufoff) + ldsw + _i * 8192), 16, 0, 0); } while (0)
; #define PG8_WAIT_V(n) asm volatile("s_waitcnt vmcnt(" #n ")" ::: "memory")
; #define PG8_WAIT_L(n) asm volatile("s_waitcnt lgkmcnt(" #n ")" ::: "memory")
; #define PG8_BAR __builtin_amdgcn_s_barrier()
; #define PG8_SCHED __builtin_amdgcn_sched_barrier(0)
; template <bool F8 = false, class Epi, class Sched>
; __device__ __forceinline__ void gemm_phase(LAS unsigned char* lds, const int lda, const int ldb, const int K, const Sched& S, const Epi& E) {
;     ...
;             PG8_LDB(B0, 1, 0); PG8_LDB(B1, 1, 1); PG8_SCHED; PG8_LDA(At, 1, 0); PG8_STAGE(PG8_SA(0, 1), a2 + hstepA, voffA);
;             PG8_WAIT_V(8); PG8_WAIT_L(0); PG8_BAR; PG8_MMA(0, 0, At, B0); PG8_MMA(0, 1, At, B1); PG8_BAR; PG8_SCHED;
;             PG8_LDA(At, 1, 1); PG8_STAGE(PG8_SB(1, 0), b3, voffB); PG8_STAGE(PG8_SB(1, 1), b3 + hstepB, voffB); PG8_STAGE(PG8_SA(1, 0), a3, voffA);
;             PG8_WAIT_V(8); PG8_WAIT_L(0); PG8_BAR; PG8_MMA(1, 0, At, B0); PG8_MMA(1, 1, At, B1); PG8_BAR; PG8_SCHED;
;         }
	s_add_i32 s30, 0, 0x18000
	s_add_i32 s31, 0, 0x1c000
	v_add_u32_e32 v14, s30, v177
	v_add_u32_e32 v30, s31, v177
	ds_read_b128 v[2:5], v14
	ds_read_b128 v[6:9], v14 offset:1024
	ds_read_b128 v[10:13], v14 offset:2048
	ds_read_b128 v[14:17], v14 offset:3072
	ds_read_b128 v[18:21], v30
	ds_read_b128 v[22:25], v30 offset:1024
	ds_read_b128 v[26:29], v30 offset:2048
	ds_read_b128 v[30:33], v30 offset:3072
	s_add_u32 s28, s52, 0x40000
	s_addc_u32 s29, s53, 0
	s_mov_b32 m0, s27
	v_lshl_add_u64 v[218:219], s[28:29], 0, v[0:1]
	ds_read_b128 v[180:183], v179 offset:32768
	ds_read_b128 v[184:187], v179 offset:33792
	ds_read_b128 v[188:191], v179 offset:34816
	ds_read_b128 v[192:195], v179 offset:35840
	ds_read_b128 v[202:205], v179 offset:36864
	ds_read_b128 v[206:209], v179 offset:37888
	ds_read_b128 v[210:213], v179 offset:38912
	ds_read_b128 v[214:217], v179 offset:39936
	global_load_lds_dwordx4 v[218:219], off
	v_lshl_add_u64 v[218:219], s[28:29], 0, v[162:163]
	s_mov_b32 m0, s56
	s_nop 0
	global_load_lds_dwordx4 v[218:219], off
	s_waitcnt vmcnt(8)
	s_waitcnt lgkmcnt(0)
	s_barrier
	v_mfma_scale_f32_16x16x128_f8f6f4 v[158:161], v[2:9], v[180:187], v[158:161], v236, v236 op_sel_hi:[0,0,0]
	v_mfma_scale_f32_16x16x128_f8f6f4 v[154:157], v[10:17], v[180:187], v[154:157], v236, v236 op_sel_hi:[0,0,0]
	v_mfma_scale_f32_16x16x128_f8f6f4 v[150:153], v[2:9], v[188:195], v[150:153], v236, v236 op_sel_hi:[0,0,0]
	v_mfma_scale_f32_16x16x128_f8f6f4 v[142:145], v[10:17], v[188:195], v[142:145], v236, v236 op_sel_hi:[0,0,0]
	v_mfma_scale_f32_16x16x128_f8f6f4 v[134:137], v[2:9], v[202:209], v[134:137], v236, v236 op_sel_hi:[0,0,0]
	v_mfma_scale_f32_16x16x128_f8f6f4 v[126:129], v[10:17], v[202:209], v[126:129], v236, v236 op_sel_hi:[0,0,0]
	v_mfma_scale_f32_16x16x128_f8f6f4 v[118:121], v[2:9], v[210:217], v[118:121], v236, v236 op_sel_hi:[0,0,0]
	v_mfma_scale_f32_16x16x128_f8f6f4 v[110:113], v[10:17], v[210:217], v[110:113], v236, v236 op_sel_hi:[0,0,0]
	v_mfma_scale_f32_16x16x128_f8f6f4 v[146:149], v[18:25], v[180:187], v[146:149], v236, v236 op_sel_hi:[0,0,0]
	v_mfma_scale_f32_16x16x128_f8f6f4 v[138:141], v[26:33], v[180:187], v[138:141], v236, v236 op_sel_hi:[0,0,0]
	v_mfma_scale_f32_16x16x128_f8f6f4 v[130:133], v[18:25], v[188:195], v[130:133], v236, v236 op_sel_hi:[0,0,0]
	v_mfma_scale_f32_16x16x128_f8f6f4 v[122:125], v[26:33], v[188:195], v[122:125], v236, v236 op_sel_hi:[0,0,0]
	v_mfma_scale_f32_16x16x128_f8f6f4 v[114:117], v[18:25], v[202:209], v[114:117], v236, v236 op_sel_hi:[0,0,0]
	v_mfma_scale_f32_16x16x128_f8f6f4 v[106:109], v[26:33], v[202:209], v[106:109], v236, v236 op_sel_hi:[0,0,0]
	v_mfma_scale_f32_16x16x128_f8f6f4 v[102:105], v[18:25], v[210:217], v[102:105], v236, v236 op_sel_hi:[0,0,0]
	v_mfma_scale_f32_16x16x128_f8f6f4 v[98:101], v[26:33], v[210:217], v[98:101], v236, v236 op_sel_hi:[0,0,0]
	s_barrier
	s_add_i32 s28, s30, s24
	v_lshl_add_u64 v[168:169], v[168:169], 0, s[40:41]
	s_mov_b32 m0, s28
	ds_read_b128 v[180:183], v179 offset:49152
	ds_read_b128 v[184:187], v179 offset:50176
	ds_read_b128 v[188:191], v179 offset:51200
	ds_read_b128 v[192:195], v179 offset:52224
	ds_read_b128 v[202:205], v179 offset:53248
	ds_read_b128 v[206:209], v179 offset:54272
	ds_read_b128 v[210:213], v179 offset:55296
	ds_read_b128 v[214:217], v179 offset:56320
	global_load_lds_dwordx4 v[168:169], off
	s_add_i32 m0, s28, 0x2000
	s_add_u32 s28, vcc_lo, 0x40080
	v_lshl_add_u64 v[168:169], v[170:171], 0, s[40:41]
	s_addc_u32 s29, vcc_hi, 0
	s_add_i32 s30, s31, s24
	global_load_lds_dwordx4 v[168:169], off
	v_lshl_add_u64 v[168:169], s[28:29], 0, v[0:1]
	s_mov_b32 m0, s30
	s_nop 0
	global_load_lds_dwordx4 v[168:169], off
	v_lshl_add_u64 v[168:169], s[28:29], 0, v[162:163]
	s_add_i32 m0, s30, 0x2000
	s_nop 0
	global_load_lds_dwordx4 v[168:169], off
	v_lshl_add_u64 v[168:169], v[172:173], 0, s[40:41]
	s_mov_b32 m0, s57
	s_nop 0
	global_load_lds_dwordx4 v[168:169], off
	v_lshl_add_u64 v[168:169], v[174:175], 0, s[40:41]
	s_mov_b32 m0, s94
	s_nop 0
	global_load_lds_dwordx4 v[168:169], off
	s_waitcnt vmcnt(8)
	s_waitcnt lgkmcnt(0)
	s_barrier
	v_mfma_scale_f32_16x16x128_f8f6f4 v[94:97], v[2:9], v[180:187], v[94:97], v236, v236 op_sel_hi:[0,0,0]
	v_mfma_scale_f32_16x16x128_f8f6f4 v[90:93], v[10:17], v[180:187], v[90:93], v236, v236 op_sel_hi:[0,0,0]
	v_mfma_scale_f32_16x16x128_f8f6f4 v[86:89], v[2:9], v[188:195], v[86:89], v236, v236 op_sel_hi:[0,0,0]
	v_mfma_scale_f32_16x16x128_f8f6f4 v[78:81], v[10:17], v[188:195], v[78:81], v236, v236 op_sel_hi:[0,0,0]
	v_mfma_scale_f32_16x16x128_f8f6f4 v[70:73], v[2:9], v[202:209], v[70:73], v236, v236 op_sel_hi:[0,0,0]
	v_mfma_scale_f32_16x16x128_f8f6f4 v[62:65], v[10:17], v[202:209], v[62:65], v236, v236 op_sel_hi:[0,0,0]
	v_mfma_scale_f32_16x16x128_f8f6f4 v[54:57], v[2:9], v[210:217], v[54:57], v236, v236 op_sel_hi:[0,0,0]
	v_mfma_scale_f32_16x16x128_f8f6f4 v[46:49], v[10:17], v[210:217], v[46:49], v236, v236 op_sel_hi:[0,0,0]
	v_mfma_scale_f32_16x16x128_f8f6f4 v[82:85], v[18:25], v[180:187], v[82:85], v236, v236 op_sel_hi:[0,0,0]
	v_mfma_scale_f32_16x16x128_f8f6f4 v[74:77], v[26:33], v[180:187], v[74:77], v236, v236 op_sel_hi:[0,0,0]
	v_mfma_scale_f32_16x16x128_f8f6f4 v[66:69], v[18:25], v[188:195], v[66:69], v236, v236 op_sel_hi:[0,0,0]
	v_mfma_scale_f32_16x16x128_f8f6f4 v[58:61], v[26:33], v[188:195], v[58:61], v236, v236 op_sel_hi:[0,0,0]
	v_mfma_scale_f32_16x16x128_f8f6f4 v[50:53], v[18:25], v[202:209], v[50:53], v236, v236 op_sel_hi:[0,0,0]
	v_mfma_scale_f32_16x16x128_f8f6f4 v[42:45], v[26:33], v[202:209], v[42:45], v236, v236 op_sel_hi:[0,0,0]
	v_mfma_scale_f32_16x16x128_f8f6f4 v[38:41], v[18:25], v[210:217], v[38:41], v236, v236 op_sel_hi:[0,0,0]
	v_mfma_scale_f32_16x16x128_f8f6f4 v[34:37], v[26:33], v[210:217], v[34:37], v236, v236 op_sel_hi:[0,0,0]
	s_barrier
	s_add_i32 s97, s97, 2
	s_add_u32 s72, s72, 0x100
	s_addc_u32 s73, s73, 0
	s_add_u32 s18, s18, 0x100
	s_addc_u32 s19, s19, 0
	s_cmp_gt_u32 s97, 13
	s_cbranch_scc0 .LBB0_292
	s_and_b64 vcc, exec, s[6:7]
	v_readlane_b32 s97, v249, 23
	s_cbranch_vccz .LBB0_295
	s_barrier

; #define PG8_STAGE(bufoff, gbase, voff) do { _Pragma("unroll") for (int _i = 0; _i < 2; ++_i) \
;         __builtin_amdgcn_global_load_lds((const unsigned*)((const char*)(gbase) + (voff)[_i]), (LAS unsigned*)(lds + (bufoff) + ldsw + _i * 8192), 16, 0, 0); } while (0)
; #define PG8_WAIT_V(n) asm volatile("s_waitcnt vmcnt(" #n ")" ::: "memory")
; #define PG8_WAIT_L(n) asm volatile("s_waitcnt lgkmcnt(" #n ")" ::: "memory")
; #define PG8_BAR __builtin_amdgcn_s_barrier()
; #define PG8_SCHED __builtin_amdgcn_sched_barrier(0)
; template <bool F8 = false, class Epi, class Sched>
; __device__ __forceinline__ void gemm_phase(LAS unsigned char* lds, const int lda, const int ldb, const int K, const Sched& S, const Epi& E) {
;     ...
;         for (int t = 0; t < nt; t += 2) {
;             const bool last = (t == nt - 2);
;             const char* a1 = cA + (size_t)(t + 1) * kstep;
;             const char* a2 = last ? nA : cA + (size_t)(t + 2) * kstep; const char* b2 = last ? nB : cB + (size_t)(t + 2) * kstep;
;             const char* a3 = a2 + kstep; const char* b3 = b2 + kstep;
;             PG8_LDB(B0, 0, 0); PG8_LDB(B1, 0, 1); PG8_SCHED; PG8_LDA(At, 0, 0); PG8_STAGE(PG8_SA(1, 1), a1 + hstepA, voffA);
;             PG8_WAIT_V(8); PG8_WAIT_L(0); PG8_BAR; PG8_MMA(0, 0, At, B0); PG8_MMA(0, 1, At, B1); PG8_BAR; PG8_SCHED;
;             PG8_LDA(At, 0, 1); PG8_STAGE(PG8_SB(0, 0), b2, voffB); PG8_STAGE(PG8_SB(0, 1), b2 + hstepB, voffB); PG8_STAGE(PG8_SA(0, 0), a2, voffA);
;             PG8_WAIT_V(8); PG8_WAIT_L(0); PG8_BAR; PG8_MMA(1, 0, At, B0); PG8_MMA(1, 1, At, B1); PG8_BAR; PG8_SCHED;
.LBB0_436:
	s_add_u32 s20, s18, 0x100
	s_addc_u32 s21, s19, 0
	s_add_i32 s30, 0, 0x10000
	s_cmp_eq_u32 s29, 4
	s_cselect_b32 s73, s15, s21
	s_cselect_b32 s72, s14, s20
	v_add_u32_e32 v140, s30, v143
	s_cselect_b32 s53, s17, s28
	s_cselect_b32 s52, s16, s11
	s_add_i32 s31, 0, 0x14000
	ds_read_b128 v[146:149], v140
	ds_read_b128 v[150:153], v140 offset:1024
	ds_read_b128 v[154:157], v140 offset:2048
	ds_read_b128 v[158:161], v140 offset:3072
	v_add_u32_e32 v140, s31, v143
	ds_read_b128 v[162:165], v140
	ds_read_b128 v[166:169], v140 offset:1024
	ds_read_b128 v[170:173], v140 offset:2048
	ds_read_b128 v[174:177], v140 offset:3072
	v_lshl_add_u64 v[140:141], s[18:19], 0, v[136:137]
	s_add_i32 m0, s13, 0xc000
	ds_read_b128 v[178:181], v145
	ds_read_b128 v[182:185], v145 offset:1024
	ds_read_b128 v[186:189], v145 offset:2048
	ds_read_b128 v[190:193], v145 offset:3072
	ds_read_b128 v[202:205], v145 offset:4096
	ds_read_b128 v[206:209], v145 offset:5120
	ds_read_b128 v[210:213], v145 offset:6144
	ds_read_b128 v[214:217], v145 offset:7168
	global_load_lds_dwordx4 v[140:141], off
	v_lshl_add_u64 v[140:141], s[18:19], 0, v[138:139]
	s_add_i32 m0, s13, 0xe000
	s_nop 0
	global_load_lds_dwordx4 v[140:141], off
	s_waitcnt vmcnt(8)
	s_waitcnt lgkmcnt(0)
	s_barrier
	v_mfma_f32_16x16x32_bf16 v[126:129], v[146:149], v[178:181], v[126:129]
	v_mfma_f32_16x16x32_bf16 v[122:125], v[154:157], v[178:181], v[122:125]
	v_mfma_f32_16x16x32_bf16 v[118:121], v[146:149], v[186:189], v[118:121]
	v_mfma_f32_16x16x32_bf16 v[110:113], v[154:157], v[186:189], v[110:113]
	v_mfma_f32_16x16x32_bf16 v[102:105], v[146:149], v[202:205], v[102:105]
	v_mfma_f32_16x16x32_bf16 v[94:97], v[154:157], v[202:205], v[94:97]
	v_mfma_f32_16x16x32_bf16 v[86:89], v[146:149], v[210:213], v[86:89]
	v_mfma_f32_16x16x32_bf16 v[78:81], v[154:157], v[210:213], v[78:81]
	v_mfma_f32_16x16x32_bf16 v[126:129], v[150:153], v[182:185], v[126:129]
	v_mfma_f32_16x16x32_bf16 v[122:125], v[158:161], v[182:185], v[122:125]
	v_mfma_f32_16x16x32_bf16 v[118:121], v[150:153], v[190:193], v[118:121]
	v_mfma_f32_16x16x32_bf16 v[110:113], v[158:161], v[190:193], v[110:113]
	v_mfma_f32_16x16x32_bf16 v[102:105], v[150:153], v[206:209], v[102:105]
	v_mfma_f32_16x16x32_bf16 v[94:97], v[158:161], v[206:209], v[94:97]
	v_mfma_f32_16x16x32_bf16 v[86:89], v[150:153], v[214:217], v[86:89]
	v_mfma_f32_16x16x32_bf16 v[78:81], v[158:161], v[214:217], v[78:81]
	v_mfma_f32_16x16x32_bf16 v[114:117], v[162:165], v[178:181], v[114:117]
	v_mfma_f32_16x16x32_bf16 v[106:109], v[170:173], v[178:181], v[106:109]
	v_mfma_f32_16x16x32_bf16 v[98:101], v[162:165], v[186:189], v[98:101]
	v_mfma_f32_16x16x32_bf16 v[90:93], v[170:173], v[186:189], v[90:93]
	v_mfma_f32_16x16x32_bf16 v[82:85], v[162:165], v[202:205], v[82:85]
	v_mfma_f32_16x16x32_bf16 v[74:77], v[170:173], v[202:205], v[74:77]
	v_mfma_f32_16x16x32_bf16 v[70:73], v[162:165], v[210:213], v[70:73]
	v_mfma_f32_16x16x32_bf16 v[66:69], v[170:173], v[210:213], v[66:69]
	v_mfma_f32_16x16x32_bf16 v[114:117], v[166:169], v[182:185], v[114:117]
	v_mfma_f32_16x16x32_bf16 v[106:109], v[174:177], v[182:185], v[106:109]
	v_mfma_f32_16x16x32_bf16 v[98:101], v[166:169], v[190:193], v[98:101]
	v_mfma_f32_16x16x32_bf16 v[90:93], v[174:177], v[190:193], v[90:93]
	v_mfma_f32_16x16x32_bf16 v[82:85], v[166:169], v[206:209], v[82:85]
	v_mfma_f32_16x16x32_bf16 v[74:77], v[174:177], v[206:209], v[74:77]
	v_mfma_f32_16x16x32_bf16 v[70:73], v[166:169], v[214:217], v[70:73]
	v_mfma_f32_16x16x32_bf16 v[66:69], v[174:177], v[214:217], v[66:69]
	s_barrier
	s_add_i32 s18, s30, s24
	v_lshl_add_u64 v[140:141], s[52:53], 0, v[0:1]
	s_mov_b32 m0, s18
	ds_read_b128 v[178:181], v145 offset:16384
	ds_read_b128 v[182:185], v145 offset:17408
	ds_read_b128 v[186:189], v145 offset:18432
	ds_read_b128 v[190:193], v145 offset:19456
	ds_read_b128 v[202:205], v145 offset:20480
	ds_read_b128 v[206:209], v145 offset:21504
	ds_read_b128 v[210:213], v145 offset:22528
	ds_read_b128 v[214:217], v145 offset:23552
	global_load_lds_dwordx4 v[140:141], off
	s_add_i32 m0, s18, 0x2000
	s_add_u32 s18, s52, 0x20000
	v_lshl_add_u64 v[194:195], s[52:53], 0, v[134:135]
	s_addc_u32 s19, s53, 0
	s_add_i32 s30, s31, s24
	global_load_lds_dwordx4 v[194:195], off
	v_lshl_add_u64 v[218:219], s[18:19], 0, v[0:1]
	s_mov_b32 m0, s30
	v_lshl_add_u64 v[220:221], s[72:73], 0, v[132:133]
	global_load_lds_dwordx4 v[218:219], off
	v_lshl_add_u64 v[218:219], s[18:19], 0, v[134:135]
	s_add_i32 m0, s30, 0x2000
	s_nop 0
	global_load_lds_dwordx4 v[218:219], off
	v_lshl_add_u64 v[218:219], s[72:73], 0, v[130:131]
	s_mov_b32 m0, s13
	s_nop 0
	global_load_lds_dwordx4 v[218:219], off
	s_mov_b32 m0, s25
	s_nop 0
	global_load_lds_dwordx4 v[220:221], off
	s_waitcnt vmcnt(8)
	s_waitcnt lgkmcnt(0)
	s_barrier
; #define PG8_STAGE(bufoff, gbase, voff) do { _Pragma("unroll") for (int _i = 0; _i < 2; ++_i) \
;         __builtin_amdgcn_global_load_lds((const unsigned*)((const char*)(gbase) + (voff)[_i]), (LAS unsigned*)(lds + (bufoff) + ldsw + _i * 8192), 16, 0, 0); } while (0)
; #define PG8_WAIT_V(n) asm volatile("s_waitcnt vmcnt(" #n ")" ::: "memory")
; #define PG8_WAIT_L(n) asm volatile("s_waitcnt lgkmcnt(" #n ")" ::: "memory")
; #define PG8_BAR __builtin_amdgcn_s_barrier()
; #define PG8_SCHED __builtin_amdgcn_sched_barrier(0)
; template <bool F8 = false, class Epi, class Sched>
; __device__ __forceinline__ void gemm_phase(LAS unsigned char* lds, const int lda, const int ldb, const int K, const Sched& S, const Epi& E) {
;     ...
;             PG8_WAIT_V(8); PG8_WAIT_L(0); PG8_BAR; PG8_MMA(1, 0, At, B0); PG8_MMA(1, 1, At, B1); PG8_BAR; PG8_SCHED;
;             PG8_LDB(B0, 1, 0); PG8_LDB(B1, 1, 1); PG8_SCHED; PG8_LDA(At, 1, 0); PG8_STAGE(PG8_SA(0, 1), a2 + hstepA, voffA);
;             PG8_WAIT_V(8); PG8_WAIT_L(0); PG8_BAR; PG8_MMA(0, 0, At, B0); PG8_MMA(0, 1, At, B1); PG8_BAR; PG8_SCHED;
	v_mfma_f32_16x16x32_bf16 v[62:65], v[146:149], v[178:181], v[62:65]
	v_mfma_f32_16x16x32_bf16 v[58:61], v[154:157], v[178:181], v[58:61]
	v_mfma_f32_16x16x32_bf16 v[54:57], v[146:149], v[186:189], v[54:57]
	v_mfma_f32_16x16x32_bf16 v[46:49], v[154:157], v[186:189], v[46:49]
	v_mfma_f32_16x16x32_bf16 v[38:41], v[146:149], v[202:205], v[38:41]
	v_mfma_f32_16x16x32_bf16 v[30:33], v[154:157], v[202:205], v[30:33]
	v_mfma_f32_16x16x32_bf16 v[22:25], v[146:149], v[210:213], v[22:25]
	v_mfma_f32_16x16x32_bf16 v[14:17], v[154:157], v[210:213], v[14:17]
	v_mfma_f32_16x16x32_bf16 v[62:65], v[150:153], v[182:185], v[62:65]
	v_mfma_f32_16x16x32_bf16 v[58:61], v[158:161], v[182:185], v[58:61]
	v_mfma_f32_16x16x32_bf16 v[54:57], v[150:153], v[190:193], v[54:57]
	v_mfma_f32_16x16x32_bf16 v[46:49], v[158:161], v[190:193], v[46:49]
	v_mfma_f32_16x16x32_bf16 v[38:41], v[150:153], v[206:209], v[38:41]
	v_mfma_f32_16x16x32_bf16 v[30:33], v[158:161], v[206:209], v[30:33]
	v_mfma_f32_16x16x32_bf16 v[22:25], v[150:153], v[214:217], v[22:25]
	v_mfma_f32_16x16x32_bf16 v[14:17], v[158:161], v[214:217], v[14:17]
	v_mfma_f32_16x16x32_bf16 v[50:53], v[162:165], v[178:181], v[50:53]
	v_mfma_f32_16x16x32_bf16 v[42:45], v[170:173], v[178:181], v[42:45]
	v_mfma_f32_16x16x32_bf16 v[34:37], v[162:165], v[186:189], v[34:37]
	v_mfma_f32_16x16x32_bf16 v[26:29], v[170:173], v[186:189], v[26:29]
	v_mfma_f32_16x16x32_bf16 v[18:21], v[162:165], v[202:205], v[18:21]
	v_mfma_f32_16x16x32_bf16 v[10:13], v[170:173], v[202:205], v[10:13]
	v_mfma_f32_16x16x32_bf16 v[6:9], v[162:165], v[210:213], v[6:9]
	v_mfma_f32_16x16x32_bf16 v[2:5], v[170:173], v[210:213], v[2:5]
	v_mfma_f32_16x16x32_bf16 v[50:53], v[166:169], v[182:185], v[50:53]
	v_mfma_f32_16x16x32_bf16 v[42:45], v[174:177], v[182:185], v[42:45]
	v_mfma_f32_16x16x32_bf16 v[34:37], v[166:169], v[190:193], v[34:37]
	v_mfma_f32_16x16x32_bf16 v[26:29], v[174:177], v[190:193], v[26:29]
	v_mfma_f32_16x16x32_bf16 v[18:21], v[166:169], v[206:209], v[18:21]
	v_mfma_f32_16x16x32_bf16 v[10:13], v[174:177], v[206:209], v[10:13]
	v_mfma_f32_16x16x32_bf16 v[6:9], v[166:169], v[214:217], v[6:9]
	v_mfma_f32_16x16x32_bf16 v[2:5], v[174:177], v[214:217], v[2:5]
	s_barrier
	s_add_i32 s30, 0, 0x18000
	s_add_i32 s31, 0, 0x1c000
	v_add_u32_e32 v158, s30, v143
	v_add_u32_e32 v174, s31, v143
	ds_read_b128 v[146:149], v158
	ds_read_b128 v[150:153], v158 offset:1024
	ds_read_b128 v[154:157], v158 offset:2048
	ds_read_b128 v[158:161], v158 offset:3072
	ds_read_b128 v[162:165], v174
	ds_read_b128 v[166:169], v174 offset:1024
	ds_read_b128 v[170:173], v174 offset:2048
	ds_read_b128 v[174:177], v174 offset:3072
	s_add_u32 s18, s72, 0x2e4000
	s_addc_u32 s19, s73, 0
	s_mov_b32 m0, s26
	v_lshl_add_u64 v[222:223], s[18:19], 0, v[130:131]
	ds_read_b128 v[178:181], v145 offset:32768
	ds_read_b128 v[182:185], v145 offset:33792
	ds_read_b128 v[186:189], v145 offset:34816
	ds_read_b128 v[190:193], v145 offset:35840
	ds_read_b128 v[202:205], v145 offset:36864
	ds_read_b128 v[206:209], v145 offset:37888
	ds_read_b128 v[210:213], v145 offset:38912
	ds_read_b128 v[214:217], v145 offset:39936
	global_load_lds_dwordx4 v[222:223], off
	v_lshl_add_u64 v[222:223], s[18:19], 0, v[132:133]
	s_mov_b32 m0, s27
	s_nop 0
	global_load_lds_dwordx4 v[222:223], off
	s_waitcnt vmcnt(8)
	s_waitcnt lgkmcnt(0)
	s_barrier
	v_mfma_f32_16x16x32_bf16 v[126:129], v[146:149], v[178:181], v[126:129]
	v_mfma_f32_16x16x32_bf16 v[122:125], v[154:157], v[178:181], v[122:125]
	v_mfma_f32_16x16x32_bf16 v[118:121], v[146:149], v[186:189], v[118:121]
	v_mfma_f32_16x16x32_bf16 v[110:113], v[154:157], v[186:189], v[110:113]
	v_mfma_f32_16x16x32_bf16 v[102:105], v[146:149], v[202:205], v[102:105]
	v_mfma_f32_16x16x32_bf16 v[94:97], v[154:157], v[202:205], v[94:97]
	v_mfma_f32_16x16x32_bf16 v[86:89], v[146:149], v[210:213], v[86:89]
	v_mfma_f32_16x16x32_bf16 v[78:81], v[154:157], v[210:213], v[78:81]
	v_mfma_f32_16x16x32_bf16 v[126:129], v[150:153], v[182:185], v[126:129]
	v_mfma_f32_16x16x32_bf16 v[122:125], v[158:161], v[182:185], v[122:125]
	v_mfma_f32_16x16x32_bf16 v[118:121], v[150:153], v[190:193], v[118:121]
	v_mfma_f32_16x16x32_bf16 v[110:113], v[158:161], v[190:193], v[110:113]
	v_mfma_f32_16x16x32_bf16 v[102:105], v[150:153], v[206:209], v[102:105]
	v_mfma_f32_16x16x32_bf16 v[94:97], v[158:161], v[206:209], v[94:97]
	v_mfma_f32_16x16x32_bf16 v[86:89], v[150:153], v[214:217], v[86:89]
	v_mfma_f32_16x16x32_bf16 v[78:81], v[158:161], v[214:217], v[78:81]
	v_mfma_f32_16x16x32_bf16 v[114:117], v[162:165], v[178:181], v[114:117]
	v_mfma_f32_16x16x32_bf16 v[106:109], v[170:173], v[178:181], v[106:109]
	v_mfma_f32_16x16x32_bf16 v[98:101], v[162:165], v[186:189], v[98:101]
	v_mfma_f32_16x16x32_bf16 v[90:93], v[170:173], v[186:189], v[90:93]
	v_mfma_f32_16x16x32_bf16 v[82:85], v[162:165], v[202:205], v[82:85]
	v_mfma_f32_16x16x32_bf16 v[74:77], v[170:173], v[202:205], v[74:77]
	v_mfma_f32_16x16x32_bf16 v[70:73], v[162:165], v[210:213], v[70:73]
	v_mfma_f32_16x16x32_bf16 v[66:69], v[170:173], v[210:213], v[66:69]
	v_mfma_f32_16x16x32_bf16 v[114:117], v[166:169], v[182:185], v[114:117]
	v_mfma_f32_16x16x32_bf16 v[106:109], v[174:177], v[182:185], v[106:109]
	v_mfma_f32_16x16x32_bf16 v[98:101], v[166:169], v[190:193], v[98:101]
	v_mfma_f32_16x16x32_bf16 v[90:93], v[174:177], v[190:193], v[90:93]
	v_mfma_f32_16x16x32_bf16 v[82:85], v[166:169], v[206:209], v[82:85]
	v_mfma_f32_16x16x32_bf16 v[74:77], v[174:177], v[206:209], v[74:77]
	v_mfma_f32_16x16x32_bf16 v[70:73], v[166:169], v[214:217], v[70:73]
	v_mfma_f32_16x16x32_bf16 v[66:69], v[174:177], v[214:217], v[66:69]
	s_barrier
; #define PG8_STAGE(bufoff, gbase, voff) do { _Pragma("unroll") for (int _i = 0; _i < 2; ++_i) \
;         __builtin_amdgcn_global_load_lds((const unsigned*)((const char*)(gbase) + (voff)[_i]), (LAS unsigned*)(lds + (bufoff) + ldsw + _i * 8192), 16, 0, 0); } while (0)
; #define PG8_WAIT_V(n) asm volatile("s_waitcnt vmcnt(" #n ")" ::: "memory")
; #define PG8_WAIT_L(n) asm volatile("s_waitcnt lgkmcnt(" #n ")" ::: "memory")
; #define PG8_BAR __builtin_amdgcn_s_barrier()
; #define PG8_SCHED __builtin_amdgcn_sched_barrier(0)
; template <bool F8 = false, class Epi, class Sched>
; __device__ __forceinline__ void gemm_phase(LAS unsigned char* lds, const int lda, const int ldb, const int K, const Sched& S, const Epi& E) {
;     ...
;             PG8_LDA(At, 1, 1); PG8_STAGE(PG8_SB(1, 0), b3, voffB); PG8_STAGE(PG8_SB(1, 1), b3 + hstepB, voffB); PG8_STAGE(PG8_SA(1, 0), a3, voffA);
;             PG8_WAIT_V(8); PG8_WAIT_L(0); PG8_BAR; PG8_MMA(1, 0, At, B0); PG8_MMA(1, 1, At, B1); PG8_BAR; PG8_SCHED;
;         }
	s_add_i32 s18, s30, s24
	v_lshl_add_u64 v[140:141], v[140:141], 0, s[40:41]
	s_mov_b32 m0, s18
	ds_read_b128 v[178:181], v145 offset:49152
	ds_read_b128 v[182:185], v145 offset:50176
	ds_read_b128 v[186:189], v145 offset:51200
	ds_read_b128 v[190:193], v145 offset:52224
	ds_read_b128 v[202:205], v145 offset:53248
	ds_read_b128 v[206:209], v145 offset:54272
	ds_read_b128 v[210:213], v145 offset:55296
	ds_read_b128 v[214:217], v145 offset:56320
	global_load_lds_dwordx4 v[140:141], off
	s_add_i32 m0, s18, 0x2000
	s_add_u32 s18, s52, 0x20080
	v_lshl_add_u64 v[140:141], v[194:195], 0, s[40:41]
	s_addc_u32 s19, s53, 0
	s_add_i32 s30, s31, s24
	global_load_lds_dwordx4 v[140:141], off
	v_lshl_add_u64 v[140:141], s[18:19], 0, v[0:1]
	s_mov_b32 m0, s30
	s_nop 0
	global_load_lds_dwordx4 v[140:141], off
	v_lshl_add_u64 v[140:141], s[18:19], 0, v[134:135]
	s_add_i32 m0, s30, 0x2000
	s_nop 0
	global_load_lds_dwordx4 v[140:141], off
	v_lshl_add_u64 v[140:141], v[218:219], 0, s[40:41]
	s_mov_b32 m0, s44
	s_nop 0
	global_load_lds_dwordx4 v[140:141], off
	v_lshl_add_u64 v[140:141], v[220:221], 0, s[40:41]
	s_mov_b32 m0, s56
	s_nop 0
	global_load_lds_dwordx4 v[140:141], off
	s_waitcnt vmcnt(8)
	s_waitcnt lgkmcnt(0)
	s_barrier
	v_mfma_f32_16x16x32_bf16 v[62:65], v[146:149], v[178:181], v[62:65]
	v_mfma_f32_16x16x32_bf16 v[58:61], v[154:157], v[178:181], v[58:61]
	v_mfma_f32_16x16x32_bf16 v[54:57], v[146:149], v[186:189], v[54:57]
	v_mfma_f32_16x16x32_bf16 v[46:49], v[154:157], v[186:189], v[46:49]
	v_mfma_f32_16x16x32_bf16 v[38:41], v[146:149], v[202:205], v[38:41]
	v_mfma_f32_16x16x32_bf16 v[30:33], v[154:157], v[202:205], v[30:33]
	v_mfma_f32_16x16x32_bf16 v[22:25], v[146:149], v[210:213], v[22:25]
	v_mfma_f32_16x16x32_bf16 v[14:17], v[154:157], v[210:213], v[14:17]
	v_mfma_f32_16x16x32_bf16 v[62:65], v[150:153], v[182:185], v[62:65]
	v_mfma_f32_16x16x32_bf16 v[58:61], v[158:161], v[182:185], v[58:61]
	v_mfma_f32_16x16x32_bf16 v[54:57], v[150:153], v[190:193], v[54:57]
	v_mfma_f32_16x16x32_bf16 v[46:49], v[158:161], v[190:193], v[46:49]
	v_mfma_f32_16x16x32_bf16 v[38:41], v[150:153], v[206:209], v[38:41]
	v_mfma_f32_16x16x32_bf16 v[30:33], v[158:161], v[206:209], v[30:33]
	v_mfma_f32_16x16x32_bf16 v[22:25], v[150:153], v[214:217], v[22:25]
	v_mfma_f32_16x16x32_bf16 v[14:17], v[158:161], v[214:217], v[14:17]
	v_mfma_f32_16x16x32_bf16 v[50:53], v[162:165], v[178:181], v[50:53]
	v_mfma_f32_16x16x32_bf16 v[42:45], v[170:173], v[178:181], v[42:45]
	v_mfma_f32_16x16x32_bf16 v[34:37], v[162:165], v[186:189], v[34:37]
	v_mfma_f32_16x16x32_bf16 v[26:29], v[170:173], v[186:189], v[26:29]
	v_mfma_f32_16x16x32_bf16 v[18:21], v[162:165], v[202:205], v[18:21]
	v_mfma_f32_16x16x32_bf16 v[10:13], v[170:173], v[202:205], v[10:13]
	v_mfma_f32_16x16x32_bf16 v[6:9], v[162:165], v[210:213], v[6:9]
	v_mfma_f32_16x16x32_bf16 v[2:5], v[170:173], v[210:213], v[2:5]
	v_mfma_f32_16x16x32_bf16 v[50:53], v[166:169], v[182:185], v[50:53]
	v_mfma_f32_16x16x32_bf16 v[42:45], v[174:177], v[182:185], v[42:45]
	v_mfma_f32_16x16x32_bf16 v[34:37], v[166:169], v[190:193], v[34:37]
	v_mfma_f32_16x16x32_bf16 v[26:29], v[174:177], v[190:193], v[26:29]
	v_mfma_f32_16x16x32_bf16 v[18:21], v[166:169], v[206:209], v[18:21]
	v_mfma_f32_16x16x32_bf16 v[10:13], v[174:177], v[206:209], v[10:13]
	v_mfma_f32_16x16x32_bf16 v[6:9], v[166:169], v[214:217], v[6:9]
	v_mfma_f32_16x16x32_bf16 v[2:5], v[174:177], v[214:217], v[2:5]
	s_barrier
	s_add_i32 s29, s29, 2
	s_add_u32 s11, s11, 0x100
	s_addc_u32 s28, s28, 0
	s_cmp_gt_u32 s29, 5
	s_mov_b64 s[18:19], s[20:21]
	s_cbranch_scc0 .LBB0_436
	s_and_b64 vcc, exec, s[8:9]
	s_cbranch_vccz .LBB0_439
	s_barrier

; #define PG8_STAGE(bufoff, gbase, voff) do { _Pragma("unroll") for (int _i = 0; _i < 2; ++_i) \
;         __builtin_amdgcn_global_load_lds((const unsigned*)((const char*)(gbase) + (voff)[_i]), (LAS unsigned*)(lds + (bufoff) + ldsw + _i * 8192), 16, 0, 0); } while (0)
; #define PG8_WAIT_V(n) asm volatile("s_waitcnt vmcnt(" #n ")" ::: "memory")
; #define PG8_WAIT_L(n) asm volatile("s_waitcnt lgkmcnt(" #n ")" ::: "memory")
; #define PG8_BAR __builtin_amdgcn_s_barrier()
; #define PG8_SCHED __builtin_amdgcn_sched_barrier(0)
; template <bool F8 = false, class Epi, class Sched>
; __device__ __forceinline__ void gemm_phase(LAS unsigned char* lds, const int lda, const int ldb, const int K, const Sched& S, const Epi& E) {
;     ...
;         for (int t = 0; t < nt; t += 2) {
;             const bool last = (t == nt - 2);
;             const char* a1 = cA + (size_t)(t + 1) * kstep;
;             const char* a2 = last ? nA : cA + (size_t)(t + 2) * kstep; const char* b2 = last ? nB : cB + (size_t)(t + 2) * kstep;
;             const char* a3 = a2 + kstep; const char* b3 = b2 + kstep;
;             PG8_LDB(B0, 0, 0); PG8_LDB(B1, 0, 1); PG8_SCHED; PG8_LDA(At, 0, 0); PG8_STAGE(PG8_SA(1, 1), a1 + hstepA, voffA);
;             PG8_WAIT_V(8); PG8_WAIT_L(0); PG8_BAR; PG8_MMA(0, 0, At, B0); PG8_MMA(0, 1, At, B1); PG8_BAR; PG8_SCHED;
;             PG8_LDA(At, 0, 1); PG8_STAGE(PG8_SB(0, 0), b2, voffB); PG8_STAGE(PG8_SB(0, 1), b2 + hstepB, voffB); PG8_STAGE(PG8_SA(0, 0), a2, voffA);
;             PG8_WAIT_V(8); PG8_WAIT_L(0); PG8_BAR; PG8_MMA(1, 0, At, B0); PG8_MMA(1, 1, At, B1); PG8_BAR; PG8_SCHED;
.LBB0_690:
	s_add_u32 s52, s18, 0x100
	s_addc_u32 s53, s19, 0
	s_add_i32 s29, 0, 0x10000
	s_cmp_eq_u32 s28, 12
	s_cselect_b32 s75, s21, s53
	s_cselect_b32 s74, s20, s52
	s_cselect_b32 s73, s11, s17
	s_cselect_b32 s72, s10, s15
	s_add_i32 s30, 0, 0x14000
	v_add_u32_e32 v142, s29, v245
	v_add_u32_e32 v158, s30, v245
	ds_read_b128 v[130:133], v142
	ds_read_b128 v[134:137], v142 offset:1024
	ds_read_b128 v[138:141], v142 offset:2048
	ds_read_b128 v[142:145], v142 offset:3072
	ds_read_b128 v[146:149], v158
	ds_read_b128 v[150:153], v158 offset:1024
	ds_read_b128 v[154:157], v158 offset:2048
	ds_read_b128 v[158:161], v158 offset:3072
	v_lshl_add_u64 v[194:195], s[18:19], 0, v[208:209]
	s_add_i32 m0, s95, 0xc000
	ds_read_b128 v[162:165], v247
	ds_read_b128 v[166:169], v247 offset:1024
	ds_read_b128 v[170:173], v247 offset:2048
	ds_read_b128 v[174:177], v247 offset:3072
	ds_read_b128 v[178:181], v247 offset:4096
	ds_read_b128 v[182:185], v247 offset:5120
	ds_read_b128 v[186:189], v247 offset:6144
	ds_read_b128 v[190:193], v247 offset:7168
	global_load_lds_dwordx4 v[194:195], off
	v_lshl_add_u64 v[194:195], s[18:19], 0, v[210:211]
	s_add_i32 m0, s95, 0xe000
	s_nop 0
	global_load_lds_dwordx4 v[194:195], off
	s_waitcnt vmcnt(8)
	s_waitcnt lgkmcnt(0)
	s_barrier
	v_mfma_f32_16x16x32_bf16 v[126:129], v[130:133], v[162:165], v[126:129]
	v_mfma_f32_16x16x32_bf16 v[122:125], v[138:141], v[162:165], v[122:125]
	v_mfma_f32_16x16x32_bf16 v[110:113], v[130:133], v[170:173], v[110:113]
	v_mfma_f32_16x16x32_bf16 v[106:109], v[138:141], v[170:173], v[106:109]
	v_mfma_f32_16x16x32_bf16 v[94:97], v[130:133], v[178:181], v[94:97]
	v_mfma_f32_16x16x32_bf16 v[90:93], v[138:141], v[178:181], v[90:93]
	v_mfma_f32_16x16x32_bf16 v[78:81], v[130:133], v[186:189], v[78:81]
	v_mfma_f32_16x16x32_bf16 v[74:77], v[138:141], v[186:189], v[74:77]
	v_mfma_f32_16x16x32_bf16 v[126:129], v[134:137], v[166:169], v[126:129]
	v_mfma_f32_16x16x32_bf16 v[122:125], v[142:145], v[166:169], v[122:125]
	v_mfma_f32_16x16x32_bf16 v[110:113], v[134:137], v[174:177], v[110:113]
	v_mfma_f32_16x16x32_bf16 v[106:109], v[142:145], v[174:177], v[106:109]
	v_mfma_f32_16x16x32_bf16 v[94:97], v[134:137], v[182:185], v[94:97]
	v_mfma_f32_16x16x32_bf16 v[90:93], v[142:145], v[182:185], v[90:93]
	v_mfma_f32_16x16x32_bf16 v[78:81], v[134:137], v[190:193], v[78:81]
	v_mfma_f32_16x16x32_bf16 v[74:77], v[142:145], v[190:193], v[74:77]
	v_mfma_f32_16x16x32_bf16 v[118:121], v[146:149], v[162:165], v[118:121]
	v_mfma_f32_16x16x32_bf16 v[114:117], v[154:157], v[162:165], v[114:117]
	v_mfma_f32_16x16x32_bf16 v[102:105], v[146:149], v[170:173], v[102:105]
	v_mfma_f32_16x16x32_bf16 v[98:101], v[154:157], v[170:173], v[98:101]
	v_mfma_f32_16x16x32_bf16 v[86:89], v[146:149], v[178:181], v[86:89]
	v_mfma_f32_16x16x32_bf16 v[82:85], v[154:157], v[178:181], v[82:85]
	v_mfma_f32_16x16x32_bf16 v[70:73], v[146:149], v[186:189], v[70:73]
	v_mfma_f32_16x16x32_bf16 v[66:69], v[154:157], v[186:189], v[66:69]
	v_mfma_f32_16x16x32_bf16 v[118:121], v[150:153], v[166:169], v[118:121]
	v_mfma_f32_16x16x32_bf16 v[114:117], v[158:161], v[166:169], v[114:117]
	v_mfma_f32_16x16x32_bf16 v[102:105], v[150:153], v[174:177], v[102:105]
	v_mfma_f32_16x16x32_bf16 v[98:101], v[158:161], v[174:177], v[98:101]
	v_mfma_f32_16x16x32_bf16 v[86:89], v[150:153], v[182:185], v[86:89]
	v_mfma_f32_16x16x32_bf16 v[82:85], v[158:161], v[182:185], v[82:85]
	v_mfma_f32_16x16x32_bf16 v[70:73], v[150:153], v[190:193], v[70:73]
	v_mfma_f32_16x16x32_bf16 v[66:69], v[158:161], v[190:193], v[66:69]
	s_barrier
	s_add_i32 s18, s29, s94
	v_lshl_add_u64 v[194:195], s[72:73], 0, v[0:1]
	s_mov_b32 m0, s18
	ds_read_b128 v[162:165], v247 offset:16384
	ds_read_b128 v[166:169], v247 offset:17408
	ds_read_b128 v[170:173], v247 offset:18432
	ds_read_b128 v[174:177], v247 offset:19456
	ds_read_b128 v[178:181], v247 offset:20480
	ds_read_b128 v[182:185], v247 offset:21504
	ds_read_b128 v[186:189], v247 offset:22528
	ds_read_b128 v[190:193], v247 offset:23552
	global_load_lds_dwordx4 v[194:195], off
	s_add_i32 m0, s18, 0x2000
	s_add_u32 s18, s72, 0x40000
	v_lshl_add_u64 v[212:213], s[72:73], 0, v[206:207]
	s_addc_u32 s19, s73, 0
	s_add_i32 s29, s30, s94
	global_load_lds_dwordx4 v[212:213], off
	v_lshl_add_u64 v[214:215], s[18:19], 0, v[0:1]
	s_mov_b32 m0, s29
	v_lshl_add_u64 v[216:217], s[74:75], 0, v[204:205]
	global_load_lds_dwordx4 v[214:215], off
	v_lshl_add_u64 v[214:215], s[18:19], 0, v[206:207]
	s_add_i32 m0, s29, 0x2000
	s_nop 0
	global_load_lds_dwordx4 v[214:215], off
	v_lshl_add_u64 v[214:215], s[74:75], 0, v[202:203]
	s_mov_b32 m0, s95
	s_nop 0
	global_load_lds_dwordx4 v[214:215], off
	s_mov_b32 m0, s96
	s_nop 0
	global_load_lds_dwordx4 v[216:217], off
	s_waitcnt vmcnt(8)
	s_waitcnt lgkmcnt(0)
	s_barrier
; #define PG8_STAGE(bufoff, gbase, voff) do { _Pragma("unroll") for (int _i = 0; _i < 2; ++_i) \
;         __builtin_amdgcn_global_load_lds((const unsigned*)((const char*)(gbase) + (voff)[_i]), (LAS unsigned*)(lds + (bufoff) + ldsw + _i * 8192), 16, 0, 0); } while (0)
; #define PG8_WAIT_V(n) asm volatile("s_waitcnt vmcnt(" #n ")" ::: "memory")
; #define PG8_WAIT_L(n) asm volatile("s_waitcnt lgkmcnt(" #n ")" ::: "memory")
; #define PG8_BAR __builtin_amdgcn_s_barrier()
; #define PG8_SCHED __builtin_amdgcn_sched_barrier(0)
; template <bool F8 = false, class Epi, class Sched>
; __device__ __forceinline__ void gemm_phase(LAS unsigned char* lds, const int lda, const int ldb, const int K, const Sched& S, const Epi& E) {
;     ...
;             PG8_WAIT_V(8); PG8_WAIT_L(0); PG8_BAR; PG8_MMA(1, 0, At, B0); PG8_MMA(1, 1, At, B1); PG8_BAR; PG8_SCHED;
;             PG8_LDB(B0, 1, 0); PG8_LDB(B1, 1, 1); PG8_SCHED; PG8_LDA(At, 1, 0); PG8_STAGE(PG8_SA(0, 1), a2 + hstepA, voffA);
;             PG8_WAIT_V(8); PG8_WAIT_L(0); PG8_BAR; PG8_MMA(0, 0, At, B0); PG8_MMA(0, 1, At, B1); PG8_BAR; PG8_SCHED;
	v_mfma_f32_16x16x32_bf16 v[62:65], v[130:133], v[162:165], v[62:65]
	v_mfma_f32_16x16x32_bf16 v[58:61], v[138:141], v[162:165], v[58:61]
	v_mfma_f32_16x16x32_bf16 v[46:49], v[130:133], v[170:173], v[46:49]
	v_mfma_f32_16x16x32_bf16 v[42:45], v[138:141], v[170:173], v[42:45]
	v_mfma_f32_16x16x32_bf16 v[30:33], v[130:133], v[178:181], v[30:33]
	v_mfma_f32_16x16x32_bf16 v[26:29], v[138:141], v[178:181], v[26:29]
	v_mfma_f32_16x16x32_bf16 v[14:17], v[130:133], v[186:189], v[14:17]
	v_mfma_f32_16x16x32_bf16 v[10:13], v[138:141], v[186:189], v[10:13]
	v_mfma_f32_16x16x32_bf16 v[62:65], v[134:137], v[166:169], v[62:65]
	v_mfma_f32_16x16x32_bf16 v[58:61], v[142:145], v[166:169], v[58:61]
	v_mfma_f32_16x16x32_bf16 v[46:49], v[134:137], v[174:177], v[46:49]
	v_mfma_f32_16x16x32_bf16 v[42:45], v[142:145], v[174:177], v[42:45]
	v_mfma_f32_16x16x32_bf16 v[30:33], v[134:137], v[182:185], v[30:33]
	v_mfma_f32_16x16x32_bf16 v[26:29], v[142:145], v[182:185], v[26:29]
	v_mfma_f32_16x16x32_bf16 v[14:17], v[134:137], v[190:193], v[14:17]
	v_mfma_f32_16x16x32_bf16 v[10:13], v[142:145], v[190:193], v[10:13]
	v_mfma_f32_16x16x32_bf16 v[54:57], v[146:149], v[162:165], v[54:57]
	v_mfma_f32_16x16x32_bf16 v[50:53], v[154:157], v[162:165], v[50:53]
	v_mfma_f32_16x16x32_bf16 v[38:41], v[146:149], v[170:173], v[38:41]
	v_mfma_f32_16x16x32_bf16 v[34:37], v[154:157], v[170:173], v[34:37]
	v_mfma_f32_16x16x32_bf16 v[22:25], v[146:149], v[178:181], v[22:25]
	v_mfma_f32_16x16x32_bf16 v[18:21], v[154:157], v[178:181], v[18:21]
	v_mfma_f32_16x16x32_bf16 v[6:9], v[146:149], v[186:189], v[6:9]
	v_mfma_f32_16x16x32_bf16 v[2:5], v[154:157], v[186:189], v[2:5]
	v_mfma_f32_16x16x32_bf16 v[54:57], v[150:153], v[166:169], v[54:57]
	v_mfma_f32_16x16x32_bf16 v[50:53], v[158:161], v[166:169], v[50:53]
	v_mfma_f32_16x16x32_bf16 v[38:41], v[150:153], v[174:177], v[38:41]
	v_mfma_f32_16x16x32_bf16 v[34:37], v[158:161], v[174:177], v[34:37]
	v_mfma_f32_16x16x32_bf16 v[22:25], v[150:153], v[182:185], v[22:25]
	v_mfma_f32_16x16x32_bf16 v[18:21], v[158:161], v[182:185], v[18:21]
	v_mfma_f32_16x16x32_bf16 v[6:9], v[150:153], v[190:193], v[6:9]
	v_mfma_f32_16x16x32_bf16 v[2:5], v[158:161], v[190:193], v[2:5]
	s_barrier
	s_add_i32 s29, 0, 0x18000
	s_add_i32 s30, 0, 0x1c000
	v_add_u32_e32 v142, s29, v245
	v_add_u32_e32 v158, s30, v245
	ds_read_b128 v[130:133], v142
	ds_read_b128 v[134:137], v142 offset:1024
	ds_read_b128 v[138:141], v142 offset:2048
	ds_read_b128 v[142:145], v142 offset:3072
	ds_read_b128 v[146:149], v158
	ds_read_b128 v[150:153], v158 offset:1024
	ds_read_b128 v[154:157], v158 offset:2048
	ds_read_b128 v[158:161], v158 offset:3072
	s_add_u32 s18, s74, 0xc0000
	s_addc_u32 s19, s75, 0
	s_mov_b32 m0, s97
	v_lshl_add_u64 v[218:219], s[18:19], 0, v[202:203]
	ds_read_b128 v[162:165], v247 offset:32768
	ds_read_b128 v[166:169], v247 offset:33792
	ds_read_b128 v[170:173], v247 offset:34816
	ds_read_b128 v[174:177], v247 offset:35840
	ds_read_b128 v[178:181], v247 offset:36864
	ds_read_b128 v[182:185], v247 offset:37888
	ds_read_b128 v[186:189], v247 offset:38912
	ds_read_b128 v[190:193], v247 offset:39936
	global_load_lds_dwordx4 v[218:219], off
	v_lshl_add_u64 v[218:219], s[18:19], 0, v[204:205]
	s_mov_b32 m0, s56
	s_nop 0
	global_load_lds_dwordx4 v[218:219], off
	s_waitcnt vmcnt(8)
	s_waitcnt lgkmcnt(0)
	s_barrier
	v_mfma_f32_16x16x32_bf16 v[126:129], v[130:133], v[162:165], v[126:129]
	v_mfma_f32_16x16x32_bf16 v[122:125], v[138:141], v[162:165], v[122:125]
	v_mfma_f32_16x16x32_bf16 v[110:113], v[130:133], v[170:173], v[110:113]
	v_mfma_f32_16x16x32_bf16 v[106:109], v[138:141], v[170:173], v[106:109]
	v_mfma_f32_16x16x32_bf16 v[94:97], v[130:133], v[178:181], v[94:97]
	v_mfma_f32_16x16x32_bf16 v[90:93], v[138:141], v[178:181], v[90:93]
	v_mfma_f32_16x16x32_bf16 v[78:81], v[130:133], v[186:189], v[78:81]
	v_mfma_f32_16x16x32_bf16 v[74:77], v[138:141], v[186:189], v[74:77]
	v_mfma_f32_16x16x32_bf16 v[126:129], v[134:137], v[166:169], v[126:129]
	v_mfma_f32_16x16x32_bf16 v[122:125], v[142:145], v[166:169], v[122:125]
	v_mfma_f32_16x16x32_bf16 v[110:113], v[134:137], v[174:177], v[110:113]
	v_mfma_f32_16x16x32_bf16 v[106:109], v[142:145], v[174:177], v[106:109]
	v_mfma_f32_16x16x32_bf16 v[94:97], v[134:137], v[182:185], v[94:97]
	v_mfma_f32_16x16x32_bf16 v[90:93], v[142:145], v[182:185], v[90:93]
	v_mfma_f32_16x16x32_bf16 v[78:81], v[134:137], v[190:193], v[78:81]
	v_mfma_f32_16x16x32_bf16 v[74:77], v[142:145], v[190:193], v[74:77]
	v_mfma_f32_16x16x32_bf16 v[118:121], v[146:149], v[162:165], v[118:121]
	v_mfma_f32_16x16x32_bf16 v[114:117], v[154:157], v[162:165], v[114:117]
	v_mfma_f32_16x16x32_bf16 v[102:105], v[146:149], v[170:173], v[102:105]
	v_mfma_f32_16x16x32_bf16 v[98:101], v[154:157], v[170:173], v[98:101]
	v_mfma_f32_16x16x32_bf16 v[86:89], v[146:149], v[178:181], v[86:89]
	v_mfma_f32_16x16x32_bf16 v[82:85], v[154:157], v[178:181], v[82:85]
	v_mfma_f32_16x16x32_bf16 v[70:73], v[146:149], v[186:189], v[70:73]
	v_mfma_f32_16x16x32_bf16 v[66:69], v[154:157], v[186:189], v[66:69]
	v_mfma_f32_16x16x32_bf16 v[118:121], v[150:153], v[166:169], v[118:121]
	v_mfma_f32_16x16x32_bf16 v[114:117], v[158:161], v[166:169], v[114:117]
	v_mfma_f32_16x16x32_bf16 v[102:105], v[150:153], v[174:177], v[102:105]
	v_mfma_f32_16x16x32_bf16 v[98:101], v[158:161], v[174:177], v[98:101]
	v_mfma_f32_16x16x32_bf16 v[86:89], v[150:153], v[182:185], v[86:89]
	v_mfma_f32_16x16x32_bf16 v[82:85], v[158:161], v[182:185], v[82:85]
	v_mfma_f32_16x16x32_bf16 v[70:73], v[150:153], v[190:193], v[70:73]
	v_mfma_f32_16x16x32_bf16 v[66:69], v[158:161], v[190:193], v[66:69]
	s_barrier
; #define PG8_STAGE(bufoff, gbase, voff) do { _Pragma("unroll") for (int _i = 0; _i < 2; ++_i) \
;         __builtin_amdgcn_global_load_lds((const unsigned*)((const char*)(gbase) + (voff)[_i]), (LAS unsigned*)(lds + (bufoff) + ldsw + _i * 8192), 16, 0, 0); } while (0)
; #define PG8_WAIT_V(n) asm volatile("s_waitcnt vmcnt(" #n ")" ::: "memory")
; #define PG8_WAIT_L(n) asm volatile("s_waitcnt lgkmcnt(" #n ")" ::: "memory")
; #define PG8_BAR __builtin_amdgcn_s_barrier()
; #define PG8_SCHED __builtin_amdgcn_sched_barrier(0)
; template <bool F8 = false, class Epi, class Sched>
; __device__ __forceinline__ void gemm_phase(LAS unsigned char* lds, const int lda, const int ldb, const int K, const Sched& S, const Epi& E) {
;     ...
;             PG8_LDA(At, 1, 1); PG8_STAGE(PG8_SB(1, 0), b3, voffB); PG8_STAGE(PG8_SB(1, 1), b3 + hstepB, voffB); PG8_STAGE(PG8_SA(1, 0), a3, voffA);
;             PG8_WAIT_V(8); PG8_WAIT_L(0); PG8_BAR; PG8_MMA(1, 0, At, B0); PG8_MMA(1, 1, At, B1); PG8_BAR; PG8_SCHED;
;         }
	s_add_i32 s18, s29, s94
	v_lshl_add_u64 v[194:195], v[194:195], 0, s[40:41]
	s_mov_b32 m0, s18
	ds_read_b128 v[162:165], v247 offset:49152
	ds_read_b128 v[166:169], v247 offset:50176
	ds_read_b128 v[170:173], v247 offset:51200
	ds_read_b128 v[174:177], v247 offset:52224
	ds_read_b128 v[178:181], v247 offset:53248
	ds_read_b128 v[182:185], v247 offset:54272
	ds_read_b128 v[186:189], v247 offset:55296
	ds_read_b128 v[190:193], v247 offset:56320
	global_load_lds_dwordx4 v[194:195], off
	s_add_i32 m0, s18, 0x2000
	s_add_u32 s18, s72, 0x40080
	v_lshl_add_u64 v[194:195], v[212:213], 0, s[40:41]
	s_addc_u32 s19, s73, 0
	s_add_i32 s29, s30, s94
	global_load_lds_dwordx4 v[194:195], off
	v_lshl_add_u64 v[194:195], s[18:19], 0, v[0:1]
	s_mov_b32 m0, s29
	s_nop 0
	global_load_lds_dwordx4 v[194:195], off
	v_lshl_add_u64 v[194:195], s[18:19], 0, v[206:207]
	s_add_i32 m0, s29, 0x2000
	s_nop 0
	global_load_lds_dwordx4 v[194:195], off
	v_lshl_add_u64 v[194:195], v[214:215], 0, s[40:41]
	s_mov_b32 m0, s57
	s_nop 0
	global_load_lds_dwordx4 v[194:195], off
	v_lshl_add_u64 v[194:195], v[216:217], 0, s[40:41]
	s_mov_b32 m0, s24
	s_nop 0
	global_load_lds_dwordx4 v[194:195], off
	s_waitcnt vmcnt(8)
	s_waitcnt lgkmcnt(0)
	s_barrier
	v_mfma_f32_16x16x32_bf16 v[62:65], v[130:133], v[162:165], v[62:65]
	v_mfma_f32_16x16x32_bf16 v[58:61], v[138:141], v[162:165], v[58:61]
	v_mfma_f32_16x16x32_bf16 v[46:49], v[130:133], v[170:173], v[46:49]
	v_mfma_f32_16x16x32_bf16 v[42:45], v[138:141], v[170:173], v[42:45]
	v_mfma_f32_16x16x32_bf16 v[30:33], v[130:133], v[178:181], v[30:33]
	v_mfma_f32_16x16x32_bf16 v[26:29], v[138:141], v[178:181], v[26:29]
	v_mfma_f32_16x16x32_bf16 v[14:17], v[130:133], v[186:189], v[14:17]
	v_mfma_f32_16x16x32_bf16 v[10:13], v[138:141], v[186:189], v[10:13]
	v_mfma_f32_16x16x32_bf16 v[62:65], v[134:137], v[166:169], v[62:65]
	v_mfma_f32_16x16x32_bf16 v[58:61], v[142:145], v[166:169], v[58:61]
	v_mfma_f32_16x16x32_bf16 v[46:49], v[134:137], v[174:177], v[46:49]
	v_mfma_f32_16x16x32_bf16 v[42:45], v[142:145], v[174:177], v[42:45]
	v_mfma_f32_16x16x32_bf16 v[30:33], v[134:137], v[182:185], v[30:33]
	v_mfma_f32_16x16x32_bf16 v[26:29], v[142:145], v[182:185], v[26:29]
	v_mfma_f32_16x16x32_bf16 v[14:17], v[134:137], v[190:193], v[14:17]
	v_mfma_f32_16x16x32_bf16 v[10:13], v[142:145], v[190:193], v[10:13]
	v_mfma_f32_16x16x32_bf16 v[54:57], v[146:149], v[162:165], v[54:57]
	v_mfma_f32_16x16x32_bf16 v[50:53], v[154:157], v[162:165], v[50:53]
	v_mfma_f32_16x16x32_bf16 v[38:41], v[146:149], v[170:173], v[38:41]
	v_mfma_f32_16x16x32_bf16 v[34:37], v[154:157], v[170:173], v[34:37]
	v_mfma_f32_16x16x32_bf16 v[22:25], v[146:149], v[178:181], v[22:25]
	v_mfma_f32_16x16x32_bf16 v[18:21], v[154:157], v[178:181], v[18:21]
	v_mfma_f32_16x16x32_bf16 v[6:9], v[146:149], v[186:189], v[6:9]
	v_mfma_f32_16x16x32_bf16 v[2:5], v[154:157], v[186:189], v[2:5]
	v_mfma_f32_16x16x32_bf16 v[54:57], v[150:153], v[166:169], v[54:57]
	v_mfma_f32_16x16x32_bf16 v[50:53], v[158:161], v[166:169], v[50:53]
	v_mfma_f32_16x16x32_bf16 v[38:41], v[150:153], v[174:177], v[38:41]
	v_mfma_f32_16x16x32_bf16 v[34:37], v[158:161], v[174:177], v[34:37]
	v_mfma_f32_16x16x32_bf16 v[22:25], v[150:153], v[182:185], v[22:25]
	v_mfma_f32_16x16x32_bf16 v[18:21], v[158:161], v[182:185], v[18:21]
	v_mfma_f32_16x16x32_bf16 v[6:9], v[150:153], v[190:193], v[6:9]
	v_mfma_f32_16x16x32_bf16 v[2:5], v[158:161], v[190:193], v[2:5]
	s_barrier
	s_add_i32 s28, s28, 2
	s_add_u32 s15, s15, 0x100
	s_addc_u32 s17, s17, 0
	s_cmp_gt_u32 s28, 13
	s_mov_b64 s[18:19], s[52:53]
	s_cbranch_scc0 .LBB0_690
	s_and_b64 vcc, exec, s[12:13]
	s_cbranch_vccz .LBB0_693
	s_barrier

; #define PG8_STAGE(bufoff, gbase, voff) do { _Pragma("unroll") for (int _i = 0; _i < 2; ++_i) \
;         __builtin_amdgcn_global_load_lds((const unsigned*)((const char*)(gbase) + (voff)[_i]), (LAS unsigned*)(lds + (bufoff) + ldsw + _i * 8192), 16, 0, 0); } while (0)
; #define PG8_WAIT_V(n) asm volatile("s_waitcnt vmcnt(" #n ")" ::: "memory")
; #define PG8_WAIT_L(n) asm volatile("s_waitcnt lgkmcnt(" #n ")" ::: "memory")
; #define PG8_BAR __builtin_amdgcn_s_barrier()
; #define PG8_SCHED __builtin_amdgcn_sched_barrier(0)
; template <bool F8 = false, class Epi, class Sched>
; __device__ __forceinline__ void gemm_phase(LAS unsigned char* lds, const int lda, const int ldb, const int K, const Sched& S, const Epi& E) {
;     ...
;         for (int t = 0; t < nt; t += 2) {
;             const bool last = (t == nt - 2);
;             const char* a1 = cA + (size_t)(t + 1) * kstep;
;             const char* a2 = last ? nA : cA + (size_t)(t + 2) * kstep; const char* b2 = last ? nB : cB + (size_t)(t + 2) * kstep;
;             const char* a3 = a2 + kstep; const char* b3 = b2 + kstep;
;             PG8_LDB(B0, 0, 0); PG8_LDB(B1, 0, 1); PG8_SCHED; PG8_LDA(At, 0, 0); PG8_STAGE(PG8_SA(1, 1), a1 + hstepA, voffA);
;             PG8_WAIT_V(8); PG8_WAIT_L(0); PG8_BAR; PG8_MMA(0, 0, At, B0); PG8_MMA(0, 1, At, B1); PG8_BAR; PG8_SCHED;
;             PG8_LDA(At, 0, 1); PG8_STAGE(PG8_SB(0, 0), b2, voffB); PG8_STAGE(PG8_SB(0, 1), b2 + hstepB, voffB); PG8_STAGE(PG8_SA(0, 0), a2, voffA);
;             PG8_WAIT_V(8); PG8_WAIT_L(0); PG8_BAR; PG8_MMA(1, 0, At, B0); PG8_MMA(1, 1, At, B1); PG8_BAR; PG8_SCHED;
.LBB0_807:
	s_add_u32 s20, s18, 0xfff80080
	s_addc_u32 s21, s19, -1
	s_add_i32 s29, 0, 0x10000
	s_cmp_eq_u32 s28, 28
	s_cselect_b32 s53, s11, s21
	s_cselect_b32 s52, s75, s20
	v_add_u32_e32 v140, s29, v143
	s_cselect_b32 s21, s9, s96
	s_cselect_b32 s20, s94, s95
	s_add_i32 s33, 0, 0x14000
	ds_read_b128 v[146:149], v140
	ds_read_b128 v[150:153], v140 offset:1024
	ds_read_b128 v[154:157], v140 offset:2048
	ds_read_b128 v[158:161], v140 offset:3072
	v_add_u32_e32 v140, s33, v143
	ds_read_b128 v[162:165], v140
	ds_read_b128 v[166:169], v140 offset:1024
	ds_read_b128 v[170:173], v140 offset:2048
	ds_read_b128 v[174:177], v140 offset:3072
	v_lshl_add_u64 v[140:141], s[18:19], 0, v[136:137]
	s_add_i32 m0, s25, 0xc000
	ds_read_b128 v[178:181], v145
	ds_read_b128 v[182:185], v145 offset:1024
	ds_read_b128 v[186:189], v145 offset:2048
	ds_read_b128 v[190:193], v145 offset:3072
	ds_read_b128 v[202:205], v145 offset:4096
	ds_read_b128 v[206:209], v145 offset:5120
	ds_read_b128 v[210:213], v145 offset:6144
	ds_read_b128 v[214:217], v145 offset:7168
	global_load_lds_dwordx4 v[140:141], off
	v_lshl_add_u64 v[140:141], s[18:19], 0, v[138:139]
	s_add_i32 m0, s25, 0xe000
	s_nop 0
	global_load_lds_dwordx4 v[140:141], off
	s_waitcnt vmcnt(8)
	s_waitcnt lgkmcnt(0)
	s_barrier
	v_mfma_f32_16x16x32_bf16 v[126:129], v[146:149], v[178:181], v[126:129]
	v_mfma_f32_16x16x32_bf16 v[122:125], v[154:157], v[178:181], v[122:125]
	v_mfma_f32_16x16x32_bf16 v[118:121], v[146:149], v[186:189], v[118:121]
	v_mfma_f32_16x16x32_bf16 v[110:113], v[154:157], v[186:189], v[110:113]
	v_mfma_f32_16x16x32_bf16 v[102:105], v[146:149], v[202:205], v[102:105]
	v_mfma_f32_16x16x32_bf16 v[94:97], v[154:157], v[202:205], v[94:97]
	v_mfma_f32_16x16x32_bf16 v[86:89], v[146:149], v[210:213], v[86:89]
	v_mfma_f32_16x16x32_bf16 v[78:81], v[154:157], v[210:213], v[78:81]
	v_mfma_f32_16x16x32_bf16 v[126:129], v[150:153], v[182:185], v[126:129]
	v_mfma_f32_16x16x32_bf16 v[122:125], v[158:161], v[182:185], v[122:125]
	v_mfma_f32_16x16x32_bf16 v[118:121], v[150:153], v[190:193], v[118:121]
	v_mfma_f32_16x16x32_bf16 v[110:113], v[158:161], v[190:193], v[110:113]
	v_mfma_f32_16x16x32_bf16 v[102:105], v[150:153], v[206:209], v[102:105]
	v_mfma_f32_16x16x32_bf16 v[94:97], v[158:161], v[206:209], v[94:97]
	v_mfma_f32_16x16x32_bf16 v[86:89], v[150:153], v[214:217], v[86:89]
	v_mfma_f32_16x16x32_bf16 v[78:81], v[158:161], v[214:217], v[78:81]
	v_mfma_f32_16x16x32_bf16 v[114:117], v[162:165], v[178:181], v[114:117]
	v_mfma_f32_16x16x32_bf16 v[106:109], v[170:173], v[178:181], v[106:109]
	v_mfma_f32_16x16x32_bf16 v[98:101], v[162:165], v[186:189], v[98:101]
	v_mfma_f32_16x16x32_bf16 v[90:93], v[170:173], v[186:189], v[90:93]
	v_mfma_f32_16x16x32_bf16 v[82:85], v[162:165], v[202:205], v[82:85]
	v_mfma_f32_16x16x32_bf16 v[74:77], v[170:173], v[202:205], v[74:77]
	v_mfma_f32_16x16x32_bf16 v[70:73], v[162:165], v[210:213], v[70:73]
	v_mfma_f32_16x16x32_bf16 v[66:69], v[170:173], v[210:213], v[66:69]
	v_mfma_f32_16x16x32_bf16 v[114:117], v[166:169], v[182:185], v[114:117]
	v_mfma_f32_16x16x32_bf16 v[106:109], v[174:177], v[182:185], v[106:109]
	v_mfma_f32_16x16x32_bf16 v[98:101], v[166:169], v[190:193], v[98:101]
	v_mfma_f32_16x16x32_bf16 v[90:93], v[174:177], v[190:193], v[90:93]
	v_mfma_f32_16x16x32_bf16 v[82:85], v[166:169], v[206:209], v[82:85]
	v_mfma_f32_16x16x32_bf16 v[74:77], v[174:177], v[206:209], v[74:77]
	v_mfma_f32_16x16x32_bf16 v[70:73], v[166:169], v[214:217], v[70:73]
	v_mfma_f32_16x16x32_bf16 v[66:69], v[174:177], v[214:217], v[66:69]
	s_barrier
	s_add_i32 s29, s29, s24
	v_lshl_add_u64 v[140:141], s[20:21], 0, v[0:1]
	s_mov_b32 m0, s29
	ds_read_b128 v[178:181], v145 offset:16384
	ds_read_b128 v[182:185], v145 offset:17408
	ds_read_b128 v[186:189], v145 offset:18432
	ds_read_b128 v[190:193], v145 offset:19456
	ds_read_b128 v[202:205], v145 offset:20480
	ds_read_b128 v[206:209], v145 offset:21504
	ds_read_b128 v[210:213], v145 offset:22528
	ds_read_b128 v[214:217], v145 offset:23552
	global_load_lds_dwordx4 v[140:141], off
	s_add_i32 m0, s29, 0x2000
	s_add_u32 s30, s20, 0x80000
	v_lshl_add_u64 v[194:195], s[20:21], 0, v[130:131]
	s_addc_u32 s31, s21, 0
	s_add_i32 s29, s33, s24
	global_load_lds_dwordx4 v[194:195], off
	v_lshl_add_u64 v[218:219], s[30:31], 0, v[0:1]
	s_mov_b32 m0, s29
	v_lshl_add_u64 v[220:221], s[52:53], 0, v[132:133]
	global_load_lds_dwordx4 v[218:219], off
	v_lshl_add_u64 v[218:219], s[30:31], 0, v[130:131]
	s_add_i32 m0, s29, 0x2000
	s_nop 0
	global_load_lds_dwordx4 v[218:219], off
	v_lshl_add_u64 v[218:219], s[52:53], 0, v[134:135]
	s_mov_b32 m0, s25
	s_nop 0
	global_load_lds_dwordx4 v[218:219], off
	s_mov_b32 m0, s26
	s_nop 0
	global_load_lds_dwordx4 v[220:221], off
	s_waitcnt vmcnt(8)
	s_waitcnt lgkmcnt(0)
	s_barrier
; #define PG8_STAGE(bufoff, gbase, voff) do { _Pragma("unroll") for (int _i = 0; _i < 2; ++_i) \
;         __builtin_amdgcn_global_load_lds((const unsigned*)((const char*)(gbase) + (voff)[_i]), (LAS unsigned*)(lds + (bufoff) + ldsw + _i * 8192), 16, 0, 0); } while (0)
; #define PG8_WAIT_V(n) asm volatile("s_waitcnt vmcnt(" #n ")" ::: "memory")
; #define PG8_WAIT_L(n) asm volatile("s_waitcnt lgkmcnt(" #n ")" ::: "memory")
; #define PG8_BAR __builtin_amdgcn_s_barrier()
; #define PG8_SCHED __builtin_amdgcn_sched_barrier(0)
; template <bool F8 = false, class Epi, class Sched>
; __device__ __forceinline__ void gemm_phase(LAS unsigned char* lds, const int lda, const int ldb, const int K, const Sched& S, const Epi& E) {
;     ...
;             PG8_WAIT_V(8); PG8_WAIT_L(0); PG8_BAR; PG8_MMA(1, 0, At, B0); PG8_MMA(1, 1, At, B1); PG8_BAR; PG8_SCHED;
;             PG8_LDB(B0, 1, 0); PG8_LDB(B1, 1, 1); PG8_SCHED; PG8_LDA(At, 1, 0); PG8_STAGE(PG8_SA(0, 1), a2 + hstepA, voffA);
;             PG8_WAIT_V(8); PG8_WAIT_L(0); PG8_BAR; PG8_MMA(0, 0, At, B0); PG8_MMA(0, 1, At, B1); PG8_BAR; PG8_SCHED;
	v_mfma_f32_16x16x32_bf16 v[62:65], v[146:149], v[178:181], v[62:65]
	v_mfma_f32_16x16x32_bf16 v[58:61], v[154:157], v[178:181], v[58:61]
	v_mfma_f32_16x16x32_bf16 v[54:57], v[146:149], v[186:189], v[54:57]
	v_mfma_f32_16x16x32_bf16 v[46:49], v[154:157], v[186:189], v[46:49]
	v_mfma_f32_16x16x32_bf16 v[38:41], v[146:149], v[202:205], v[38:41]
	v_mfma_f32_16x16x32_bf16 v[30:33], v[154:157], v[202:205], v[30:33]
	v_mfma_f32_16x16x32_bf16 v[22:25], v[146:149], v[210:213], v[22:25]
	v_mfma_f32_16x16x32_bf16 v[14:17], v[154:157], v[210:213], v[14:17]
	v_mfma_f32_16x16x32_bf16 v[62:65], v[150:153], v[182:185], v[62:65]
	v_mfma_f32_16x16x32_bf16 v[58:61], v[158:161], v[182:185], v[58:61]
	v_mfma_f32_16x16x32_bf16 v[54:57], v[150:153], v[190:193], v[54:57]
	v_mfma_f32_16x16x32_bf16 v[46:49], v[158:161], v[190:193], v[46:49]
	v_mfma_f32_16x16x32_bf16 v[38:41], v[150:153], v[206:209], v[38:41]
	v_mfma_f32_16x16x32_bf16 v[30:33], v[158:161], v[206:209], v[30:33]
	v_mfma_f32_16x16x32_bf16 v[22:25], v[150:153], v[214:217], v[22:25]
	v_mfma_f32_16x16x32_bf16 v[14:17], v[158:161], v[214:217], v[14:17]
	v_mfma_f32_16x16x32_bf16 v[50:53], v[162:165], v[178:181], v[50:53]
	v_mfma_f32_16x16x32_bf16 v[42:45], v[170:173], v[178:181], v[42:45]
	v_mfma_f32_16x16x32_bf16 v[34:37], v[162:165], v[186:189], v[34:37]
	v_mfma_f32_16x16x32_bf16 v[26:29], v[170:173], v[186:189], v[26:29]
	v_mfma_f32_16x16x32_bf16 v[18:21], v[162:165], v[202:205], v[18:21]
	v_mfma_f32_16x16x32_bf16 v[10:13], v[170:173], v[202:205], v[10:13]
	v_mfma_f32_16x16x32_bf16 v[6:9], v[162:165], v[210:213], v[6:9]
	v_mfma_f32_16x16x32_bf16 v[2:5], v[170:173], v[210:213], v[2:5]
	v_mfma_f32_16x16x32_bf16 v[50:53], v[166:169], v[182:185], v[50:53]
	v_mfma_f32_16x16x32_bf16 v[42:45], v[174:177], v[182:185], v[42:45]
	v_mfma_f32_16x16x32_bf16 v[34:37], v[166:169], v[190:193], v[34:37]
	v_mfma_f32_16x16x32_bf16 v[26:29], v[174:177], v[190:193], v[26:29]
	v_mfma_f32_16x16x32_bf16 v[18:21], v[166:169], v[206:209], v[18:21]
	v_mfma_f32_16x16x32_bf16 v[10:13], v[174:177], v[206:209], v[10:13]
	v_mfma_f32_16x16x32_bf16 v[6:9], v[166:169], v[214:217], v[6:9]
	v_mfma_f32_16x16x32_bf16 v[2:5], v[174:177], v[214:217], v[2:5]
	s_barrier
	s_add_i32 s29, 0, 0x18000
	s_add_i32 s33, 0, 0x1c000
	v_add_u32_e32 v158, s29, v143
	v_add_u32_e32 v174, s33, v143
	ds_read_b128 v[146:149], v158
	ds_read_b128 v[150:153], v158 offset:1024
	ds_read_b128 v[154:157], v158 offset:2048
	ds_read_b128 v[158:161], v158 offset:3072
	ds_read_b128 v[162:165], v174
	ds_read_b128 v[166:169], v174 offset:1024
	ds_read_b128 v[170:173], v174 offset:2048
	ds_read_b128 v[174:177], v174 offset:3072
	s_add_u32 s30, s52, 0x80000
	s_addc_u32 s31, s53, 0
	s_mov_b32 m0, s27
	v_lshl_add_u64 v[222:223], s[30:31], 0, v[134:135]
	ds_read_b128 v[178:181], v145 offset:32768
	ds_read_b128 v[182:185], v145 offset:33792
	ds_read_b128 v[186:189], v145 offset:34816
	ds_read_b128 v[190:193], v145 offset:35840
	ds_read_b128 v[202:205], v145 offset:36864
	ds_read_b128 v[206:209], v145 offset:37888
	ds_read_b128 v[210:213], v145 offset:38912
	ds_read_b128 v[214:217], v145 offset:39936
	global_load_lds_dwordx4 v[222:223], off
	v_lshl_add_u64 v[222:223], s[30:31], 0, v[132:133]
	s_mov_b32 m0, s44
	s_nop 0
	global_load_lds_dwordx4 v[222:223], off
	s_waitcnt vmcnt(8)
	s_waitcnt lgkmcnt(0)
	s_barrier
	v_mfma_f32_16x16x32_bf16 v[126:129], v[146:149], v[178:181], v[126:129]
	v_mfma_f32_16x16x32_bf16 v[122:125], v[154:157], v[178:181], v[122:125]
	v_mfma_f32_16x16x32_bf16 v[118:121], v[146:149], v[186:189], v[118:121]
	v_mfma_f32_16x16x32_bf16 v[110:113], v[154:157], v[186:189], v[110:113]
	v_mfma_f32_16x16x32_bf16 v[102:105], v[146:149], v[202:205], v[102:105]
	v_mfma_f32_16x16x32_bf16 v[94:97], v[154:157], v[202:205], v[94:97]
	v_mfma_f32_16x16x32_bf16 v[86:89], v[146:149], v[210:213], v[86:89]
	v_mfma_f32_16x16x32_bf16 v[78:81], v[154:157], v[210:213], v[78:81]
	v_mfma_f32_16x16x32_bf16 v[126:129], v[150:153], v[182:185], v[126:129]
	v_mfma_f32_16x16x32_bf16 v[122:125], v[158:161], v[182:185], v[122:125]
	v_mfma_f32_16x16x32_bf16 v[118:121], v[150:153], v[190:193], v[118:121]
	v_mfma_f32_16x16x32_bf16 v[110:113], v[158:161], v[190:193], v[110:113]
	v_mfma_f32_16x16x32_bf16 v[102:105], v[150:153], v[206:209], v[102:105]
	v_mfma_f32_16x16x32_bf16 v[94:97], v[158:161], v[206:209], v[94:97]
	v_mfma_f32_16x16x32_bf16 v[86:89], v[150:153], v[214:217], v[86:89]
	v_mfma_f32_16x16x32_bf16 v[78:81], v[158:161], v[214:217], v[78:81]
	v_mfma_f32_16x16x32_bf16 v[114:117], v[162:165], v[178:181], v[114:117]
	v_mfma_f32_16x16x32_bf16 v[106:109], v[170:173], v[178:181], v[106:109]
	v_mfma_f32_16x16x32_bf16 v[98:101], v[162:165], v[186:189], v[98:101]
	v_mfma_f32_16x16x32_bf16 v[90:93], v[170:173], v[186:189], v[90:93]
	v_mfma_f32_16x16x32_bf16 v[82:85], v[162:165], v[202:205], v[82:85]
	v_mfma_f32_16x16x32_bf16 v[74:77], v[170:173], v[202:205], v[74:77]
	v_mfma_f32_16x16x32_bf16 v[70:73], v[162:165], v[210:213], v[70:73]
	v_mfma_f32_16x16x32_bf16 v[66:69], v[170:173], v[210:213], v[66:69]
	v_mfma_f32_16x16x32_bf16 v[114:117], v[166:169], v[182:185], v[114:117]
	v_mfma_f32_16x16x32_bf16 v[106:109], v[174:177], v[182:185], v[106:109]
	v_mfma_f32_16x16x32_bf16 v[98:101], v[166:169], v[190:193], v[98:101]
	v_mfma_f32_16x16x32_bf16 v[90:93], v[174:177], v[190:193], v[90:93]
	v_mfma_f32_16x16x32_bf16 v[82:85], v[166:169], v[206:209], v[82:85]
	v_mfma_f32_16x16x32_bf16 v[74:77], v[174:177], v[206:209], v[74:77]
	v_mfma_f32_16x16x32_bf16 v[70:73], v[166:169], v[214:217], v[70:73]
	v_mfma_f32_16x16x32_bf16 v[66:69], v[174:177], v[214:217], v[66:69]
	s_barrier
; #define PG8_STAGE(bufoff, gbase, voff) do { _Pragma("unroll") for (int _i = 0; _i < 2; ++_i) \
;         __builtin_amdgcn_global_load_lds((const unsigned*)((const char*)(gbase) + (voff)[_i]), (LAS unsigned*)(lds + (bufoff) + ldsw + _i * 8192), 16, 0, 0); } while (0)
; #define PG8_WAIT_V(n) asm volatile("s_waitcnt vmcnt(" #n ")" ::: "memory")
; #define PG8_WAIT_L(n) asm volatile("s_waitcnt lgkmcnt(" #n ")" ::: "memory")
; #define PG8_BAR __builtin_amdgcn_s_barrier()
; #define PG8_SCHED __builtin_amdgcn_sched_barrier(0)
; template <bool F8 = false, class Epi, class Sched>
; __device__ __forceinline__ void gemm_phase(LAS unsigned char* lds, const int lda, const int ldb, const int K, const Sched& S, const Epi& E) {
;     ...
;             PG8_LDA(At, 1, 1); PG8_STAGE(PG8_SB(1, 0), b3, voffB); PG8_STAGE(PG8_SB(1, 1), b3 + hstepB, voffB); PG8_STAGE(PG8_SA(1, 0), a3, voffA);
;             PG8_WAIT_V(8); PG8_WAIT_L(0); PG8_BAR; PG8_MMA(1, 0, At, B0); PG8_MMA(1, 1, At, B1); PG8_BAR; PG8_SCHED;
;         }
	s_add_i32 s29, s29, s24
	v_lshl_add_u64 v[140:141], v[140:141], 0, s[40:41]
	s_mov_b32 m0, s29
	ds_read_b128 v[178:181], v145 offset:49152
	ds_read_b128 v[182:185], v145 offset:50176
	ds_read_b128 v[186:189], v145 offset:51200
	ds_read_b128 v[190:193], v145 offset:52224
	ds_read_b128 v[202:205], v145 offset:53248
	ds_read_b128 v[206:209], v145 offset:54272
	ds_read_b128 v[210:213], v145 offset:55296
	ds_read_b128 v[214:217], v145 offset:56320
	global_load_lds_dwordx4 v[140:141], off
	s_add_i32 m0, s29, 0x2000
	s_add_u32 s20, s20, 0x80080
	v_lshl_add_u64 v[140:141], v[194:195], 0, s[40:41]
	s_addc_u32 s21, s21, 0
	s_add_i32 s29, s33, s24
	global_load_lds_dwordx4 v[140:141], off
	v_lshl_add_u64 v[140:141], s[20:21], 0, v[0:1]
	s_mov_b32 m0, s29
	s_nop 0
	global_load_lds_dwordx4 v[140:141], off
	v_lshl_add_u64 v[140:141], s[20:21], 0, v[130:131]
	s_add_i32 m0, s29, 0x2000
	s_nop 0
	global_load_lds_dwordx4 v[140:141], off
	v_lshl_add_u64 v[140:141], v[218:219], 0, s[40:41]
	s_mov_b32 m0, s56
	s_nop 0
	global_load_lds_dwordx4 v[140:141], off
	v_lshl_add_u64 v[140:141], v[220:221], 0, s[40:41]
	s_mov_b32 m0, s57
	s_nop 0
	global_load_lds_dwordx4 v[140:141], off
	s_waitcnt vmcnt(8)
	s_waitcnt lgkmcnt(0)
	s_barrier
	v_mfma_f32_16x16x32_bf16 v[62:65], v[146:149], v[178:181], v[62:65]
	v_mfma_f32_16x16x32_bf16 v[58:61], v[154:157], v[178:181], v[58:61]
	v_mfma_f32_16x16x32_bf16 v[54:57], v[146:149], v[186:189], v[54:57]
	v_mfma_f32_16x16x32_bf16 v[46:49], v[154:157], v[186:189], v[46:49]
	v_mfma_f32_16x16x32_bf16 v[38:41], v[146:149], v[202:205], v[38:41]
	v_mfma_f32_16x16x32_bf16 v[30:33], v[154:157], v[202:205], v[30:33]
	v_mfma_f32_16x16x32_bf16 v[22:25], v[146:149], v[210:213], v[22:25]
	v_mfma_f32_16x16x32_bf16 v[14:17], v[154:157], v[210:213], v[14:17]
	v_mfma_f32_16x16x32_bf16 v[62:65], v[150:153], v[182:185], v[62:65]
	v_mfma_f32_16x16x32_bf16 v[58:61], v[158:161], v[182:185], v[58:61]
	v_mfma_f32_16x16x32_bf16 v[54:57], v[150:153], v[190:193], v[54:57]
	v_mfma_f32_16x16x32_bf16 v[46:49], v[158:161], v[190:193], v[46:49]
	v_mfma_f32_16x16x32_bf16 v[38:41], v[150:153], v[206:209], v[38:41]
	v_mfma_f32_16x16x32_bf16 v[30:33], v[158:161], v[206:209], v[30:33]
	v_mfma_f32_16x16x32_bf16 v[22:25], v[150:153], v[214:217], v[22:25]
	v_mfma_f32_16x16x32_bf16 v[14:17], v[158:161], v[214:217], v[14:17]
	v_mfma_f32_16x16x32_bf16 v[50:53], v[162:165], v[178:181], v[50:53]
	v_mfma_f32_16x16x32_bf16 v[42:45], v[170:173], v[178:181], v[42:45]
	v_mfma_f32_16x16x32_bf16 v[34:37], v[162:165], v[186:189], v[34:37]
	v_mfma_f32_16x16x32_bf16 v[26:29], v[170:173], v[186:189], v[26:29]
	v_mfma_f32_16x16x32_bf16 v[18:21], v[162:165], v[202:205], v[18:21]
	v_mfma_f32_16x16x32_bf16 v[10:13], v[170:173], v[202:205], v[10:13]
	v_mfma_f32_16x16x32_bf16 v[6:9], v[162:165], v[210:213], v[6:9]
	v_mfma_f32_16x16x32_bf16 v[2:5], v[170:173], v[210:213], v[2:5]
	v_mfma_f32_16x16x32_bf16 v[50:53], v[166:169], v[182:185], v[50:53]
	v_mfma_f32_16x16x32_bf16 v[42:45], v[174:177], v[182:185], v[42:45]
	v_mfma_f32_16x16x32_bf16 v[34:37], v[166:169], v[190:193], v[34:37]
	v_mfma_f32_16x16x32_bf16 v[26:29], v[174:177], v[190:193], v[26:29]
	v_mfma_f32_16x16x32_bf16 v[18:21], v[166:169], v[206:209], v[18:21]
	v_mfma_f32_16x16x32_bf16 v[10:13], v[174:177], v[206:209], v[10:13]
	v_mfma_f32_16x16x32_bf16 v[6:9], v[166:169], v[214:217], v[6:9]
	v_mfma_f32_16x16x32_bf16 v[2:5], v[174:177], v[214:217], v[2:5]
	s_barrier
	s_add_i32 s28, s28, 2
	s_add_u32 s18, s18, 0x100
	s_addc_u32 s19, s19, 0
	s_add_u32 s95, s95, 0x100
	s_addc_u32 s96, s96, 0
	s_cmp_gt_u32 s28, 29
	s_cbranch_scc0 .LBB0_807
	s_and_b64 vcc, exec, s[6:7]
	s_cbranch_vccz .LBB0_810
	s_barrier

; #define PG8_STAGE(bufoff, gbase, voff) do { _Pragma("unroll") for (int _i = 0; _i < 2; ++_i) \
;         __builtin_amdgcn_global_load_lds((const unsigned*)((const char*)(gbase) + (voff)[_i]), (LAS unsigned*)(lds + (bufoff) + ldsw + _i * 8192), 16, 0, 0); } while (0)
; #define PG8_WAIT_V(n) asm volatile("s_waitcnt vmcnt(" #n ")" ::: "memory")
; #define PG8_WAIT_L(n) asm volatile("s_waitcnt lgkmcnt(" #n ")" ::: "memory")
; #define PG8_BAR __builtin_amdgcn_s_barrier()
; #define PG8_SCHED __builtin_amdgcn_sched_barrier(0)
; template <bool F8 = false, class Epi, class Sched>
; __device__ __forceinline__ void gemm_phase(LAS unsigned char* lds, const int lda, const int ldb, const int K, const Sched& S, const Epi& E) {
;     ...
;         for (int t = 0; t < nt; t += 2) {
;             const bool last = (t == nt - 2);
;             const char* a1 = cA + (size_t)(t + 1) * kstep;
;             const char* a2 = last ? nA : cA + (size_t)(t + 2) * kstep; const char* b2 = last ? nB : cB + (size_t)(t + 2) * kstep;
;             const char* a3 = a2 + kstep; const char* b3 = b2 + kstep;
;             PG8_LDB(B0, 0, 0); PG8_LDB(B1, 0, 1); PG8_SCHED; PG8_LDA(At, 0, 0); PG8_STAGE(PG8_SA(1, 1), a1 + hstepA, voffA);
;             PG8_WAIT_V(8); PG8_WAIT_L(0); PG8_BAR; PG8_MMA(0, 0, At, B0); PG8_MMA(0, 1, At, B1); PG8_BAR; PG8_SCHED;
;             PG8_LDA(At, 0, 1); PG8_STAGE(PG8_SB(0, 0), b2, voffB); PG8_STAGE(PG8_SB(0, 1), b2 + hstepB, voffB); PG8_STAGE(PG8_SA(0, 0), a2, voffA);
;             PG8_WAIT_V(8); PG8_WAIT_L(0); PG8_BAR; PG8_MMA(1, 0, At, B0); PG8_MMA(1, 1, At, B1); PG8_BAR; PG8_SCHED;
.LBB0_835:
	s_add_u32 s18, s16, 0xfff80080
	s_addc_u32 s19, s17, -1
	s_add_i32 s29, 0, 0x10000
	s_cmp_eq_u32 s28, 4
	s_cselect_b32 s21, s13, s19
	s_cselect_b32 s20, s12, s18
	v_add_u32_e32 v0, s29, v140
	s_cselect_b32 s19, s75, s96
	s_cselect_b32 s18, s94, s95
	s_add_i32 s33, 0, 0x14000
	ds_read_b128 v[144:147], v0
	ds_read_b128 v[148:151], v0 offset:1024
	ds_read_b128 v[152:155], v0 offset:2048
	ds_read_b128 v[156:159], v0 offset:3072
	v_add_u32_e32 v0, s33, v140
	ds_read_b128 v[160:163], v0
	ds_read_b128 v[164:167], v0 offset:1024
	ds_read_b128 v[168:171], v0 offset:2048
	ds_read_b128 v[172:175], v0 offset:3072
	v_lshl_add_u64 v[138:139], s[16:17], 0, v[134:135]
	s_add_i32 m0, s25, 0xc000
	ds_read_b128 v[176:179], v142
	ds_read_b128 v[180:183], v142 offset:1024
	ds_read_b128 v[184:187], v142 offset:2048
	ds_read_b128 v[188:191], v142 offset:3072
	ds_read_b128 v[192:195], v142 offset:4096
	ds_read_b128 v[202:205], v142 offset:5120
	ds_read_b128 v[206:209], v142 offset:6144
	ds_read_b128 v[210:213], v142 offset:7168
	global_load_lds_dwordx4 v[138:139], off
	v_lshl_add_u64 v[138:139], s[16:17], 0, v[136:137]
	s_add_i32 m0, s25, 0xe000
	s_nop 0
	global_load_lds_dwordx4 v[138:139], off
	s_waitcnt vmcnt(8)
	s_waitcnt lgkmcnt(0)
	s_barrier
	v_mfma_f32_16x16x32_bf16 v[126:129], v[144:147], v[176:179], v[126:129]
	v_mfma_f32_16x16x32_bf16 v[122:125], v[152:155], v[176:179], v[122:125]
	v_mfma_f32_16x16x32_bf16 v[118:121], v[144:147], v[184:187], v[118:121]
	v_mfma_f32_16x16x32_bf16 v[110:113], v[152:155], v[184:187], v[110:113]
	v_mfma_f32_16x16x32_bf16 v[102:105], v[144:147], v[192:195], v[102:105]
	v_mfma_f32_16x16x32_bf16 v[94:97], v[152:155], v[192:195], v[94:97]
	v_mfma_f32_16x16x32_bf16 v[86:89], v[144:147], v[206:209], v[86:89]
	v_mfma_f32_16x16x32_bf16 v[78:81], v[152:155], v[206:209], v[78:81]
	v_mfma_f32_16x16x32_bf16 v[126:129], v[148:151], v[180:183], v[126:129]
	v_mfma_f32_16x16x32_bf16 v[122:125], v[156:159], v[180:183], v[122:125]
	v_mfma_f32_16x16x32_bf16 v[118:121], v[148:151], v[188:191], v[118:121]
	v_mfma_f32_16x16x32_bf16 v[110:113], v[156:159], v[188:191], v[110:113]
	v_mfma_f32_16x16x32_bf16 v[102:105], v[148:151], v[202:205], v[102:105]
	v_mfma_f32_16x16x32_bf16 v[94:97], v[156:159], v[202:205], v[94:97]
	v_mfma_f32_16x16x32_bf16 v[86:89], v[148:151], v[210:213], v[86:89]
	v_mfma_f32_16x16x32_bf16 v[78:81], v[156:159], v[210:213], v[78:81]
	v_mfma_f32_16x16x32_bf16 v[114:117], v[160:163], v[176:179], v[114:117]
	v_mfma_f32_16x16x32_bf16 v[106:109], v[168:171], v[176:179], v[106:109]
	v_mfma_f32_16x16x32_bf16 v[98:101], v[160:163], v[184:187], v[98:101]
	v_mfma_f32_16x16x32_bf16 v[90:93], v[168:171], v[184:187], v[90:93]
	v_mfma_f32_16x16x32_bf16 v[82:85], v[160:163], v[192:195], v[82:85]
	v_mfma_f32_16x16x32_bf16 v[74:77], v[168:171], v[192:195], v[74:77]
	v_mfma_f32_16x16x32_bf16 v[70:73], v[160:163], v[206:209], v[70:73]
	v_mfma_f32_16x16x32_bf16 v[66:69], v[168:171], v[206:209], v[66:69]
	v_mfma_f32_16x16x32_bf16 v[114:117], v[164:167], v[180:183], v[114:117]
	v_mfma_f32_16x16x32_bf16 v[106:109], v[172:175], v[180:183], v[106:109]
	v_mfma_f32_16x16x32_bf16 v[98:101], v[164:167], v[188:191], v[98:101]
	v_mfma_f32_16x16x32_bf16 v[90:93], v[172:175], v[188:191], v[90:93]
	v_mfma_f32_16x16x32_bf16 v[82:85], v[164:167], v[202:205], v[82:85]
	v_mfma_f32_16x16x32_bf16 v[74:77], v[172:175], v[202:205], v[74:77]
	v_mfma_f32_16x16x32_bf16 v[70:73], v[164:167], v[210:213], v[70:73]
	v_mfma_f32_16x16x32_bf16 v[66:69], v[172:175], v[210:213], v[66:69]
	s_barrier
	s_add_i32 s29, s29, s24
	v_lshl_add_u64 v[138:139], s[18:19], 0, v[132:133]
	s_mov_b32 m0, s29
	ds_read_b128 v[176:179], v142 offset:16384
	ds_read_b128 v[180:183], v142 offset:17408
	ds_read_b128 v[184:187], v142 offset:18432
	ds_read_b128 v[188:191], v142 offset:19456
	ds_read_b128 v[192:195], v142 offset:20480
	ds_read_b128 v[202:205], v142 offset:21504
	ds_read_b128 v[206:209], v142 offset:22528
	ds_read_b128 v[210:213], v142 offset:23552
	global_load_lds_dwordx4 v[138:139], off
	s_add_i32 m0, s29, 0x2000
	s_add_u32 s30, s18, 0x80000
	v_lshl_add_u64 v[214:215], s[18:19], 0, v[130:131]
	s_addc_u32 s31, s19, 0
	s_add_i32 s29, s33, s24
	global_load_lds_dwordx4 v[214:215], off
	v_lshl_add_u64 v[216:217], s[30:31], 0, v[132:133]
	s_mov_b32 m0, s29
	v_lshl_add_u64 v[218:219], s[20:21], 0, v[130:131]
	global_load_lds_dwordx4 v[216:217], off
	v_lshl_add_u64 v[216:217], s[30:31], 0, v[130:131]
	s_add_i32 m0, s29, 0x2000
	s_nop 0
	global_load_lds_dwordx4 v[216:217], off
	v_lshl_add_u64 v[216:217], s[20:21], 0, v[132:133]
	s_mov_b32 m0, s25
	s_nop 0
	global_load_lds_dwordx4 v[216:217], off
	s_mov_b32 m0, s26
	s_nop 0
	global_load_lds_dwordx4 v[218:219], off
	s_waitcnt vmcnt(8)
	s_waitcnt lgkmcnt(0)
	s_barrier
; #define PG8_STAGE(bufoff, gbase, voff) do { _Pragma("unroll") for (int _i = 0; _i < 2; ++_i) \
;         __builtin_amdgcn_global_load_lds((const unsigned*)((const char*)(gbase) + (voff)[_i]), (LAS unsigned*)(lds + (bufoff) + ldsw + _i * 8192), 16, 0, 0); } while (0)
; #define PG8_WAIT_V(n) asm volatile("s_waitcnt vmcnt(" #n ")" ::: "memory")
; #define PG8_WAIT_L(n) asm volatile("s_waitcnt lgkmcnt(" #n ")" ::: "memory")
; #define PG8_BAR __builtin_amdgcn_s_barrier()
; #define PG8_SCHED __builtin_amdgcn_sched_barrier(0)
; template <bool F8 = false, class Epi, class Sched>
; __device__ __forceinline__ void gemm_phase(LAS unsigned char* lds, const int lda, const int ldb, const int K, const Sched& S, const Epi& E) {
;     ...
;             PG8_WAIT_V(8); PG8_WAIT_L(0); PG8_BAR; PG8_MMA(1, 0, At, B0); PG8_MMA(1, 1, At, B1); PG8_BAR; PG8_SCHED;
;             PG8_LDB(B0, 1, 0); PG8_LDB(B1, 1, 1); PG8_SCHED; PG8_LDA(At, 1, 0); PG8_STAGE(PG8_SA(0, 1), a2 + hstepA, voffA);
;             PG8_WAIT_V(8); PG8_WAIT_L(0); PG8_BAR; PG8_MMA(0, 0, At, B0); PG8_MMA(0, 1, At, B1); PG8_BAR; PG8_SCHED;
	v_mfma_f32_16x16x32_bf16 v[62:65], v[144:147], v[176:179], v[62:65]
	v_mfma_f32_16x16x32_bf16 v[58:61], v[152:155], v[176:179], v[58:61]
	v_mfma_f32_16x16x32_bf16 v[54:57], v[144:147], v[184:187], v[54:57]
	v_mfma_f32_16x16x32_bf16 v[42:45], v[152:155], v[184:187], v[42:45]
	v_mfma_f32_16x16x32_bf16 v[38:41], v[144:147], v[192:195], v[38:41]
	v_mfma_f32_16x16x32_bf16 v[26:29], v[152:155], v[192:195], v[26:29]
	v_mfma_f32_16x16x32_bf16 v[22:25], v[144:147], v[206:209], v[22:25]
	v_mfma_f32_16x16x32_bf16 v[10:13], v[152:155], v[206:209], v[10:13]
	v_mfma_f32_16x16x32_bf16 v[62:65], v[148:151], v[180:183], v[62:65]
	v_mfma_f32_16x16x32_bf16 v[58:61], v[156:159], v[180:183], v[58:61]
	v_mfma_f32_16x16x32_bf16 v[54:57], v[148:151], v[188:191], v[54:57]
	v_mfma_f32_16x16x32_bf16 v[42:45], v[156:159], v[188:191], v[42:45]
	v_mfma_f32_16x16x32_bf16 v[38:41], v[148:151], v[202:205], v[38:41]
	v_mfma_f32_16x16x32_bf16 v[26:29], v[156:159], v[202:205], v[26:29]
	v_mfma_f32_16x16x32_bf16 v[22:25], v[148:151], v[210:213], v[22:25]
	v_mfma_f32_16x16x32_bf16 v[10:13], v[156:159], v[210:213], v[10:13]
	v_mfma_f32_16x16x32_bf16 v[50:53], v[160:163], v[176:179], v[50:53]
	v_mfma_f32_16x16x32_bf16 v[46:49], v[168:171], v[176:179], v[46:49]
	v_mfma_f32_16x16x32_bf16 v[34:37], v[160:163], v[184:187], v[34:37]
	v_mfma_f32_16x16x32_bf16 v[30:33], v[168:171], v[184:187], v[30:33]
	v_mfma_f32_16x16x32_bf16 v[18:21], v[160:163], v[192:195], v[18:21]
	v_mfma_f32_16x16x32_bf16 v[14:17], v[168:171], v[192:195], v[14:17]
	v_mfma_f32_16x16x32_bf16 v[6:9], v[160:163], v[206:209], v[6:9]
	v_mfma_f32_16x16x32_bf16 v[2:5], v[168:171], v[206:209], v[2:5]
	v_mfma_f32_16x16x32_bf16 v[50:53], v[164:167], v[180:183], v[50:53]
	v_mfma_f32_16x16x32_bf16 v[46:49], v[172:175], v[180:183], v[46:49]
	v_mfma_f32_16x16x32_bf16 v[34:37], v[164:167], v[188:191], v[34:37]
	v_mfma_f32_16x16x32_bf16 v[30:33], v[172:175], v[188:191], v[30:33]
	v_mfma_f32_16x16x32_bf16 v[18:21], v[164:167], v[202:205], v[18:21]
	v_mfma_f32_16x16x32_bf16 v[14:17], v[172:175], v[202:205], v[14:17]
	v_mfma_f32_16x16x32_bf16 v[6:9], v[164:167], v[210:213], v[6:9]
	v_mfma_f32_16x16x32_bf16 v[2:5], v[172:175], v[210:213], v[2:5]
	s_barrier
	s_add_i32 s29, 0, 0x18000
	v_add_u32_e32 v0, s29, v140
	s_add_i32 s30, 0, 0x1c000
	ds_read_b128 v[144:147], v0
	ds_read_b128 v[148:151], v0 offset:1024
	ds_read_b128 v[152:155], v0 offset:2048
	ds_read_b128 v[156:159], v0 offset:3072
	v_add_u32_e32 v0, s30, v140
	ds_read_b128 v[160:163], v0
	ds_read_b128 v[164:167], v0 offset:1024
	ds_read_b128 v[168:171], v0 offset:2048
	ds_read_b128 v[172:175], v0 offset:3072
	s_add_u32 s20, s20, 0x80000
	s_addc_u32 s21, s21, 0
	s_mov_b32 m0, s27
	v_lshl_add_u64 v[220:221], s[20:21], 0, v[132:133]
	ds_read_b128 v[176:179], v142 offset:32768
	ds_read_b128 v[180:183], v142 offset:33792
	ds_read_b128 v[184:187], v142 offset:34816
	ds_read_b128 v[188:191], v142 offset:35840
	ds_read_b128 v[192:195], v142 offset:36864
	ds_read_b128 v[202:205], v142 offset:37888
	ds_read_b128 v[206:209], v142 offset:38912
	ds_read_b128 v[210:213], v142 offset:39936
	global_load_lds_dwordx4 v[220:221], off
	v_lshl_add_u64 v[220:221], s[20:21], 0, v[130:131]
	s_mov_b32 m0, s44
	s_nop 0
	global_load_lds_dwordx4 v[220:221], off
	s_waitcnt vmcnt(8)
	s_waitcnt lgkmcnt(0)
	s_barrier
	v_mfma_f32_16x16x32_bf16 v[126:129], v[144:147], v[176:179], v[126:129]
	v_mfma_f32_16x16x32_bf16 v[122:125], v[152:155], v[176:179], v[122:125]
	v_mfma_f32_16x16x32_bf16 v[118:121], v[144:147], v[184:187], v[118:121]
	v_mfma_f32_16x16x32_bf16 v[110:113], v[152:155], v[184:187], v[110:113]
	v_mfma_f32_16x16x32_bf16 v[102:105], v[144:147], v[192:195], v[102:105]
	v_mfma_f32_16x16x32_bf16 v[94:97], v[152:155], v[192:195], v[94:97]
	v_mfma_f32_16x16x32_bf16 v[86:89], v[144:147], v[206:209], v[86:89]
	v_mfma_f32_16x16x32_bf16 v[78:81], v[152:155], v[206:209], v[78:81]
	v_mfma_f32_16x16x32_bf16 v[126:129], v[148:151], v[180:183], v[126:129]
	v_mfma_f32_16x16x32_bf16 v[122:125], v[156:159], v[180:183], v[122:125]
	v_mfma_f32_16x16x32_bf16 v[118:121], v[148:151], v[188:191], v[118:121]
	v_mfma_f32_16x16x32_bf16 v[110:113], v[156:159], v[188:191], v[110:113]
	v_mfma_f32_16x16x32_bf16 v[102:105], v[148:151], v[202:205], v[102:105]
	v_mfma_f32_16x16x32_bf16 v[94:97], v[156:159], v[202:205], v[94:97]
	v_mfma_f32_16x16x32_bf16 v[86:89], v[148:151], v[210:213], v[86:89]
	v_mfma_f32_16x16x32_bf16 v[78:81], v[156:159], v[210:213], v[78:81]
	v_mfma_f32_16x16x32_bf16 v[114:117], v[160:163], v[176:179], v[114:117]
	v_mfma_f32_16x16x32_bf16 v[106:109], v[168:171], v[176:179], v[106:109]
	v_mfma_f32_16x16x32_bf16 v[98:101], v[160:163], v[184:187], v[98:101]
	v_mfma_f32_16x16x32_bf16 v[90:93], v[168:171], v[184:187], v[90:93]
	v_mfma_f32_16x16x32_bf16 v[82:85], v[160:163], v[192:195], v[82:85]
	v_mfma_f32_16x16x32_bf16 v[74:77], v[168:171], v[192:195], v[74:77]
	v_mfma_f32_16x16x32_bf16 v[70:73], v[160:163], v[206:209], v[70:73]
	v_mfma_f32_16x16x32_bf16 v[66:69], v[168:171], v[206:209], v[66:69]
	v_mfma_f32_16x16x32_bf16 v[114:117], v[164:167], v[180:183], v[114:117]
	v_mfma_f32_16x16x32_bf16 v[106:109], v[172:175], v[180:183], v[106:109]
	v_mfma_f32_16x16x32_bf16 v[98:101], v[164:167], v[188:191], v[98:101]
	v_mfma_f32_16x16x32_bf16 v[90:93], v[172:175], v[188:191], v[90:93]
	v_mfma_f32_16x16x32_bf16 v[82:85], v[164:167], v[202:205], v[82:85]
	v_mfma_f32_16x16x32_bf16 v[74:77], v[172:175], v[202:205], v[74:77]
	v_mfma_f32_16x16x32_bf16 v[70:73], v[164:167], v[210:213], v[70:73]
	v_mfma_f32_16x16x32_bf16 v[66:69], v[172:175], v[210:213], v[66:69]
	s_barrier
; #define PG8_STAGE(bufoff, gbase, voff) do { _Pragma("unroll") for (int _i = 0; _i < 2; ++_i) \
;         __builtin_amdgcn_global_load_lds((const unsigned*)((const char*)(gbase) + (voff)[_i]), (LAS unsigned*)(lds + (bufoff) + ldsw + _i * 8192), 16, 0, 0); } while (0)
; #define PG8_WAIT_V(n) asm volatile("s_waitcnt vmcnt(" #n ")" ::: "memory")
; #define PG8_WAIT_L(n) asm volatile("s_waitcnt lgkmcnt(" #n ")" ::: "memory")
; #define PG8_BAR __builtin_amdgcn_s_barrier()
; #define PG8_SCHED __builtin_amdgcn_sched_barrier(0)
; template <bool F8 = false, class Epi, class Sched>
; __device__ __forceinline__ void gemm_phase(LAS unsigned char* lds, const int lda, const int ldb, const int K, const Sched& S, const Epi& E) {
;     ...
;             PG8_LDA(At, 1, 1); PG8_STAGE(PG8_SB(1, 0), b3, voffB); PG8_STAGE(PG8_SB(1, 1), b3 + hstepB, voffB); PG8_STAGE(PG8_SA(1, 0), a3, voffA);
;             PG8_WAIT_V(8); PG8_WAIT_L(0); PG8_BAR; PG8_MMA(1, 0, At, B0); PG8_MMA(1, 1, At, B1); PG8_BAR; PG8_SCHED;
;         }
	s_add_i32 s20, s29, s24
	v_lshl_add_u64 v[138:139], v[138:139], 0, s[40:41]
	s_mov_b32 m0, s20
	ds_read_b128 v[176:179], v142 offset:49152
	ds_read_b128 v[180:183], v142 offset:50176
	ds_read_b128 v[184:187], v142 offset:51200
	ds_read_b128 v[188:191], v142 offset:52224
	ds_read_b128 v[192:195], v142 offset:53248
	ds_read_b128 v[202:205], v142 offset:54272
	ds_read_b128 v[206:209], v142 offset:55296
	ds_read_b128 v[210:213], v142 offset:56320
	global_load_lds_dwordx4 v[138:139], off
	s_add_i32 m0, s20, 0x2000
	s_add_u32 s18, s18, 0x80080
	v_lshl_add_u64 v[138:139], v[214:215], 0, s[40:41]
	s_addc_u32 s19, s19, 0
	s_add_i32 s20, s30, s24
	global_load_lds_dwordx4 v[138:139], off
	v_lshl_add_u64 v[138:139], s[18:19], 0, v[132:133]
	s_mov_b32 m0, s20
	s_nop 0
	global_load_lds_dwordx4 v[138:139], off
	v_lshl_add_u64 v[138:139], s[18:19], 0, v[130:131]
	s_add_i32 m0, s20, 0x2000
	s_nop 0
	global_load_lds_dwordx4 v[138:139], off
	v_lshl_add_u64 v[138:139], v[216:217], 0, s[40:41]
	s_mov_b32 m0, s52
	s_nop 0
	global_load_lds_dwordx4 v[138:139], off
	v_lshl_add_u64 v[138:139], v[218:219], 0, s[40:41]
	s_mov_b32 m0, s53
	s_nop 0
	global_load_lds_dwordx4 v[138:139], off
	s_waitcnt vmcnt(8)
	s_waitcnt lgkmcnt(0)
	s_barrier
	v_mfma_f32_16x16x32_bf16 v[62:65], v[144:147], v[176:179], v[62:65]
	v_mfma_f32_16x16x32_bf16 v[58:61], v[152:155], v[176:179], v[58:61]
	v_mfma_f32_16x16x32_bf16 v[54:57], v[144:147], v[184:187], v[54:57]
	v_mfma_f32_16x16x32_bf16 v[42:45], v[152:155], v[184:187], v[42:45]
	v_mfma_f32_16x16x32_bf16 v[38:41], v[144:147], v[192:195], v[38:41]
	v_mfma_f32_16x16x32_bf16 v[26:29], v[152:155], v[192:195], v[26:29]
	v_mfma_f32_16x16x32_bf16 v[22:25], v[144:147], v[206:209], v[22:25]
	v_mfma_f32_16x16x32_bf16 v[10:13], v[152:155], v[206:209], v[10:13]
	v_mfma_f32_16x16x32_bf16 v[62:65], v[148:151], v[180:183], v[62:65]
	v_mfma_f32_16x16x32_bf16 v[58:61], v[156:159], v[180:183], v[58:61]
	v_mfma_f32_16x16x32_bf16 v[54:57], v[148:151], v[188:191], v[54:57]
	v_mfma_f32_16x16x32_bf16 v[42:45], v[156:159], v[188:191], v[42:45]
	v_mfma_f32_16x16x32_bf16 v[38:41], v[148:151], v[202:205], v[38:41]
	v_mfma_f32_16x16x32_bf16 v[26:29], v[156:159], v[202:205], v[26:29]
	v_mfma_f32_16x16x32_bf16 v[22:25], v[148:151], v[210:213], v[22:25]
	v_mfma_f32_16x16x32_bf16 v[10:13], v[156:159], v[210:213], v[10:13]
	v_mfma_f32_16x16x32_bf16 v[50:53], v[160:163], v[176:179], v[50:53]
	v_mfma_f32_16x16x32_bf16 v[46:49], v[168:171], v[176:179], v[46:49]
	v_mfma_f32_16x16x32_bf16 v[34:37], v[160:163], v[184:187], v[34:37]
	v_mfma_f32_16x16x32_bf16 v[30:33], v[168:171], v[184:187], v[30:33]
	v_mfma_f32_16x16x32_bf16 v[18:21], v[160:163], v[192:195], v[18:21]
	v_mfma_f32_16x16x32_bf16 v[14:17], v[168:171], v[192:195], v[14:17]
	v_mfma_f32_16x16x32_bf16 v[6:9], v[160:163], v[206:209], v[6:9]
	v_mfma_f32_16x16x32_bf16 v[2:5], v[168:171], v[206:209], v[2:5]
	v_mfma_f32_16x16x32_bf16 v[50:53], v[164:167], v[180:183], v[50:53]
	v_mfma_f32_16x16x32_bf16 v[46:49], v[172:175], v[180:183], v[46:49]
	v_mfma_f32_16x16x32_bf16 v[34:37], v[164:167], v[188:191], v[34:37]
	v_mfma_f32_16x16x32_bf16 v[30:33], v[172:175], v[188:191], v[30:33]
	v_mfma_f32_16x16x32_bf16 v[18:21], v[164:167], v[202:205], v[18:21]
	v_mfma_f32_16x16x32_bf16 v[14:17], v[172:175], v[202:205], v[14:17]
	v_mfma_f32_16x16x32_bf16 v[6:9], v[164:167], v[210:213], v[6:9]
	v_mfma_f32_16x16x32_bf16 v[2:5], v[172:175], v[210:213], v[2:5]
	s_barrier
	s_add_i32 s28, s28, 2
	s_add_u32 s16, s16, 0x100
	s_addc_u32 s17, s17, 0
	s_add_u32 s95, s95, 0x100
	s_addc_u32 s96, s96, 0
	s_cmp_gt_u32 s28, 5
	s_cbranch_scc0 .LBB0_835
	s_and_b64 vcc, exec, s[6:7]
	s_cbranch_vccz .LBB0_838
	s_barrier

; #define PG8_STAGE(bufoff, gbase, voff) do { _Pragma("unroll") for (int _i = 0; _i < 2; ++_i) \
;         __builtin_amdgcn_global_load_lds((const unsigned*)((const char*)(gbase) + (voff)[_i]), (LAS unsigned*)(lds + (bufoff) + ldsw + _i * 8192), 16, 0, 0); } while (0)
; #define PG8_WAIT_V(n) asm volatile("s_waitcnt vmcnt(" #n ")" ::: "memory")
; #define PG8_WAIT_L(n) asm volatile("s_waitcnt lgkmcnt(" #n ")" ::: "memory")
; #define PG8_BAR __builtin_amdgcn_s_barrier()
; #define PG8_SCHED __builtin_amdgcn_sched_barrier(0)
; template <bool F8 = false, class Epi, class Sched>
; __device__ __forceinline__ void gemm_phase(LAS unsigned char* lds, const int lda, const int ldb, const int K, const Sched& S, const Epi& E) {
;     ...
;         for (int t = 0; t < nt; t += 2) {
;             const bool last = (t == nt - 2);
;             const char* a1 = cA + (size_t)(t + 1) * kstep;
;             const char* a2 = last ? nA : cA + (size_t)(t + 2) * kstep; const char* b2 = last ? nB : cB + (size_t)(t + 2) * kstep;
;             const char* a3 = a2 + kstep; const char* b3 = b2 + kstep;
;             PG8_LDB(B0, 0, 0); PG8_LDB(B1, 0, 1); PG8_SCHED; PG8_LDA(At, 0, 0); PG8_STAGE(PG8_SA(1, 1), a1 + hstepA, voffA);
;             PG8_WAIT_V(8); PG8_WAIT_L(0); PG8_BAR; PG8_MMA(0, 0, At, B0); PG8_MMA(0, 1, At, B1); PG8_BAR; PG8_SCHED;
;             PG8_LDA(At, 0, 1); PG8_STAGE(PG8_SB(0, 0), b2, voffB); PG8_STAGE(PG8_SB(0, 1), b2 + hstepB, voffB); PG8_STAGE(PG8_SA(0, 0), a2, voffA);
;             PG8_WAIT_V(8); PG8_WAIT_L(0); PG8_BAR; PG8_MMA(1, 0, At, B0); PG8_MMA(1, 1, At, B1); PG8_BAR; PG8_SCHED;
.LBB0_1062:
	s_add_u32 s30, vcc_lo, 0xfff80080
	s_addc_u32 s31, vcc_hi, -1
	s_add_i32 s33, 0, 0x10000
	s_cmp_eq_u32 s29, 28
	s_cselect_b32 s75, s13, s31
	s_cselect_b32 s74, s26, s30
	s_cselect_b32 s53, s9, s28
	s_cselect_b32 s52, s27, s73
	s_add_i32 s93, 0, 0x14000
	v_add_u32_e32 v152, s33, v141
	v_add_u32_e32 v168, s93, v141
	ds_read_b128 v[136:139], v152
	ds_read_b128 v[144:147], v152 offset:1024
	ds_read_b128 v[148:151], v152 offset:2048
	ds_read_b128 v[152:155], v152 offset:3072
	ds_read_b128 v[156:159], v168
	ds_read_b128 v[160:163], v168 offset:1024
	ds_read_b128 v[164:167], v168 offset:2048
	ds_read_b128 v[168:171], v168 offset:3072
	v_lshl_add_u64 v[210:211], vcc, 0, v[132:133]
	s_add_i32 m0, s19, 0xc000
	ds_read_b128 v[172:175], v143
	ds_read_b128 v[176:179], v143 offset:1024
	ds_read_b128 v[180:183], v143 offset:2048
	ds_read_b128 v[184:187], v143 offset:3072
	ds_read_b128 v[188:191], v143 offset:4096
	ds_read_b128 v[192:195], v143 offset:5120
	ds_read_b128 v[202:205], v143 offset:6144
	ds_read_b128 v[206:209], v143 offset:7168
	global_load_lds_dwordx4 v[210:211], off
	v_lshl_add_u64 v[210:211], vcc, 0, v[134:135]
	s_add_i32 m0, s19, 0xe000
	s_nop 0
	global_load_lds_dwordx4 v[210:211], off
	s_waitcnt vmcnt(8)
	s_waitcnt lgkmcnt(0)
	s_barrier
	v_mfma_f32_16x16x32_bf16 v[126:129], v[136:139], v[172:175], v[126:129]
	v_mfma_f32_16x16x32_bf16 v[122:125], v[148:151], v[172:175], v[122:125]
	v_mfma_f32_16x16x32_bf16 v[110:113], v[136:139], v[180:183], v[110:113]
	v_mfma_f32_16x16x32_bf16 v[106:109], v[148:151], v[180:183], v[106:109]
	v_mfma_f32_16x16x32_bf16 v[94:97], v[136:139], v[188:191], v[94:97]
	v_mfma_f32_16x16x32_bf16 v[90:93], v[148:151], v[188:191], v[90:93]
	v_mfma_f32_16x16x32_bf16 v[78:81], v[136:139], v[202:205], v[78:81]
	v_mfma_f32_16x16x32_bf16 v[74:77], v[148:151], v[202:205], v[74:77]
	v_mfma_f32_16x16x32_bf16 v[126:129], v[144:147], v[176:179], v[126:129]
	v_mfma_f32_16x16x32_bf16 v[122:125], v[152:155], v[176:179], v[122:125]
	v_mfma_f32_16x16x32_bf16 v[110:113], v[144:147], v[184:187], v[110:113]
	v_mfma_f32_16x16x32_bf16 v[106:109], v[152:155], v[184:187], v[106:109]
	v_mfma_f32_16x16x32_bf16 v[94:97], v[144:147], v[192:195], v[94:97]
	v_mfma_f32_16x16x32_bf16 v[90:93], v[152:155], v[192:195], v[90:93]
	v_mfma_f32_16x16x32_bf16 v[78:81], v[144:147], v[206:209], v[78:81]
	v_mfma_f32_16x16x32_bf16 v[74:77], v[152:155], v[206:209], v[74:77]
	v_mfma_f32_16x16x32_bf16 v[118:121], v[156:159], v[172:175], v[118:121]
	v_mfma_f32_16x16x32_bf16 v[114:117], v[164:167], v[172:175], v[114:117]
	v_mfma_f32_16x16x32_bf16 v[102:105], v[156:159], v[180:183], v[102:105]
	v_mfma_f32_16x16x32_bf16 v[98:101], v[164:167], v[180:183], v[98:101]
	v_mfma_f32_16x16x32_bf16 v[86:89], v[156:159], v[188:191], v[86:89]
	v_mfma_f32_16x16x32_bf16 v[82:85], v[164:167], v[188:191], v[82:85]
	v_mfma_f32_16x16x32_bf16 v[70:73], v[156:159], v[202:205], v[70:73]
	v_mfma_f32_16x16x32_bf16 v[66:69], v[164:167], v[202:205], v[66:69]
	v_mfma_f32_16x16x32_bf16 v[118:121], v[160:163], v[176:179], v[118:121]
	v_mfma_f32_16x16x32_bf16 v[114:117], v[168:171], v[176:179], v[114:117]
	v_mfma_f32_16x16x32_bf16 v[102:105], v[160:163], v[184:187], v[102:105]
	v_mfma_f32_16x16x32_bf16 v[98:101], v[168:171], v[184:187], v[98:101]
	v_mfma_f32_16x16x32_bf16 v[86:89], v[160:163], v[192:195], v[86:89]
	v_mfma_f32_16x16x32_bf16 v[82:85], v[168:171], v[192:195], v[82:85]
	v_mfma_f32_16x16x32_bf16 v[70:73], v[160:163], v[206:209], v[70:73]
	v_mfma_f32_16x16x32_bf16 v[66:69], v[168:171], v[206:209], v[66:69]
	s_barrier
	s_add_i32 s30, s33, s94
	v_lshl_add_u64 v[210:211], s[52:53], 0, v[0:1]
	s_mov_b32 m0, s30
	ds_read_b128 v[172:175], v143 offset:16384
	ds_read_b128 v[176:179], v143 offset:17408
	ds_read_b128 v[180:183], v143 offset:18432
	ds_read_b128 v[184:187], v143 offset:19456
	ds_read_b128 v[188:191], v143 offset:20480
	ds_read_b128 v[192:195], v143 offset:21504
	ds_read_b128 v[202:205], v143 offset:22528
	ds_read_b128 v[206:209], v143 offset:23552
	global_load_lds_dwordx4 v[210:211], off
	s_add_i32 m0, s30, 0x2000
	s_add_u32 s30, s52, 0x80000
	v_lshl_add_u64 v[212:213], s[52:53], 0, v[130:131]
	s_addc_u32 s31, s53, 0
	s_add_i32 s33, s93, s94
	global_load_lds_dwordx4 v[212:213], off
	v_lshl_add_u64 v[214:215], s[30:31], 0, v[0:1]
	s_mov_b32 m0, s33
	v_lshl_add_u64 v[216:217], s[74:75], 0, v[130:131]
	global_load_lds_dwordx4 v[214:215], off
	v_lshl_add_u64 v[214:215], s[30:31], 0, v[130:131]
	s_add_i32 m0, s33, 0x2000
	s_nop 0
	global_load_lds_dwordx4 v[214:215], off
	v_lshl_add_u64 v[214:215], s[74:75], 0, v[0:1]
	s_mov_b32 m0, s19
	s_nop 0
	global_load_lds_dwordx4 v[214:215], off
	s_mov_b32 m0, s56
	s_nop 0
	global_load_lds_dwordx4 v[216:217], off
	s_waitcnt vmcnt(8)
	s_waitcnt lgkmcnt(0)
	s_barrier
; #define PG8_STAGE(bufoff, gbase, voff) do { _Pragma("unroll") for (int _i = 0; _i < 2; ++_i) \
;         __builtin_amdgcn_global_load_lds((const unsigned*)((const char*)(gbase) + (voff)[_i]), (LAS unsigned*)(lds + (bufoff) + ldsw + _i * 8192), 16, 0, 0); } while (0)
; #define PG8_WAIT_V(n) asm volatile("s_waitcnt vmcnt(" #n ")" ::: "memory")
; #define PG8_WAIT_L(n) asm volatile("s_waitcnt lgkmcnt(" #n ")" ::: "memory")
; #define PG8_BAR __builtin_amdgcn_s_barrier()
; #define PG8_SCHED __builtin_amdgcn_sched_barrier(0)
; template <bool F8 = false, class Epi, class Sched>
; __device__ __forceinline__ void gemm_phase(LAS unsigned char* lds, const int lda, const int ldb, const int K, const Sched& S, const Epi& E) {
;     ...
;             PG8_WAIT_V(8); PG8_WAIT_L(0); PG8_BAR; PG8_MMA(1, 0, At, B0); PG8_MMA(1, 1, At, B1); PG8_BAR; PG8_SCHED;
;             PG8_LDB(B0, 1, 0); PG8_LDB(B1, 1, 1); PG8_SCHED; PG8_LDA(At, 1, 0); PG8_STAGE(PG8_SA(0, 1), a2 + hstepA, voffA);
;             PG8_WAIT_V(8); PG8_WAIT_L(0); PG8_BAR; PG8_MMA(0, 0, At, B0); PG8_MMA(0, 1, At, B1); PG8_BAR; PG8_SCHED;
	v_mfma_f32_16x16x32_bf16 v[62:65], v[136:139], v[172:175], v[62:65]
	v_mfma_f32_16x16x32_bf16 v[58:61], v[148:151], v[172:175], v[58:61]
	v_mfma_f32_16x16x32_bf16 v[46:49], v[136:139], v[180:183], v[46:49]
	v_mfma_f32_16x16x32_bf16 v[42:45], v[148:151], v[180:183], v[42:45]
	v_mfma_f32_16x16x32_bf16 v[30:33], v[136:139], v[188:191], v[30:33]
	v_mfma_f32_16x16x32_bf16 v[26:29], v[148:151], v[188:191], v[26:29]
	v_mfma_f32_16x16x32_bf16 v[14:17], v[136:139], v[202:205], v[14:17]
	v_mfma_f32_16x16x32_bf16 v[10:13], v[148:151], v[202:205], v[10:13]
	v_mfma_f32_16x16x32_bf16 v[62:65], v[144:147], v[176:179], v[62:65]
	v_mfma_f32_16x16x32_bf16 v[58:61], v[152:155], v[176:179], v[58:61]
	v_mfma_f32_16x16x32_bf16 v[46:49], v[144:147], v[184:187], v[46:49]
	v_mfma_f32_16x16x32_bf16 v[42:45], v[152:155], v[184:187], v[42:45]
	v_mfma_f32_16x16x32_bf16 v[30:33], v[144:147], v[192:195], v[30:33]
	v_mfma_f32_16x16x32_bf16 v[26:29], v[152:155], v[192:195], v[26:29]
	v_mfma_f32_16x16x32_bf16 v[14:17], v[144:147], v[206:209], v[14:17]
	v_mfma_f32_16x16x32_bf16 v[10:13], v[152:155], v[206:209], v[10:13]
	v_mfma_f32_16x16x32_bf16 v[54:57], v[156:159], v[172:175], v[54:57]
	v_mfma_f32_16x16x32_bf16 v[50:53], v[164:167], v[172:175], v[50:53]
	v_mfma_f32_16x16x32_bf16 v[38:41], v[156:159], v[180:183], v[38:41]
	v_mfma_f32_16x16x32_bf16 v[34:37], v[164:167], v[180:183], v[34:37]
	v_mfma_f32_16x16x32_bf16 v[22:25], v[156:159], v[188:191], v[22:25]
	v_mfma_f32_16x16x32_bf16 v[18:21], v[164:167], v[188:191], v[18:21]
	v_mfma_f32_16x16x32_bf16 v[6:9], v[156:159], v[202:205], v[6:9]
	v_mfma_f32_16x16x32_bf16 v[2:5], v[164:167], v[202:205], v[2:5]
	v_mfma_f32_16x16x32_bf16 v[54:57], v[160:163], v[176:179], v[54:57]
	v_mfma_f32_16x16x32_bf16 v[50:53], v[168:171], v[176:179], v[50:53]
	v_mfma_f32_16x16x32_bf16 v[38:41], v[160:163], v[184:187], v[38:41]
	v_mfma_f32_16x16x32_bf16 v[34:37], v[168:171], v[184:187], v[34:37]
	v_mfma_f32_16x16x32_bf16 v[22:25], v[160:163], v[192:195], v[22:25]
	v_mfma_f32_16x16x32_bf16 v[18:21], v[168:171], v[192:195], v[18:21]
	v_mfma_f32_16x16x32_bf16 v[6:9], v[160:163], v[206:209], v[6:9]
	v_mfma_f32_16x16x32_bf16 v[2:5], v[168:171], v[206:209], v[2:5]
	s_barrier
	s_add_i32 s33, 0, 0x18000
	s_add_i32 s93, 0, 0x1c000
	v_add_u32_e32 v152, s33, v141
	v_add_u32_e32 v168, s93, v141
	ds_read_b128 v[136:139], v152
	ds_read_b128 v[144:147], v152 offset:1024
	ds_read_b128 v[148:151], v152 offset:2048
	ds_read_b128 v[152:155], v152 offset:3072
	ds_read_b128 v[156:159], v168
	ds_read_b128 v[160:163], v168 offset:1024
	ds_read_b128 v[164:167], v168 offset:2048
	ds_read_b128 v[168:171], v168 offset:3072
	s_add_u32 s30, s74, 0x80000
	s_addc_u32 s31, s75, 0
	s_mov_b32 m0, s57
	v_lshl_add_u64 v[218:219], s[30:31], 0, v[0:1]
	ds_read_b128 v[172:175], v143 offset:32768
	ds_read_b128 v[176:179], v143 offset:33792
	ds_read_b128 v[180:183], v143 offset:34816
	ds_read_b128 v[184:187], v143 offset:35840
	ds_read_b128 v[188:191], v143 offset:36864
	ds_read_b128 v[192:195], v143 offset:37888
	ds_read_b128 v[202:205], v143 offset:38912
	ds_read_b128 v[206:209], v143 offset:39936
	global_load_lds_dwordx4 v[218:219], off
	v_lshl_add_u64 v[218:219], s[30:31], 0, v[130:131]
	s_mov_b32 m0, s96
	s_nop 0
	global_load_lds_dwordx4 v[218:219], off
	s_waitcnt vmcnt(8)
	s_waitcnt lgkmcnt(0)
	s_barrier
	v_mfma_f32_16x16x32_bf16 v[126:129], v[136:139], v[172:175], v[126:129]
	v_mfma_f32_16x16x32_bf16 v[122:125], v[148:151], v[172:175], v[122:125]
	v_mfma_f32_16x16x32_bf16 v[110:113], v[136:139], v[180:183], v[110:113]
	v_mfma_f32_16x16x32_bf16 v[106:109], v[148:151], v[180:183], v[106:109]
	v_mfma_f32_16x16x32_bf16 v[94:97], v[136:139], v[188:191], v[94:97]
	v_mfma_f32_16x16x32_bf16 v[90:93], v[148:151], v[188:191], v[90:93]
	v_mfma_f32_16x16x32_bf16 v[78:81], v[136:139], v[202:205], v[78:81]
	v_mfma_f32_16x16x32_bf16 v[74:77], v[148:151], v[202:205], v[74:77]
	v_mfma_f32_16x16x32_bf16 v[126:129], v[144:147], v[176:179], v[126:129]
	v_mfma_f32_16x16x32_bf16 v[122:125], v[152:155], v[176:179], v[122:125]
	v_mfma_f32_16x16x32_bf16 v[110:113], v[144:147], v[184:187], v[110:113]
	v_mfma_f32_16x16x32_bf16 v[106:109], v[152:155], v[184:187], v[106:109]
	v_mfma_f32_16x16x32_bf16 v[94:97], v[144:147], v[192:195], v[94:97]
	v_mfma_f32_16x16x32_bf16 v[90:93], v[152:155], v[192:195], v[90:93]
	v_mfma_f32_16x16x32_bf16 v[78:81], v[144:147], v[206:209], v[78:81]
	v_mfma_f32_16x16x32_bf16 v[74:77], v[152:155], v[206:209], v[74:77]
	v_mfma_f32_16x16x32_bf16 v[118:121], v[156:159], v[172:175], v[118:121]
	v_mfma_f32_16x16x32_bf16 v[114:117], v[164:167], v[172:175], v[114:117]
	v_mfma_f32_16x16x32_bf16 v[102:105], v[156:159], v[180:183], v[102:105]
	v_mfma_f32_16x16x32_bf16 v[98:101], v[164:167], v[180:183], v[98:101]
	v_mfma_f32_16x16x32_bf16 v[86:89], v[156:159], v[188:191], v[86:89]
	v_mfma_f32_16x16x32_bf16 v[82:85], v[164:167], v[188:191], v[82:85]
	v_mfma_f32_16x16x32_bf16 v[70:73], v[156:159], v[202:205], v[70:73]
	v_mfma_f32_16x16x32_bf16 v[66:69], v[164:167], v[202:205], v[66:69]
	v_mfma_f32_16x16x32_bf16 v[118:121], v[160:163], v[176:179], v[118:121]
	v_mfma_f32_16x16x32_bf16 v[114:117], v[168:171], v[176:179], v[114:117]
	v_mfma_f32_16x16x32_bf16 v[102:105], v[160:163], v[184:187], v[102:105]
	v_mfma_f32_16x16x32_bf16 v[98:101], v[168:171], v[184:187], v[98:101]
	v_mfma_f32_16x16x32_bf16 v[86:89], v[160:163], v[192:195], v[86:89]
	v_mfma_f32_16x16x32_bf16 v[82:85], v[168:171], v[192:195], v[82:85]
	v_mfma_f32_16x16x32_bf16 v[70:73], v[160:163], v[206:209], v[70:73]
	v_mfma_f32_16x16x32_bf16 v[66:69], v[168:171], v[206:209], v[66:69]
	s_barrier
; #define PG8_STAGE(bufoff, gbase, voff) do { _Pragma("unroll") for (int _i = 0; _i < 2; ++_i) \
;         __builtin_amdgcn_global_load_lds((const unsigned*)((const char*)(gbase) + (voff)[_i]), (LAS unsigned*)(lds + (bufoff) + ldsw + _i * 8192), 16, 0, 0); } while (0)
; #define PG8_WAIT_V(n) asm volatile("s_waitcnt vmcnt(" #n ")" ::: "memory")
; #define PG8_WAIT_L(n) asm volatile("s_waitcnt lgkmcnt(" #n ")" ::: "memory")
; #define PG8_BAR __builtin_amdgcn_s_barrier()
; #define PG8_SCHED __builtin_amdgcn_sched_barrier(0)
; template <bool F8 = false, class Epi, class Sched>
; __device__ __forceinline__ void gemm_phase(LAS unsigned char* lds, const int lda, const int ldb, const int K, const Sched& S, const Epi& E) {
;     ...
;             PG8_LDA(At, 1, 1); PG8_STAGE(PG8_SB(1, 0), b3, voffB); PG8_STAGE(PG8_SB(1, 1), b3 + hstepB, voffB); PG8_STAGE(PG8_SA(1, 0), a3, voffA);
;             PG8_WAIT_V(8); PG8_WAIT_L(0); PG8_BAR; PG8_MMA(1, 0, At, B0); PG8_MMA(1, 1, At, B1); PG8_BAR; PG8_SCHED;
;         }
	s_add_i32 s30, s33, s94
	v_lshl_add_u64 v[210:211], v[210:211], 0, s[40:41]
	s_mov_b32 m0, s30
	ds_read_b128 v[172:175], v143 offset:49152
	ds_read_b128 v[176:179], v143 offset:50176
	ds_read_b128 v[180:183], v143 offset:51200
	ds_read_b128 v[184:187], v143 offset:52224
	ds_read_b128 v[188:191], v143 offset:53248
	ds_read_b128 v[192:195], v143 offset:54272
	ds_read_b128 v[202:205], v143 offset:55296
	ds_read_b128 v[206:209], v143 offset:56320
	global_load_lds_dwordx4 v[210:211], off
	s_add_i32 m0, s30, 0x2000
	s_add_u32 s30, s52, 0x80080
	v_lshl_add_u64 v[210:211], v[212:213], 0, s[40:41]
	s_addc_u32 s31, s53, 0
	s_add_i32 s33, s93, s94
	global_load_lds_dwordx4 v[210:211], off
	v_lshl_add_u64 v[210:211], s[30:31], 0, v[0:1]
	s_mov_b32 m0, s33
	s_nop 0
	global_load_lds_dwordx4 v[210:211], off
	v_lshl_add_u64 v[210:211], s[30:31], 0, v[130:131]
	s_add_i32 m0, s33, 0x2000
	s_nop 0
	global_load_lds_dwordx4 v[210:211], off
	v_lshl_add_u64 v[210:211], v[214:215], 0, s[40:41]
	s_mov_b32 m0, s24
	s_nop 0
	global_load_lds_dwordx4 v[210:211], off
	v_lshl_add_u64 v[210:211], v[216:217], 0, s[40:41]
	s_mov_b32 m0, s25
	s_nop 0
	global_load_lds_dwordx4 v[210:211], off
	s_waitcnt vmcnt(8)
	s_waitcnt lgkmcnt(0)
	s_barrier
	v_mfma_f32_16x16x32_bf16 v[62:65], v[136:139], v[172:175], v[62:65]
	v_mfma_f32_16x16x32_bf16 v[58:61], v[148:151], v[172:175], v[58:61]
	v_mfma_f32_16x16x32_bf16 v[46:49], v[136:139], v[180:183], v[46:49]
	v_mfma_f32_16x16x32_bf16 v[42:45], v[148:151], v[180:183], v[42:45]
	v_mfma_f32_16x16x32_bf16 v[30:33], v[136:139], v[188:191], v[30:33]
	v_mfma_f32_16x16x32_bf16 v[26:29], v[148:151], v[188:191], v[26:29]
	v_mfma_f32_16x16x32_bf16 v[14:17], v[136:139], v[202:205], v[14:17]
	v_mfma_f32_16x16x32_bf16 v[10:13], v[148:151], v[202:205], v[10:13]
	v_mfma_f32_16x16x32_bf16 v[62:65], v[144:147], v[176:179], v[62:65]
	v_mfma_f32_16x16x32_bf16 v[58:61], v[152:155], v[176:179], v[58:61]
	v_mfma_f32_16x16x32_bf16 v[46:49], v[144:147], v[184:187], v[46:49]
	v_mfma_f32_16x16x32_bf16 v[42:45], v[152:155], v[184:187], v[42:45]
	v_mfma_f32_16x16x32_bf16 v[30:33], v[144:147], v[192:195], v[30:33]
	v_mfma_f32_16x16x32_bf16 v[26:29], v[152:155], v[192:195], v[26:29]
	v_mfma_f32_16x16x32_bf16 v[14:17], v[144:147], v[206:209], v[14:17]
	v_mfma_f32_16x16x32_bf16 v[10:13], v[152:155], v[206:209], v[10:13]
	v_mfma_f32_16x16x32_bf16 v[54:57], v[156:159], v[172:175], v[54:57]
	v_mfma_f32_16x16x32_bf16 v[50:53], v[164:167], v[172:175], v[50:53]
	v_mfma_f32_16x16x32_bf16 v[38:41], v[156:159], v[180:183], v[38:41]
	v_mfma_f32_16x16x32_bf16 v[34:37], v[164:167], v[180:183], v[34:37]
	v_mfma_f32_16x16x32_bf16 v[22:25], v[156:159], v[188:191], v[22:25]
	v_mfma_f32_16x16x32_bf16 v[18:21], v[164:167], v[188:191], v[18:21]
	v_mfma_f32_16x16x32_bf16 v[6:9], v[156:159], v[202:205], v[6:9]
	v_mfma_f32_16x16x32_bf16 v[2:5], v[164:167], v[202:205], v[2:5]
	v_mfma_f32_16x16x32_bf16 v[54:57], v[160:163], v[176:179], v[54:57]
	v_mfma_f32_16x16x32_bf16 v[50:53], v[168:171], v[176:179], v[50:53]
	v_mfma_f32_16x16x32_bf16 v[38:41], v[160:163], v[184:187], v[38:41]
	v_mfma_f32_16x16x32_bf16 v[34:37], v[168:171], v[184:187], v[34:37]
	v_mfma_f32_16x16x32_bf16 v[22:25], v[160:163], v[192:195], v[22:25]
	v_mfma_f32_16x16x32_bf16 v[18:21], v[168:171], v[192:195], v[18:21]
	v_mfma_f32_16x16x32_bf16 v[6:9], v[160:163], v[206:209], v[6:9]
	v_mfma_f32_16x16x32_bf16 v[2:5], v[168:171], v[206:209], v[2:5]
	s_barrier
	s_add_i32 s29, s29, 2
	s_add_u32 vcc_lo, vcc_lo, 0x100
	s_addc_u32 vcc_hi, vcc_hi, 0
	s_add_u32 s73, s73, 0x100
	s_addc_u32 s28, s28, 0
	s_cmp_gt_u32 s29, 29
	s_cbranch_scc0 .LBB0_1062
	s_and_b64 vcc, exec, s[6:7]
	s_cbranch_vccz .LBB0_1065
	s_barrier

; #define PG8_STAGE(bufoff, gbase, voff) do { _Pragma("unroll") for (int _i = 0; _i < 2; ++_i) \
;         __builtin_amdgcn_global_load_lds((const unsigned*)((const char*)(gbase) + (voff)[_i]), (LAS unsigned*)(lds + (bufoff) + ldsw + _i * 8192), 16, 0, 0); } while (0)
; #define PG8_WAIT_V(n) asm volatile("s_waitcnt vmcnt(" #n ")" ::: "memory")
; #define PG8_WAIT_L(n) asm volatile("s_waitcnt lgkmcnt(" #n ")" ::: "memory")
; #define PG8_BAR __builtin_amdgcn_s_barrier()
; #define PG8_SCHED __builtin_amdgcn_sched_barrier(0)
; template <bool F8 = false, class Epi, class Sched>
; __device__ __forceinline__ void gemm_phase(LAS unsigned char* lds, const int lda, const int ldb, const int K, const Sched& S, const Epi& E) {
;     ...
;         for (int t = 0; t < nt; t += 2) {
;             const bool last = (t == nt - 2);
;             const char* a1 = cA + (size_t)(t + 1) * kstep;
;             const char* a2 = last ? nA : cA + (size_t)(t + 2) * kstep; const char* b2 = last ? nB : cB + (size_t)(t + 2) * kstep;
;             const char* a3 = a2 + kstep; const char* b3 = b2 + kstep;
;             PG8_LDB(B0, 0, 0); PG8_LDB(B1, 0, 1); PG8_SCHED; PG8_LDA(At, 0, 0); PG8_STAGE(PG8_SA(1, 1), a1 + hstepA, voffA);
;             PG8_WAIT_V(8); PG8_WAIT_L(0); PG8_BAR; PG8_MMA(0, 0, At, B0); PG8_MMA(0, 1, At, B1); PG8_BAR; PG8_SCHED;
;             PG8_LDA(At, 0, 1); PG8_STAGE(PG8_SB(0, 0), b2, voffB); PG8_STAGE(PG8_SB(0, 1), b2 + hstepB, voffB); PG8_STAGE(PG8_SA(0, 0), a2, voffA);
;             PG8_WAIT_V(8); PG8_WAIT_L(0); PG8_BAR; PG8_MMA(1, 0, At, B0); PG8_MMA(1, 1, At, B1); PG8_BAR; PG8_SCHED;
.LBB0_1149:
	s_add_u32 s18, s16, 0x100
	s_addc_u32 s19, s17, 0
	s_add_i32 s30, 0, 0x10000
	s_cmpk_eq_i32 s94, 0x54
	s_cselect_b32 s53, s13, s19
	s_cselect_b32 s52, s12, s18
	v_add_u32_e32 v140, s30, v143
	s_cselect_b32 s21, s15, s29
	s_cselect_b32 s20, s14, s28
	s_add_i32 s31, 0, 0x14000
	ds_read_b128 v[146:149], v140
	ds_read_b128 v[150:153], v140 offset:1024
	ds_read_b128 v[154:157], v140 offset:2048
	ds_read_b128 v[158:161], v140 offset:3072
	v_add_u32_e32 v140, s31, v143
	ds_read_b128 v[162:165], v140
	ds_read_b128 v[166:169], v140 offset:1024
	ds_read_b128 v[170:173], v140 offset:2048
	ds_read_b128 v[174:177], v140 offset:3072
	v_lshl_add_u64 v[140:141], s[16:17], 0, v[136:137]
	s_add_i32 m0, s25, 0xc000
	ds_read_b128 v[178:181], v145
	ds_read_b128 v[182:185], v145 offset:1024
	ds_read_b128 v[186:189], v145 offset:2048
	ds_read_b128 v[190:193], v145 offset:3072
	ds_read_b128 v[202:205], v145 offset:4096
	ds_read_b128 v[206:209], v145 offset:5120
	ds_read_b128 v[210:213], v145 offset:6144
	ds_read_b128 v[214:217], v145 offset:7168
	global_load_lds_dwordx4 v[140:141], off
	v_lshl_add_u64 v[140:141], s[16:17], 0, v[138:139]
	s_add_i32 m0, s25, 0xe000
	s_nop 0
	global_load_lds_dwordx4 v[140:141], off
	s_waitcnt vmcnt(8)
	s_waitcnt lgkmcnt(0)
	s_barrier
	v_mfma_f32_16x16x32_bf16 v[126:129], v[146:149], v[178:181], v[126:129]
	v_mfma_f32_16x16x32_bf16 v[122:125], v[154:157], v[178:181], v[122:125]
	v_mfma_f32_16x16x32_bf16 v[118:121], v[146:149], v[186:189], v[118:121]
	v_mfma_f32_16x16x32_bf16 v[110:113], v[154:157], v[186:189], v[110:113]
	v_mfma_f32_16x16x32_bf16 v[102:105], v[146:149], v[202:205], v[102:105]
	v_mfma_f32_16x16x32_bf16 v[94:97], v[154:157], v[202:205], v[94:97]
	v_mfma_f32_16x16x32_bf16 v[86:89], v[146:149], v[210:213], v[86:89]
	v_mfma_f32_16x16x32_bf16 v[78:81], v[154:157], v[210:213], v[78:81]
	v_mfma_f32_16x16x32_bf16 v[126:129], v[150:153], v[182:185], v[126:129]
	v_mfma_f32_16x16x32_bf16 v[122:125], v[158:161], v[182:185], v[122:125]
	v_mfma_f32_16x16x32_bf16 v[118:121], v[150:153], v[190:193], v[118:121]
	v_mfma_f32_16x16x32_bf16 v[110:113], v[158:161], v[190:193], v[110:113]
	v_mfma_f32_16x16x32_bf16 v[102:105], v[150:153], v[206:209], v[102:105]
	v_mfma_f32_16x16x32_bf16 v[94:97], v[158:161], v[206:209], v[94:97]
	v_mfma_f32_16x16x32_bf16 v[86:89], v[150:153], v[214:217], v[86:89]
	v_mfma_f32_16x16x32_bf16 v[78:81], v[158:161], v[214:217], v[78:81]
	v_mfma_f32_16x16x32_bf16 v[114:117], v[162:165], v[178:181], v[114:117]
	v_mfma_f32_16x16x32_bf16 v[106:109], v[170:173], v[178:181], v[106:109]
	v_mfma_f32_16x16x32_bf16 v[98:101], v[162:165], v[186:189], v[98:101]
	v_mfma_f32_16x16x32_bf16 v[90:93], v[170:173], v[186:189], v[90:93]
	v_mfma_f32_16x16x32_bf16 v[82:85], v[162:165], v[202:205], v[82:85]
	v_mfma_f32_16x16x32_bf16 v[74:77], v[170:173], v[202:205], v[74:77]
	v_mfma_f32_16x16x32_bf16 v[70:73], v[162:165], v[210:213], v[70:73]
	v_mfma_f32_16x16x32_bf16 v[66:69], v[170:173], v[210:213], v[66:69]
	v_mfma_f32_16x16x32_bf16 v[114:117], v[166:169], v[182:185], v[114:117]
	v_mfma_f32_16x16x32_bf16 v[106:109], v[174:177], v[182:185], v[106:109]
	v_mfma_f32_16x16x32_bf16 v[98:101], v[166:169], v[190:193], v[98:101]
	v_mfma_f32_16x16x32_bf16 v[90:93], v[174:177], v[190:193], v[90:93]
	v_mfma_f32_16x16x32_bf16 v[82:85], v[166:169], v[206:209], v[82:85]
	v_mfma_f32_16x16x32_bf16 v[74:77], v[174:177], v[206:209], v[74:77]
	v_mfma_f32_16x16x32_bf16 v[70:73], v[166:169], v[214:217], v[70:73]
	v_mfma_f32_16x16x32_bf16 v[66:69], v[174:177], v[214:217], v[66:69]
	s_barrier
	s_add_i32 s16, s30, s24
	v_lshl_add_u64 v[140:141], s[20:21], 0, v[0:1]
	s_mov_b32 m0, s16
	ds_read_b128 v[178:181], v145 offset:16384
	ds_read_b128 v[182:185], v145 offset:17408
	ds_read_b128 v[186:189], v145 offset:18432
	ds_read_b128 v[190:193], v145 offset:19456
	ds_read_b128 v[202:205], v145 offset:20480
	ds_read_b128 v[206:209], v145 offset:21504
	ds_read_b128 v[210:213], v145 offset:22528
	ds_read_b128 v[214:217], v145 offset:23552
	global_load_lds_dwordx4 v[140:141], off
	s_add_i32 m0, s16, 0x2000
	s_add_u32 s16, s20, 0x160000
	v_lshl_add_u64 v[194:195], s[20:21], 0, v[130:131]
	s_addc_u32 s17, s21, 0
	s_add_i32 s30, s31, s24
	global_load_lds_dwordx4 v[194:195], off
	v_lshl_add_u64 v[218:219], s[16:17], 0, v[0:1]
	s_mov_b32 m0, s30
	v_lshl_add_u64 v[220:221], s[52:53], 0, v[132:133]
	global_load_lds_dwordx4 v[218:219], off
	v_lshl_add_u64 v[218:219], s[16:17], 0, v[130:131]
	s_add_i32 m0, s30, 0x2000
	s_nop 0
	global_load_lds_dwordx4 v[218:219], off
	v_lshl_add_u64 v[218:219], s[52:53], 0, v[134:135]
	s_mov_b32 m0, s25
	s_nop 0
	global_load_lds_dwordx4 v[218:219], off
	s_mov_b32 m0, s26
	s_nop 0
	global_load_lds_dwordx4 v[220:221], off
	s_waitcnt vmcnt(8)
	s_waitcnt lgkmcnt(0)
	s_barrier
; #define PG8_STAGE(bufoff, gbase, voff) do { _Pragma("unroll") for (int _i = 0; _i < 2; ++_i) \
;         __builtin_amdgcn_global_load_lds((const unsigned*)((const char*)(gbase) + (voff)[_i]), (LAS unsigned*)(lds + (bufoff) + ldsw + _i * 8192), 16, 0, 0); } while (0)
; #define PG8_WAIT_V(n) asm volatile("s_waitcnt vmcnt(" #n ")" ::: "memory")
; #define PG8_WAIT_L(n) asm volatile("s_waitcnt lgkmcnt(" #n ")" ::: "memory")
; #define PG8_BAR __builtin_amdgcn_s_barrier()
; #define PG8_SCHED __builtin_amdgcn_sched_barrier(0)
; template <bool F8 = false, class Epi, class Sched>
; __device__ __forceinline__ void gemm_phase(LAS unsigned char* lds, const int lda, const int ldb, const int K, const Sched& S, const Epi& E) {
;     ...
;             PG8_WAIT_V(8); PG8_WAIT_L(0); PG8_BAR; PG8_MMA(1, 0, At, B0); PG8_MMA(1, 1, At, B1); PG8_BAR; PG8_SCHED;
;             PG8_LDB(B0, 1, 0); PG8_LDB(B1, 1, 1); PG8_SCHED; PG8_LDA(At, 1, 0); PG8_STAGE(PG8_SA(0, 1), a2 + hstepA, voffA);
;             PG8_WAIT_V(8); PG8_WAIT_L(0); PG8_BAR; PG8_MMA(0, 0, At, B0); PG8_MMA(0, 1, At, B1); PG8_BAR; PG8_SCHED;
	v_mfma_f32_16x16x32_bf16 v[62:65], v[146:149], v[178:181], v[62:65]
	v_mfma_f32_16x16x32_bf16 v[58:61], v[154:157], v[178:181], v[58:61]
	v_mfma_f32_16x16x32_bf16 v[54:57], v[146:149], v[186:189], v[54:57]
	v_mfma_f32_16x16x32_bf16 v[46:49], v[154:157], v[186:189], v[46:49]
	v_mfma_f32_16x16x32_bf16 v[38:41], v[146:149], v[202:205], v[38:41]
	v_mfma_f32_16x16x32_bf16 v[30:33], v[154:157], v[202:205], v[30:33]
	v_mfma_f32_16x16x32_bf16 v[22:25], v[146:149], v[210:213], v[22:25]
	v_mfma_f32_16x16x32_bf16 v[14:17], v[154:157], v[210:213], v[14:17]
	v_mfma_f32_16x16x32_bf16 v[62:65], v[150:153], v[182:185], v[62:65]
	v_mfma_f32_16x16x32_bf16 v[58:61], v[158:161], v[182:185], v[58:61]
	v_mfma_f32_16x16x32_bf16 v[54:57], v[150:153], v[190:193], v[54:57]
	v_mfma_f32_16x16x32_bf16 v[46:49], v[158:161], v[190:193], v[46:49]
	v_mfma_f32_16x16x32_bf16 v[38:41], v[150:153], v[206:209], v[38:41]
	v_mfma_f32_16x16x32_bf16 v[30:33], v[158:161], v[206:209], v[30:33]
	v_mfma_f32_16x16x32_bf16 v[22:25], v[150:153], v[214:217], v[22:25]
	v_mfma_f32_16x16x32_bf16 v[14:17], v[158:161], v[214:217], v[14:17]
	v_mfma_f32_16x16x32_bf16 v[50:53], v[162:165], v[178:181], v[50:53]
	v_mfma_f32_16x16x32_bf16 v[42:45], v[170:173], v[178:181], v[42:45]
	v_mfma_f32_16x16x32_bf16 v[34:37], v[162:165], v[186:189], v[34:37]
	v_mfma_f32_16x16x32_bf16 v[26:29], v[170:173], v[186:189], v[26:29]
	v_mfma_f32_16x16x32_bf16 v[18:21], v[162:165], v[202:205], v[18:21]
	v_mfma_f32_16x16x32_bf16 v[10:13], v[170:173], v[202:205], v[10:13]
	v_mfma_f32_16x16x32_bf16 v[6:9], v[162:165], v[210:213], v[6:9]
	v_mfma_f32_16x16x32_bf16 v[2:5], v[170:173], v[210:213], v[2:5]
	v_mfma_f32_16x16x32_bf16 v[50:53], v[166:169], v[182:185], v[50:53]
	v_mfma_f32_16x16x32_bf16 v[42:45], v[174:177], v[182:185], v[42:45]
	v_mfma_f32_16x16x32_bf16 v[34:37], v[166:169], v[190:193], v[34:37]
	v_mfma_f32_16x16x32_bf16 v[26:29], v[174:177], v[190:193], v[26:29]
	v_mfma_f32_16x16x32_bf16 v[18:21], v[166:169], v[206:209], v[18:21]
	v_mfma_f32_16x16x32_bf16 v[10:13], v[174:177], v[206:209], v[10:13]
	v_mfma_f32_16x16x32_bf16 v[6:9], v[166:169], v[214:217], v[6:9]
	v_mfma_f32_16x16x32_bf16 v[2:5], v[174:177], v[214:217], v[2:5]
	s_barrier
	s_add_i32 s30, 0, 0x18000
	s_add_i32 s31, 0, 0x1c000
	v_add_u32_e32 v158, s30, v143
	v_add_u32_e32 v174, s31, v143
	ds_read_b128 v[146:149], v158
	ds_read_b128 v[150:153], v158 offset:1024
	ds_read_b128 v[154:157], v158 offset:2048
	ds_read_b128 v[158:161], v158 offset:3072
	ds_read_b128 v[162:165], v174
	ds_read_b128 v[166:169], v174 offset:1024
	ds_read_b128 v[170:173], v174 offset:2048
	ds_read_b128 v[174:177], v174 offset:3072
	s_add_u32 s16, s52, 0x160000
	s_addc_u32 s17, s53, 0
	s_mov_b32 m0, s27
	v_lshl_add_u64 v[222:223], s[16:17], 0, v[134:135]
	ds_read_b128 v[178:181], v145 offset:32768
	ds_read_b128 v[182:185], v145 offset:33792
	ds_read_b128 v[186:189], v145 offset:34816
	ds_read_b128 v[190:193], v145 offset:35840
	ds_read_b128 v[202:205], v145 offset:36864
	ds_read_b128 v[206:209], v145 offset:37888
	ds_read_b128 v[210:213], v145 offset:38912
	ds_read_b128 v[214:217], v145 offset:39936
	global_load_lds_dwordx4 v[222:223], off
	v_lshl_add_u64 v[222:223], s[16:17], 0, v[132:133]
	s_mov_b32 m0, s44
	s_nop 0
	global_load_lds_dwordx4 v[222:223], off
	s_waitcnt vmcnt(8)
	s_waitcnt lgkmcnt(0)
	s_barrier
	v_mfma_f32_16x16x32_bf16 v[126:129], v[146:149], v[178:181], v[126:129]
	v_mfma_f32_16x16x32_bf16 v[122:125], v[154:157], v[178:181], v[122:125]
	v_mfma_f32_16x16x32_bf16 v[118:121], v[146:149], v[186:189], v[118:121]
	v_mfma_f32_16x16x32_bf16 v[110:113], v[154:157], v[186:189], v[110:113]
	v_mfma_f32_16x16x32_bf16 v[102:105], v[146:149], v[202:205], v[102:105]
	v_mfma_f32_16x16x32_bf16 v[94:97], v[154:157], v[202:205], v[94:97]
	v_mfma_f32_16x16x32_bf16 v[86:89], v[146:149], v[210:213], v[86:89]
	v_mfma_f32_16x16x32_bf16 v[78:81], v[154:157], v[210:213], v[78:81]
	v_mfma_f32_16x16x32_bf16 v[126:129], v[150:153], v[182:185], v[126:129]
	v_mfma_f32_16x16x32_bf16 v[122:125], v[158:161], v[182:185], v[122:125]
	v_mfma_f32_16x16x32_bf16 v[118:121], v[150:153], v[190:193], v[118:121]
	v_mfma_f32_16x16x32_bf16 v[110:113], v[158:161], v[190:193], v[110:113]
	v_mfma_f32_16x16x32_bf16 v[102:105], v[150:153], v[206:209], v[102:105]
	v_mfma_f32_16x16x32_bf16 v[94:97], v[158:161], v[206:209], v[94:97]
	v_mfma_f32_16x16x32_bf16 v[86:89], v[150:153], v[214:217], v[86:89]
	v_mfma_f32_16x16x32_bf16 v[78:81], v[158:161], v[214:217], v[78:81]
	v_mfma_f32_16x16x32_bf16 v[114:117], v[162:165], v[178:181], v[114:117]
	v_mfma_f32_16x16x32_bf16 v[106:109], v[170:173], v[178:181], v[106:109]
	v_mfma_f32_16x16x32_bf16 v[98:101], v[162:165], v[186:189], v[98:101]
	v_mfma_f32_16x16x32_bf16 v[90:93], v[170:173], v[186:189], v[90:93]
	v_mfma_f32_16x16x32_bf16 v[82:85], v[162:165], v[202:205], v[82:85]
	v_mfma_f32_16x16x32_bf16 v[74:77], v[170:173], v[202:205], v[74:77]
	v_mfma_f32_16x16x32_bf16 v[70:73], v[162:165], v[210:213], v[70:73]
	v_mfma_f32_16x16x32_bf16 v[66:69], v[170:173], v[210:213], v[66:69]
	v_mfma_f32_16x16x32_bf16 v[114:117], v[166:169], v[182:185], v[114:117]
	v_mfma_f32_16x16x32_bf16 v[106:109], v[174:177], v[182:185], v[106:109]
	v_mfma_f32_16x16x32_bf16 v[98:101], v[166:169], v[190:193], v[98:101]
	v_mfma_f32_16x16x32_bf16 v[90:93], v[174:177], v[190:193], v[90:93]
	v_mfma_f32_16x16x32_bf16 v[82:85], v[166:169], v[206:209], v[82:85]
	v_mfma_f32_16x16x32_bf16 v[74:77], v[174:177], v[206:209], v[74:77]
	v_mfma_f32_16x16x32_bf16 v[70:73], v[166:169], v[214:217], v[70:73]
	v_mfma_f32_16x16x32_bf16 v[66:69], v[174:177], v[214:217], v[66:69]
	s_barrier
; #define PG8_STAGE(bufoff, gbase, voff) do { _Pragma("unroll") for (int _i = 0; _i < 2; ++_i) \
;         __builtin_amdgcn_global_load_lds((const unsigned*)((const char*)(gbase) + (voff)[_i]), (LAS unsigned*)(lds + (bufoff) + ldsw + _i * 8192), 16, 0, 0); } while (0)
; #define PG8_WAIT_V(n) asm volatile("s_waitcnt vmcnt(" #n ")" ::: "memory")
; #define PG8_WAIT_L(n) asm volatile("s_waitcnt lgkmcnt(" #n ")" ::: "memory")
; #define PG8_BAR __builtin_amdgcn_s_barrier()
; #define PG8_SCHED __builtin_amdgcn_sched_barrier(0)
; template <bool F8 = false, class Epi, class Sched>
; __device__ __forceinline__ void gemm_phase(LAS unsigned char* lds, const int lda, const int ldb, const int K, const Sched& S, const Epi& E) {
;     ...
;             PG8_LDA(At, 1, 1); PG8_STAGE(PG8_SB(1, 0), b3, voffB); PG8_STAGE(PG8_SB(1, 1), b3 + hstepB, voffB); PG8_STAGE(PG8_SA(1, 0), a3, voffA);
;             PG8_WAIT_V(8); PG8_WAIT_L(0); PG8_BAR; PG8_MMA(1, 0, At, B0); PG8_MMA(1, 1, At, B1); PG8_BAR; PG8_SCHED;
;         }
;         if (wr == 0) PG8_BAR;
	s_add_i32 s16, s30, s24
	v_lshl_add_u64 v[140:141], v[140:141], 0, s[40:41]
	s_mov_b32 m0, s16
	ds_read_b128 v[178:181], v145 offset:49152
	ds_read_b128 v[182:185], v145 offset:50176
	ds_read_b128 v[186:189], v145 offset:51200
	ds_read_b128 v[190:193], v145 offset:52224
	ds_read_b128 v[202:205], v145 offset:53248
	ds_read_b128 v[206:209], v145 offset:54272
	ds_read_b128 v[210:213], v145 offset:55296
	ds_read_b128 v[214:217], v145 offset:56320
	global_load_lds_dwordx4 v[140:141], off
	s_add_i32 m0, s16, 0x2000
	s_add_u32 s16, s20, 0x160080
	v_lshl_add_u64 v[140:141], v[194:195], 0, s[40:41]
	s_addc_u32 s17, s21, 0
	s_add_i32 s20, s31, s24
	global_load_lds_dwordx4 v[140:141], off
	v_lshl_add_u64 v[140:141], s[16:17], 0, v[0:1]
	s_mov_b32 m0, s20
	s_nop 0
	global_load_lds_dwordx4 v[140:141], off
	v_lshl_add_u64 v[140:141], s[16:17], 0, v[130:131]
	s_add_i32 m0, s20, 0x2000
	s_nop 0
	global_load_lds_dwordx4 v[140:141], off
	v_lshl_add_u64 v[140:141], v[218:219], 0, s[40:41]
	s_mov_b32 m0, s56
	s_nop 0
	global_load_lds_dwordx4 v[140:141], off
	v_lshl_add_u64 v[140:141], v[220:221], 0, s[40:41]
	s_mov_b32 m0, s57
	s_nop 0
	global_load_lds_dwordx4 v[140:141], off
	s_waitcnt vmcnt(8)
	s_waitcnt lgkmcnt(0)
	s_barrier
	v_mfma_f32_16x16x32_bf16 v[62:65], v[146:149], v[178:181], v[62:65]
	v_mfma_f32_16x16x32_bf16 v[58:61], v[154:157], v[178:181], v[58:61]
	v_mfma_f32_16x16x32_bf16 v[54:57], v[146:149], v[186:189], v[54:57]
	v_mfma_f32_16x16x32_bf16 v[46:49], v[154:157], v[186:189], v[46:49]
	v_mfma_f32_16x16x32_bf16 v[38:41], v[146:149], v[202:205], v[38:41]
	v_mfma_f32_16x16x32_bf16 v[30:33], v[154:157], v[202:205], v[30:33]
	v_mfma_f32_16x16x32_bf16 v[22:25], v[146:149], v[210:213], v[22:25]
	v_mfma_f32_16x16x32_bf16 v[14:17], v[154:157], v[210:213], v[14:17]
	v_mfma_f32_16x16x32_bf16 v[62:65], v[150:153], v[182:185], v[62:65]
	v_mfma_f32_16x16x32_bf16 v[58:61], v[158:161], v[182:185], v[58:61]
	v_mfma_f32_16x16x32_bf16 v[54:57], v[150:153], v[190:193], v[54:57]
	v_mfma_f32_16x16x32_bf16 v[46:49], v[158:161], v[190:193], v[46:49]
	v_mfma_f32_16x16x32_bf16 v[38:41], v[150:153], v[206:209], v[38:41]
	v_mfma_f32_16x16x32_bf16 v[30:33], v[158:161], v[206:209], v[30:33]
	v_mfma_f32_16x16x32_bf16 v[22:25], v[150:153], v[214:217], v[22:25]
	v_mfma_f32_16x16x32_bf16 v[14:17], v[158:161], v[214:217], v[14:17]
	v_mfma_f32_16x16x32_bf16 v[50:53], v[162:165], v[178:181], v[50:53]
	v_mfma_f32_16x16x32_bf16 v[42:45], v[170:173], v[178:181], v[42:45]
	v_mfma_f32_16x16x32_bf16 v[34:37], v[162:165], v[186:189], v[34:37]
	v_mfma_f32_16x16x32_bf16 v[26:29], v[170:173], v[186:189], v[26:29]
	v_mfma_f32_16x16x32_bf16 v[18:21], v[162:165], v[202:205], v[18:21]
	v_mfma_f32_16x16x32_bf16 v[10:13], v[170:173], v[202:205], v[10:13]
	v_mfma_f32_16x16x32_bf16 v[6:9], v[162:165], v[210:213], v[6:9]
	v_mfma_f32_16x16x32_bf16 v[2:5], v[170:173], v[210:213], v[2:5]
	v_mfma_f32_16x16x32_bf16 v[50:53], v[166:169], v[182:185], v[50:53]
	v_mfma_f32_16x16x32_bf16 v[42:45], v[174:177], v[182:185], v[42:45]
	v_mfma_f32_16x16x32_bf16 v[34:37], v[166:169], v[190:193], v[34:37]
	v_mfma_f32_16x16x32_bf16 v[26:29], v[174:177], v[190:193], v[26:29]
	v_mfma_f32_16x16x32_bf16 v[18:21], v[166:169], v[206:209], v[18:21]
	v_mfma_f32_16x16x32_bf16 v[10:13], v[174:177], v[206:209], v[10:13]
	v_mfma_f32_16x16x32_bf16 v[6:9], v[166:169], v[214:217], v[6:9]
	v_mfma_f32_16x16x32_bf16 v[2:5], v[174:177], v[214:217], v[2:5]
	s_barrier
	s_add_i32 s94, s94, 2
	s_add_u32 s28, s28, 0x100
	s_addc_u32 s29, s29, 0
	s_cmpk_gt_u32 s94, 0x55
	s_mov_b64 s[16:17], s[18:19]
	s_cbranch_scc0 .LBB0_1149
	s_and_b64 vcc, exec, s[6:7]
	s_cbranch_vccz .LBB0_1152
	s_barrier

; #define PG8_STAGE(bufoff, gbase, voff) do { _Pragma("unroll") for (int _i = 0; _i < 2; ++_i) \
;         __builtin_amdgcn_global_load_lds((const unsigned*)((const char*)(gbase) + (voff)[_i]), (LAS unsigned*)(lds + (bufoff) + ldsw + _i * 8192), 16, 0, 0); } while (0)
; #define PG8_WAIT_V(n) asm volatile("s_waitcnt vmcnt(" #n ")" ::: "memory")
; #define PG8_WAIT_L(n) asm volatile("s_waitcnt lgkmcnt(" #n ")" ::: "memory")
; #define PG8_BAR __builtin_amdgcn_s_barrier()
; #define PG8_SCHED __builtin_amdgcn_sched_barrier(0)
; template <bool F8 = false, class Epi, class Sched>
; __device__ __forceinline__ void gemm_phase(LAS unsigned char* lds, const int lda, const int ldb, const int K, const Sched& S, const Epi& E) {
;     ...
;         for (int t = 0; t < nt; t += 2) {
;             const bool last = (t == nt - 2);
;             const char* a1 = cA + (size_t)(t + 1) * kstep;
;             const char* a2 = last ? nA : cA + (size_t)(t + 2) * kstep; const char* b2 = last ? nB : cB + (size_t)(t + 2) * kstep;
;             const char* a3 = a2 + kstep; const char* b3 = b2 + kstep;
;             PG8_LDB(B0, 0, 0); PG8_LDB(B1, 0, 1); PG8_SCHED; PG8_LDA(At, 0, 0); PG8_STAGE(PG8_SA(1, 1), a1 + hstepA, voffA);
;             PG8_WAIT_V(8); PG8_WAIT_L(0); PG8_BAR; PG8_MMA(0, 0, At, B0); PG8_MMA(0, 1, At, B1); PG8_BAR; PG8_SCHED;
;             PG8_LDA(At, 0, 1); PG8_STAGE(PG8_SB(0, 0), b2, voffB); PG8_STAGE(PG8_SB(0, 1), b2 + hstepB, voffB); PG8_STAGE(PG8_SA(0, 0), a2, voffA);
;             PG8_WAIT_V(8); PG8_WAIT_L(0); PG8_BAR; PG8_MMA(1, 0, At, B0); PG8_MMA(1, 1, At, B1); PG8_BAR; PG8_SCHED;
.LBB0_1177:
	s_add_u32 s18, s16, 0x100
	s_addc_u32 s19, s17, 0
	s_add_i32 s30, 0, 0x10000
	s_cmp_eq_u32 s96, 18
	s_cselect_b32 s53, s13, s19
	s_cselect_b32 s52, s12, s18
	v_add_u32_e32 v0, s30, v140
	s_cselect_b32 s21, s15, s29
	s_cselect_b32 s20, s14, s28
	s_add_i32 s31, 0, 0x14000
	ds_read_b128 v[144:147], v0
	ds_read_b128 v[148:151], v0 offset:1024
	ds_read_b128 v[152:155], v0 offset:2048
	ds_read_b128 v[156:159], v0 offset:3072
	v_add_u32_e32 v0, s31, v140
	ds_read_b128 v[160:163], v0
	ds_read_b128 v[164:167], v0 offset:1024
	ds_read_b128 v[168:171], v0 offset:2048
	ds_read_b128 v[172:175], v0 offset:3072
	v_lshl_add_u64 v[138:139], s[16:17], 0, v[134:135]
	s_add_i32 m0, s25, 0xc000
	ds_read_b128 v[176:179], v142
	ds_read_b128 v[180:183], v142 offset:1024
	ds_read_b128 v[184:187], v142 offset:2048
	ds_read_b128 v[188:191], v142 offset:3072
	ds_read_b128 v[192:195], v142 offset:4096
	ds_read_b128 v[202:205], v142 offset:5120
	ds_read_b128 v[206:209], v142 offset:6144
	ds_read_b128 v[210:213], v142 offset:7168
	global_load_lds_dwordx4 v[138:139], off
	v_lshl_add_u64 v[138:139], s[16:17], 0, v[136:137]
	s_add_i32 m0, s25, 0xe000
	s_nop 0
	global_load_lds_dwordx4 v[138:139], off
	s_waitcnt vmcnt(8)
	s_waitcnt lgkmcnt(0)
	s_barrier
	v_mfma_f32_16x16x32_bf16 v[126:129], v[144:147], v[176:179], v[126:129]
	v_mfma_f32_16x16x32_bf16 v[122:125], v[152:155], v[176:179], v[122:125]
	v_mfma_f32_16x16x32_bf16 v[118:121], v[144:147], v[184:187], v[118:121]
	v_mfma_f32_16x16x32_bf16 v[110:113], v[152:155], v[184:187], v[110:113]
	v_mfma_f32_16x16x32_bf16 v[102:105], v[144:147], v[192:195], v[102:105]
	v_mfma_f32_16x16x32_bf16 v[94:97], v[152:155], v[192:195], v[94:97]
	v_mfma_f32_16x16x32_bf16 v[86:89], v[144:147], v[206:209], v[86:89]
	v_mfma_f32_16x16x32_bf16 v[78:81], v[152:155], v[206:209], v[78:81]
	v_mfma_f32_16x16x32_bf16 v[126:129], v[148:151], v[180:183], v[126:129]
	v_mfma_f32_16x16x32_bf16 v[122:125], v[156:159], v[180:183], v[122:125]
	v_mfma_f32_16x16x32_bf16 v[118:121], v[148:151], v[188:191], v[118:121]
	v_mfma_f32_16x16x32_bf16 v[110:113], v[156:159], v[188:191], v[110:113]
	v_mfma_f32_16x16x32_bf16 v[102:105], v[148:151], v[202:205], v[102:105]
	v_mfma_f32_16x16x32_bf16 v[94:97], v[156:159], v[202:205], v[94:97]
	v_mfma_f32_16x16x32_bf16 v[86:89], v[148:151], v[210:213], v[86:89]
	v_mfma_f32_16x16x32_bf16 v[78:81], v[156:159], v[210:213], v[78:81]
	v_mfma_f32_16x16x32_bf16 v[114:117], v[160:163], v[176:179], v[114:117]
	v_mfma_f32_16x16x32_bf16 v[106:109], v[168:171], v[176:179], v[106:109]
	v_mfma_f32_16x16x32_bf16 v[98:101], v[160:163], v[184:187], v[98:101]
	v_mfma_f32_16x16x32_bf16 v[90:93], v[168:171], v[184:187], v[90:93]
	v_mfma_f32_16x16x32_bf16 v[82:85], v[160:163], v[192:195], v[82:85]
	v_mfma_f32_16x16x32_bf16 v[74:77], v[168:171], v[192:195], v[74:77]
	v_mfma_f32_16x16x32_bf16 v[70:73], v[160:163], v[206:209], v[70:73]
	v_mfma_f32_16x16x32_bf16 v[66:69], v[168:171], v[206:209], v[66:69]
	v_mfma_f32_16x16x32_bf16 v[114:117], v[164:167], v[180:183], v[114:117]
	v_mfma_f32_16x16x32_bf16 v[106:109], v[172:175], v[180:183], v[106:109]
	v_mfma_f32_16x16x32_bf16 v[98:101], v[164:167], v[188:191], v[98:101]
	v_mfma_f32_16x16x32_bf16 v[90:93], v[172:175], v[188:191], v[90:93]
	v_mfma_f32_16x16x32_bf16 v[82:85], v[164:167], v[202:205], v[82:85]
	v_mfma_f32_16x16x32_bf16 v[74:77], v[172:175], v[202:205], v[74:77]
	v_mfma_f32_16x16x32_bf16 v[70:73], v[164:167], v[210:213], v[70:73]
	v_mfma_f32_16x16x32_bf16 v[66:69], v[172:175], v[210:213], v[66:69]
	s_barrier
	s_add_i32 s16, s30, s24
	v_lshl_add_u64 v[138:139], s[20:21], 0, v[132:133]
	s_mov_b32 m0, s16
	ds_read_b128 v[176:179], v142 offset:16384
	ds_read_b128 v[180:183], v142 offset:17408
	ds_read_b128 v[184:187], v142 offset:18432
	ds_read_b128 v[188:191], v142 offset:19456
	ds_read_b128 v[192:195], v142 offset:20480
	ds_read_b128 v[202:205], v142 offset:21504
	ds_read_b128 v[206:209], v142 offset:22528
	ds_read_b128 v[210:213], v142 offset:23552
	global_load_lds_dwordx4 v[138:139], off
	s_add_i32 m0, s16, 0x2000
	s_add_u32 s16, s20, 0x160000
	v_lshl_add_u64 v[214:215], s[20:21], 0, v[130:131]
	s_addc_u32 s17, s21, 0
	s_add_i32 s30, s31, s24
	global_load_lds_dwordx4 v[214:215], off
	v_lshl_add_u64 v[216:217], s[16:17], 0, v[132:133]
	s_mov_b32 m0, s30
	v_lshl_add_u64 v[218:219], s[52:53], 0, v[130:131]
	global_load_lds_dwordx4 v[216:217], off
	v_lshl_add_u64 v[216:217], s[16:17], 0, v[130:131]
	s_add_i32 m0, s30, 0x2000
	s_nop 0
	global_load_lds_dwordx4 v[216:217], off
	v_lshl_add_u64 v[216:217], s[52:53], 0, v[132:133]
	s_mov_b32 m0, s25
	s_nop 0
	global_load_lds_dwordx4 v[216:217], off
	s_mov_b32 m0, s26
	s_nop 0
	global_load_lds_dwordx4 v[218:219], off
	s_waitcnt vmcnt(8)
	s_waitcnt lgkmcnt(0)
	s_barrier
; #define PG8_STAGE(bufoff, gbase, voff) do { _Pragma("unroll") for (int _i = 0; _i < 2; ++_i) \
;         __builtin_amdgcn_global_load_lds((const unsigned*)((const char*)(gbase) + (voff)[_i]), (LAS unsigned*)(lds + (bufoff) + ldsw + _i * 8192), 16, 0, 0); } while (0)
; #define PG8_WAIT_V(n) asm volatile("s_waitcnt vmcnt(" #n ")" ::: "memory")
; #define PG8_WAIT_L(n) asm volatile("s_waitcnt lgkmcnt(" #n ")" ::: "memory")
; #define PG8_BAR __builtin_amdgcn_s_barrier()
; #define PG8_SCHED __builtin_amdgcn_sched_barrier(0)
; template <bool F8 = false, class Epi, class Sched>
; __device__ __forceinline__ void gemm_phase(LAS unsigned char* lds, const int lda, const int ldb, const int K, const Sched& S, const Epi& E) {
;     ...
;             PG8_WAIT_V(8); PG8_WAIT_L(0); PG8_BAR; PG8_MMA(1, 0, At, B0); PG8_MMA(1, 1, At, B1); PG8_BAR; PG8_SCHED;
;             PG8_LDB(B0, 1, 0); PG8_LDB(B1, 1, 1); PG8_SCHED; PG8_LDA(At, 1, 0); PG8_STAGE(PG8_SA(0, 1), a2 + hstepA, voffA);
;             PG8_WAIT_V(8); PG8_WAIT_L(0); PG8_BAR; PG8_MMA(0, 0, At, B0); PG8_MMA(0, 1, At, B1); PG8_BAR; PG8_SCHED;
	v_mfma_f32_16x16x32_bf16 v[62:65], v[144:147], v[176:179], v[62:65]
	v_mfma_f32_16x16x32_bf16 v[58:61], v[152:155], v[176:179], v[58:61]
	v_mfma_f32_16x16x32_bf16 v[54:57], v[144:147], v[184:187], v[54:57]
	v_mfma_f32_16x16x32_bf16 v[42:45], v[152:155], v[184:187], v[42:45]
	v_mfma_f32_16x16x32_bf16 v[38:41], v[144:147], v[192:195], v[38:41]
	v_mfma_f32_16x16x32_bf16 v[26:29], v[152:155], v[192:195], v[26:29]
	v_mfma_f32_16x16x32_bf16 v[22:25], v[144:147], v[206:209], v[22:25]
	v_mfma_f32_16x16x32_bf16 v[10:13], v[152:155], v[206:209], v[10:13]
	v_mfma_f32_16x16x32_bf16 v[62:65], v[148:151], v[180:183], v[62:65]
	v_mfma_f32_16x16x32_bf16 v[58:61], v[156:159], v[180:183], v[58:61]
	v_mfma_f32_16x16x32_bf16 v[54:57], v[148:151], v[188:191], v[54:57]
	v_mfma_f32_16x16x32_bf16 v[42:45], v[156:159], v[188:191], v[42:45]
	v_mfma_f32_16x16x32_bf16 v[38:41], v[148:151], v[202:205], v[38:41]
	v_mfma_f32_16x16x32_bf16 v[26:29], v[156:159], v[202:205], v[26:29]
	v_mfma_f32_16x16x32_bf16 v[22:25], v[148:151], v[210:213], v[22:25]
	v_mfma_f32_16x16x32_bf16 v[10:13], v[156:159], v[210:213], v[10:13]
	v_mfma_f32_16x16x32_bf16 v[50:53], v[160:163], v[176:179], v[50:53]
	v_mfma_f32_16x16x32_bf16 v[46:49], v[168:171], v[176:179], v[46:49]
	v_mfma_f32_16x16x32_bf16 v[34:37], v[160:163], v[184:187], v[34:37]
	v_mfma_f32_16x16x32_bf16 v[30:33], v[168:171], v[184:187], v[30:33]
	v_mfma_f32_16x16x32_bf16 v[18:21], v[160:163], v[192:195], v[18:21]
	v_mfma_f32_16x16x32_bf16 v[14:17], v[168:171], v[192:195], v[14:17]
	v_mfma_f32_16x16x32_bf16 v[6:9], v[160:163], v[206:209], v[6:9]
	v_mfma_f32_16x16x32_bf16 v[2:5], v[168:171], v[206:209], v[2:5]
	v_mfma_f32_16x16x32_bf16 v[50:53], v[164:167], v[180:183], v[50:53]
	v_mfma_f32_16x16x32_bf16 v[46:49], v[172:175], v[180:183], v[46:49]
	v_mfma_f32_16x16x32_bf16 v[34:37], v[164:167], v[188:191], v[34:37]
	v_mfma_f32_16x16x32_bf16 v[30:33], v[172:175], v[188:191], v[30:33]
	v_mfma_f32_16x16x32_bf16 v[18:21], v[164:167], v[202:205], v[18:21]
	v_mfma_f32_16x16x32_bf16 v[14:17], v[172:175], v[202:205], v[14:17]
	v_mfma_f32_16x16x32_bf16 v[6:9], v[164:167], v[210:213], v[6:9]
	v_mfma_f32_16x16x32_bf16 v[2:5], v[172:175], v[210:213], v[2:5]
	s_barrier
	s_add_i32 s30, 0, 0x18000
	v_add_u32_e32 v0, s30, v140
	s_add_i32 s31, 0, 0x1c000
	ds_read_b128 v[144:147], v0
	ds_read_b128 v[148:151], v0 offset:1024
	ds_read_b128 v[152:155], v0 offset:2048
	ds_read_b128 v[156:159], v0 offset:3072
	v_add_u32_e32 v0, s31, v140
	ds_read_b128 v[160:163], v0
	ds_read_b128 v[164:167], v0 offset:1024
	ds_read_b128 v[168:171], v0 offset:2048
	ds_read_b128 v[172:175], v0 offset:3072
	s_add_u32 s16, s52, 0x160000
	s_addc_u32 s17, s53, 0
	s_mov_b32 m0, s27
	v_lshl_add_u64 v[220:221], s[16:17], 0, v[132:133]
	ds_read_b128 v[176:179], v142 offset:32768
	ds_read_b128 v[180:183], v142 offset:33792
	ds_read_b128 v[184:187], v142 offset:34816
	ds_read_b128 v[188:191], v142 offset:35840
	ds_read_b128 v[192:195], v142 offset:36864
	ds_read_b128 v[202:205], v142 offset:37888
	ds_read_b128 v[206:209], v142 offset:38912
	ds_read_b128 v[210:213], v142 offset:39936
	global_load_lds_dwordx4 v[220:221], off
	v_lshl_add_u64 v[220:221], s[16:17], 0, v[130:131]
	s_mov_b32 m0, s44
	s_nop 0
	global_load_lds_dwordx4 v[220:221], off
	s_waitcnt vmcnt(8)
	s_waitcnt lgkmcnt(0)
	s_barrier
	v_mfma_f32_16x16x32_bf16 v[126:129], v[144:147], v[176:179], v[126:129]
	v_mfma_f32_16x16x32_bf16 v[122:125], v[152:155], v[176:179], v[122:125]
	v_mfma_f32_16x16x32_bf16 v[118:121], v[144:147], v[184:187], v[118:121]
	v_mfma_f32_16x16x32_bf16 v[110:113], v[152:155], v[184:187], v[110:113]
	v_mfma_f32_16x16x32_bf16 v[102:105], v[144:147], v[192:195], v[102:105]
	v_mfma_f32_16x16x32_bf16 v[94:97], v[152:155], v[192:195], v[94:97]
	v_mfma_f32_16x16x32_bf16 v[86:89], v[144:147], v[206:209], v[86:89]
	v_mfma_f32_16x16x32_bf16 v[78:81], v[152:155], v[206:209], v[78:81]
	v_mfma_f32_16x16x32_bf16 v[126:129], v[148:151], v[180:183], v[126:129]
	v_mfma_f32_16x16x32_bf16 v[122:125], v[156:159], v[180:183], v[122:125]
	v_mfma_f32_16x16x32_bf16 v[118:121], v[148:151], v[188:191], v[118:121]
	v_mfma_f32_16x16x32_bf16 v[110:113], v[156:159], v[188:191], v[110:113]
	v_mfma_f32_16x16x32_bf16 v[102:105], v[148:151], v[202:205], v[102:105]
	v_mfma_f32_16x16x32_bf16 v[94:97], v[156:159], v[202:205], v[94:97]
	v_mfma_f32_16x16x32_bf16 v[86:89], v[148:151], v[210:213], v[86:89]
	v_mfma_f32_16x16x32_bf16 v[78:81], v[156:159], v[210:213], v[78:81]
	v_mfma_f32_16x16x32_bf16 v[114:117], v[160:163], v[176:179], v[114:117]
	v_mfma_f32_16x16x32_bf16 v[106:109], v[168:171], v[176:179], v[106:109]
	v_mfma_f32_16x16x32_bf16 v[98:101], v[160:163], v[184:187], v[98:101]
	v_mfma_f32_16x16x32_bf16 v[90:93], v[168:171], v[184:187], v[90:93]
	v_mfma_f32_16x16x32_bf16 v[82:85], v[160:163], v[192:195], v[82:85]
	v_mfma_f32_16x16x32_bf16 v[74:77], v[168:171], v[192:195], v[74:77]
	v_mfma_f32_16x16x32_bf16 v[70:73], v[160:163], v[206:209], v[70:73]
	v_mfma_f32_16x16x32_bf16 v[66:69], v[168:171], v[206:209], v[66:69]
	v_mfma_f32_16x16x32_bf16 v[114:117], v[164:167], v[180:183], v[114:117]
	v_mfma_f32_16x16x32_bf16 v[106:109], v[172:175], v[180:183], v[106:109]
	v_mfma_f32_16x16x32_bf16 v[98:101], v[164:167], v[188:191], v[98:101]
	v_mfma_f32_16x16x32_bf16 v[90:93], v[172:175], v[188:191], v[90:93]
	v_mfma_f32_16x16x32_bf16 v[82:85], v[164:167], v[202:205], v[82:85]
	v_mfma_f32_16x16x32_bf16 v[74:77], v[172:175], v[202:205], v[74:77]
	v_mfma_f32_16x16x32_bf16 v[70:73], v[164:167], v[210:213], v[70:73]
	v_mfma_f32_16x16x32_bf16 v[66:69], v[172:175], v[210:213], v[66:69]
	s_barrier
; #define PG8_STAGE(bufoff, gbase, voff) do { _Pragma("unroll") for (int _i = 0; _i < 2; ++_i) \
;         __builtin_amdgcn_global_load_lds((const unsigned*)((const char*)(gbase) + (voff)[_i]), (LAS unsigned*)(lds + (bufoff) + ldsw + _i * 8192), 16, 0, 0); } while (0)
; #define PG8_WAIT_V(n) asm volatile("s_waitcnt vmcnt(" #n ")" ::: "memory")
; #define PG8_WAIT_L(n) asm volatile("s_waitcnt lgkmcnt(" #n ")" ::: "memory")
; #define PG8_BAR __builtin_amdgcn_s_barrier()
; #define PG8_SCHED __builtin_amdgcn_sched_barrier(0)
; template <bool F8 = false, class Epi, class Sched>
; __device__ __forceinline__ void gemm_phase(LAS unsigned char* lds, const int lda, const int ldb, const int K, const Sched& S, const Epi& E) {
;     ...
;             PG8_LDA(At, 1, 1); PG8_STAGE(PG8_SB(1, 0), b3, voffB); PG8_STAGE(PG8_SB(1, 1), b3 + hstepB, voffB); PG8_STAGE(PG8_SA(1, 0), a3, voffA);
;             PG8_WAIT_V(8); PG8_WAIT_L(0); PG8_BAR; PG8_MMA(1, 0, At, B0); PG8_MMA(1, 1, At, B1); PG8_BAR; PG8_SCHED;
;         }
;         if (wr == 0) PG8_BAR;
	s_add_i32 s16, s30, s24
	v_lshl_add_u64 v[138:139], v[138:139], 0, s[40:41]
	s_mov_b32 m0, s16
	ds_read_b128 v[176:179], v142 offset:49152
	ds_read_b128 v[180:183], v142 offset:50176
	ds_read_b128 v[184:187], v142 offset:51200
	ds_read_b128 v[188:191], v142 offset:52224
	ds_read_b128 v[192:195], v142 offset:53248
	ds_read_b128 v[202:205], v142 offset:54272
	ds_read_b128 v[206:209], v142 offset:55296
	ds_read_b128 v[210:213], v142 offset:56320
	global_load_lds_dwordx4 v[138:139], off
	s_add_i32 m0, s16, 0x2000
	s_add_u32 s16, s20, 0x160080
	v_lshl_add_u64 v[138:139], v[214:215], 0, s[40:41]
	s_addc_u32 s17, s21, 0
	s_add_i32 s20, s31, s24
	global_load_lds_dwordx4 v[138:139], off
	v_lshl_add_u64 v[138:139], s[16:17], 0, v[132:133]
	s_mov_b32 m0, s20
	s_nop 0
	global_load_lds_dwordx4 v[138:139], off
	v_lshl_add_u64 v[138:139], s[16:17], 0, v[130:131]
	s_add_i32 m0, s20, 0x2000
	s_nop 0
	global_load_lds_dwordx4 v[138:139], off
	v_lshl_add_u64 v[138:139], v[216:217], 0, s[40:41]
	s_mov_b32 m0, s56
	s_nop 0
	global_load_lds_dwordx4 v[138:139], off
	v_lshl_add_u64 v[138:139], v[218:219], 0, s[40:41]
	s_mov_b32 m0, s57
	s_nop 0
	global_load_lds_dwordx4 v[138:139], off
	s_waitcnt vmcnt(8)
	s_waitcnt lgkmcnt(0)
	s_barrier
	v_mfma_f32_16x16x32_bf16 v[62:65], v[144:147], v[176:179], v[62:65]
	v_mfma_f32_16x16x32_bf16 v[58:61], v[152:155], v[176:179], v[58:61]
	v_mfma_f32_16x16x32_bf16 v[54:57], v[144:147], v[184:187], v[54:57]
	v_mfma_f32_16x16x32_bf16 v[42:45], v[152:155], v[184:187], v[42:45]
	v_mfma_f32_16x16x32_bf16 v[38:41], v[144:147], v[192:195], v[38:41]
	v_mfma_f32_16x16x32_bf16 v[26:29], v[152:155], v[192:195], v[26:29]
	v_mfma_f32_16x16x32_bf16 v[22:25], v[144:147], v[206:209], v[22:25]
	v_mfma_f32_16x16x32_bf16 v[10:13], v[152:155], v[206:209], v[10:13]
	v_mfma_f32_16x16x32_bf16 v[62:65], v[148:151], v[180:183], v[62:65]
	v_mfma_f32_16x16x32_bf16 v[58:61], v[156:159], v[180:183], v[58:61]
	v_mfma_f32_16x16x32_bf16 v[54:57], v[148:151], v[188:191], v[54:57]
	v_mfma_f32_16x16x32_bf16 v[42:45], v[156:159], v[188:191], v[42:45]
	v_mfma_f32_16x16x32_bf16 v[38:41], v[148:151], v[202:205], v[38:41]
	v_mfma_f32_16x16x32_bf16 v[26:29], v[156:159], v[202:205], v[26:29]
	v_mfma_f32_16x16x32_bf16 v[22:25], v[148:151], v[210:213], v[22:25]
	v_mfma_f32_16x16x32_bf16 v[10:13], v[156:159], v[210:213], v[10:13]
	v_mfma_f32_16x16x32_bf16 v[50:53], v[160:163], v[176:179], v[50:53]
	v_mfma_f32_16x16x32_bf16 v[46:49], v[168:171], v[176:179], v[46:49]
	v_mfma_f32_16x16x32_bf16 v[34:37], v[160:163], v[184:187], v[34:37]
	v_mfma_f32_16x16x32_bf16 v[30:33], v[168:171], v[184:187], v[30:33]
	v_mfma_f32_16x16x32_bf16 v[18:21], v[160:163], v[192:195], v[18:21]
	v_mfma_f32_16x16x32_bf16 v[14:17], v[168:171], v[192:195], v[14:17]
	v_mfma_f32_16x16x32_bf16 v[6:9], v[160:163], v[206:209], v[6:9]
	v_mfma_f32_16x16x32_bf16 v[2:5], v[168:171], v[206:209], v[2:5]
	v_mfma_f32_16x16x32_bf16 v[50:53], v[164:167], v[180:183], v[50:53]
	v_mfma_f32_16x16x32_bf16 v[46:49], v[172:175], v[180:183], v[46:49]
	v_mfma_f32_16x16x32_bf16 v[34:37], v[164:167], v[188:191], v[34:37]
	v_mfma_f32_16x16x32_bf16 v[30:33], v[172:175], v[188:191], v[30:33]
	v_mfma_f32_16x16x32_bf16 v[18:21], v[164:167], v[202:205], v[18:21]
	v_mfma_f32_16x16x32_bf16 v[14:17], v[172:175], v[202:205], v[14:17]
	v_mfma_f32_16x16x32_bf16 v[6:9], v[164:167], v[210:213], v[6:9]
	v_mfma_f32_16x16x32_bf16 v[2:5], v[172:175], v[210:213], v[2:5]
	s_barrier
	s_add_i32 s96, s96, 2
	s_add_u32 s28, s28, 0x100
	s_addc_u32 s29, s29, 0
	s_cmp_gt_u32 s96, 19
	s_mov_b64 s[16:17], s[18:19]
	s_cbranch_scc0 .LBB0_1177
	s_and_b64 vcc, exec, s[8:9]
	s_cbranch_vccz .LBB0_1180
	s_barrier
